# adds: lru_phase prologue loads issued together (one round trip), gelu exponent argument refactored x*(c2+c1*x^2) saving 2 VALU per gelu; f32 math, same kinds
# speedup vs baseline: 1.0163x; 1.0044x over previous
_Z8mega_fwd4Args:
	s_mov_b64 s[52:53], s[0:1]
	v_mov_b32_e32 v245, 0xc0135761
	s_load_dwordx4 s[68:71], s[0:1], 0xd0
	s_load_dwordx2 s[80:81], s[0:1], 0xe0
	s_load_dword s3, s[0:1], 0xe8
	s_add_u32 s0, s52, 0xe0
	s_addc_u32 s1, s53, 0
	v_and_b32_e32 v175, 0x3ff, v0
	v_writelane_b32 v244, s0, 0
	v_cmp_gt_u32_e32 vcc, 4, v175
	s_nop 0
	v_writelane_b32 v244, s1, 1
	s_waitcnt lgkmcnt(0)
	s_mov_b64 s[0:1], s[68:69]
	s_nop 0
	v_writelane_b32 v244, s0, 2
	s_nop 1
	v_writelane_b32 v244, s1, 3
	s_and_saveexec_b64 s[0:1], vcc
	v_lshl_add_u32 v1, v175, 2, 0
	v_add_u32_e32 v1, 0x20ff0, v1
	v_mov_b32_e32 v2, 0
	ds_write_b32 v1, v2
	s_or_b64 exec, exec, s[0:1]
	s_waitcnt lgkmcnt(0)
	s_barrier
	s_add_u32 s0, s68, 0x16370d00
	s_getreg_b32 s4, hwreg(HW_REG_XCC_ID, 0, 4)
	s_addc_u32 s1, s69, 0
	s_and_b32 s33, s4, 15
	v_cmp_eq_u32_e64 s[56:57], 0, v175
	s_and_saveexec_b64 s[4:5], s[56:57]
	s_cbranch_execz .LBB0_5
	s_mov_b64 s[6:7], exec
	v_mbcnt_lo_u32_b32 v1, s6, 0
	v_mbcnt_hi_u32_b32 v1, s7, v1
	v_cmp_eq_u32_e32 vcc, 0, v1
	s_and_b64 s[8:9], exec, vcc
	s_mov_b64 exec, s[8:9]
	s_cbranch_execz .LBB0_5
	s_lshl_b32 s8, s33, 8
	s_bcnt1_i32_b64 s6, s[6:7]
	v_mov_b32_e32 v1, s8
	v_mov_b32_e32 v2, s6
	global_atomic_add v1, v2, s[0:1] offset:1024

.LBB0_329:
	s_xor_b64 s[64:65], s[10:11], -1
	s_cmp_le_i32 s70, s4
	s_cselect_b64 s[0:1], -1, 0
	s_cmp_lt_i32 s4, s71
	s_cselect_b64 s[4:5], -1, 0
	s_and_b64 s[28:29], s[0:1], s[4:5]
	s_andn2_b64 vcc, exec, s[28:29]
	s_cbranch_vccnz .LBB0_431
	v_readlane_b32 s4, v243, 10
	s_lshl_b32 s0, s96, 18
	v_readlane_b32 s5, v243, 11
	v_writelane_b32 v242, s0, 50
	v_mov_b32_e32 v0, v175
	s_mov_b64 s[0:1], s[68:69]
	s_andn2_b64 vcc, exec, s[4:5]
	s_cbranch_vccnz .LBB0_361
	v_readlane_b32 s4, v243, 12
	v_readlane_b32 s5, v242, 50
	s_or_b32 s4, s5, s4
	s_lshl_b32 s4, s4, 1
	s_add_u32 s4, s0, s4
	s_addc_u32 s5, s1, 0
	s_add_u32 s4, s4, 0x15ee4c40
	s_addc_u32 s5, s5, 0
	v_ashrrev_i32_e32 v1, 31, v0
	v_lshl_add_u64 v[6:7], v[0:1], 4, s[4:5]
	s_barrier
	global_load_dwordx4 v[48:51], v[6:7], off
	v_add_u32_e32 v10, 0x200, v0
	v_lshl_add_u32 v4, v0, 4, 0
	v_ashrrev_i32_e32 v11, 31, v10
	v_lshl_add_u64 v[6:7], v[10:11], 4, s[4:5]
	global_load_dwordx4 v[52:55], v[6:7], off
	v_add_u32_e32 v10, 0x400, v0
	v_ashrrev_i32_e32 v11, 31, v10
	v_lshl_add_u64 v[6:7], v[10:11], 4, s[4:5]
	global_load_dwordx4 v[56:59], v[6:7], off
	v_add_u32_e32 v10, 0x600, v0
	v_ashrrev_i32_e32 v11, 31, v10
	v_lshl_add_u64 v[6:7], v[10:11], 4, s[4:5]
	global_load_dwordx4 v[60:63], v[6:7], off
	v_and_b32_e32 v5, 63, v0
	v_ashrrev_i32_e32 v2, 6, v0
	v_lshlrev_b32_e32 v29, 4, v0
	v_lshlrev_b32_e32 v31, 2, v0
	s_movk_i32 s4, 0x140
	v_cmp_gt_i32_e32 vcc, s4, v0
	s_and_saveexec_b64 s[40:41], vcc
	s_cbranch_execz .LBB0_337
	v_cmp_lt_i32_e32 vcc, 3, v2
	s_and_saveexec_b64 s[4:5], vcc
	s_xor_b64 s[42:43], exec, s[4:5]
	s_cbranch_execz .LBB0_334
	s_lshl_b32 s4, s96, 10
	v_readlane_b32 s5, v243, 13
	s_or_b32 s4, s4, s5
	v_or_b32_e32 v144, s4, v5
	v_readlane_b32 s4, v243, 14
	v_readlane_b32 s6, v243, 16
	v_readlane_b32 s7, v243, 17
	v_readlane_b32 s5, v243, 15
	s_nop 0
	v_lshl_add_u64 v[6:7], v[144:145], 2, s[6:7]

.LBB0_336:
	s_or_b64 exec, exec, s[42:43]
	global_load_dword v30, v[6:7], off

.LBB0_341:
	s_or_b64 exec, exec, s[46:47]
	s_movk_i32 s4, 0x90
	v_mul_lo_u32 v89, v88, s4
	v_lshlrev_b32_e32 v90, 5, v9
	v_add3_u32 v9, 0, v89, v90
	v_mul_lo_u32 v91, v6, s4
	s_waitcnt vmcnt(0)
	ds_write_b128 v29, v[48:51]
	ds_write_b128 v29, v[52:55] offset:8192
	ds_write_b128 v29, v[56:59] offset:16384
	ds_write_b128 v29, v[60:63] offset:24576
	v_cmp_gt_i32_e32 vcc, 0x140, v0
	s_and_saveexec_b64 s[42:43], vcc
	ds_write_b32 v31, v30 offset:32768
	s_or_b64 exec, exec, s[42:43]
	ds_write_b128 v9, v[36:39] offset:35104
	ds_write_b128 v9, v[32:35] offset:35120
	s_and_saveexec_b64 s[42:43], s[40:41]
	s_cbranch_execz .LBB0_343
	v_add3_u32 v9, 0, v91, v90
	ds_write_b128 v9, v[44:47] offset:34816
	ds_write_b128 v9, v[40:43] offset:34832

.LBB0_362:
	s_or_b64 exec, exec, s[44:45]
	v_readlane_b32 s5, v242, 50
	s_add_u32 s5, s48, s5
	s_addc_u32 s6, s49, 0
	v_ashrrev_i32_e32 v122, 2, v32
	s_add_u32 s42, s5, 0x15fe4c40
	v_lshl_add_u32 v0, v122, 3, 0
	s_addc_u32 s43, s6, 0
	s_waitcnt lgkmcnt(0)
	s_barrier
	ds_read_b64 v[156:157], v0
	s_lshl_b32 s5, s92, 2
	v_lshlrev_b32_e32 v0, 4, v32
	s_and_b32 s5, s5, 4
	v_and_b32_e32 v173, 48, v0
	v_lshl_or_b32 v16, s5, 6, v173
	v_add_u32_e32 v124, s4, v122
	v_mov_b64_e32 v[0:1], s[76:77]
	v_mad_i64_i32 v[162:163], s[6:7], v124, s62, v[0:1]
	v_lshlrev_b32_e32 v144, 1, v16
	v_lshl_add_u64 v[0:1], v[162:163], 0, v[144:145]
	v_add_co_u32_e32 v4, vcc, s3, v0
	s_mov_b64 s[14:15], 0x2000
	s_nop 0
	v_addc_co_u32_e32 v5, vcc, 0, v1, vcc
	v_lshl_add_u64 v[2:3], v[0:1], 0, s[14:15]
	global_load_dwordx4 v[108:111], v[4:5], off
	global_load_dwordx4 v[72:75], v[2:3], off offset:16
	s_mov_b64 s[16:17], 0x1c00
	v_add_co_u32_e32 v6, vcc, s74, v0
	s_mov_b64 s[8:9], 0x2400
	v_lshl_add_u64 v[2:3], v[0:1], 0, s[16:17]
	v_addc_co_u32_e32 v7, vcc, 0, v1, vcc
	v_lshl_add_u64 v[0:1], v[0:1], 0, s[8:9]
	s_lshl_b32 s92, s5, 7
	v_ashrrev_i32_e32 v121, 31, v120
	v_and_b32_e32 v136, 15, v32
	global_load_dwordx4 v[8:11], v[2:3], off offset:16
	global_load_dwordx4 v[24:27], v[4:5], off offset:1024
	global_load_dwordx4 v[28:31], v[6:7], off offset:3072
	global_load_dwordx4 v[12:15], v[0:1], off offset:16
	v_lshl_add_u64 v[0:1], v[120:121], 0, s[92:93]
	v_or_b32_e32 v0, v0, v136
	v_lshlrev_b64 v[0:1], 8, v[0:1]
	v_lshl_add_u64 v[0:1], s[42:43], 0, v[0:1]
	v_and_b32_e32 v2, 48, v127
	v_mov_b32_e32 v3, v145
	v_lshl_add_u64 v[0:1], v[0:1], 0, v[2:3]
	v_lshlrev_b32_e32 v6, 2, v16
	global_load_dwordx4 v[60:63], v[0:1], off
	global_load_dwordx4 v[56:59], v[0:1], off offset:64
	global_load_dwordx4 v[44:47], v[0:1], off offset:128
	global_load_dwordx4 v[40:43], v[0:1], off offset:192
	global_load_dwordx4 v[138:141], v6, s[0:1] offset:16
	global_load_dwordx4 v[158:161], v6, s[0:1]
	global_load_dwordx4 v[188:191], v6, s[72:73] offset:16
	global_load_dwordx4 v[192:195], v6, s[72:73]
	s_or_b32 s4, s5, s53
	s_lshl_b32 s92, s4, 7
	s_lshl_b64 s[6:7], s[92:93], 2
	v_readlane_b32 s12, v242, 12
	v_readlane_b32 s13, v242, 13
	s_add_u32 s6, s12, s6
	v_ashrrev_i32_e32 v123, 31, v122
	s_addc_u32 s7, s13, s7
	s_or_b32 s4, s5, 1
	v_lshlrev_b64 v[0:1], 2, v[122:123]
	v_lshl_or_b32 v70, s4, 6, v173
	v_lshl_add_u64 v[4:5], s[6:7], 0, v[0:1]
	v_lshl_add_u64 v[164:165], s[12:13], 0, v[0:1]
	v_lshlrev_b32_e32 v0, 1, v70
	v_mov_b32_e32 v1, v145
	v_lshl_add_u64 v[0:1], v[162:163], 0, v[0:1]
	global_load_dword v123, v[4:5], off
	global_load_dwordx4 v[84:87], v6, s[0:1] offset:48
	global_load_dwordx4 v[100:103], v6, s[0:1] offset:32
	global_load_dwordx4 v[80:83], v6, s[72:73] offset:48
	global_load_dwordx4 v[96:99], v6, s[72:73] offset:32
	v_add_co_u32_e32 v4, vcc, s3, v0
	v_lshl_add_u64 v[168:169], s[42:43], 0, v[2:3]
	s_nop 0
	v_addc_co_u32_e32 v5, vcc, 0, v1, vcc
	v_lshl_add_u64 v[2:3], v[0:1], 0, s[14:15]
	v_add_co_u32_e32 v6, vcc, s74, v0
	v_or_b32_e32 v166, v120, v136
	v_mov_b32_e32 v167, v121
	v_and_b32_e32 v121, 48, v32
	global_load_dwordx4 v[104:107], v[4:5], off
	global_load_dwordx4 v[64:67], v[2:3], off offset:16
	v_lshl_add_u64 v[2:3], v[0:1], 0, s[16:17]
	v_addc_co_u32_e32 v7, vcc, 0, v1, vcc
	v_lshl_add_u64 v[32:33], v[0:1], 0, s[8:9]
	s_lshl_b32 s92, s4, 7
	global_load_dwordx4 v[0:3], v[2:3], off offset:16
	s_nop 0
	global_load_dwordx4 v[16:19], v[4:5], off offset:1024
	global_load_dwordx4 v[20:23], v[6:7], off offset:3072
	s_nop 0
	global_load_dwordx4 v[4:7], v[32:33], off offset:16
	v_lshl_add_u64 v[32:33], v[166:167], 0, s[92:93]
	s_or_b32 s4, s4, s53
	v_lshlrev_b64 v[32:33], 8, v[32:33]
	s_lshl_b32 s92, s4, 7
	v_lshl_add_u64 v[32:33], v[168:169], 0, v[32:33]
	v_lshl_add_u64 v[68:69], s[92:93], 2, v[164:165]
	v_lshlrev_b32_e32 v125, 2, v70
	global_load_dwordx4 v[52:55], v[32:33], off
	global_load_dwordx4 v[48:51], v[32:33], off offset:64
	global_load_dwordx4 v[36:39], v[32:33], off offset:128
	s_nop 0
	global_load_dwordx4 v[32:35], v[32:33], off offset:192
	v_lshl_add_u32 v126, v173, 2, 0
	global_load_dword v174, v[68:69], off
	s_nop 0
	global_load_dwordx4 v[68:71], v125, s[0:1] offset:48
	global_load_dwordx4 v[88:91], v125, s[0:1] offset:32
	v_lshlrev_b32_e32 v172, 1, v122
	s_movk_i32 s4, 0x110
	s_waitcnt vmcnt(31)
	v_lshlrev_b32_e32 v137, 16, v108
	v_mul_f32_e32 v76, v137, v137
	v_fmamk_f32 v76, v76, 0xbdd2d3e8, v245
	v_mul_f32_e32 v76, v76, v137
	v_and_b32_e32 v108, 0xffff0000, v108
	v_mul_f32_e32 v117, v108, v108
	v_fmamk_f32 v117, v117, 0xbdd2d3e8, v245
	v_exp_f32_e32 v116, v76
	v_mul_f32_e32 v117, v117, v108
	v_exp_f32_e32 v142, v117
	v_add_f32_e32 v116, 1.0, v116
	v_rcp_f32_e32 v143, v116
	global_load_dwordx4 v[112:115], v125, s[0:1] offset:16
	global_load_dwordx4 v[128:131], v125, s[0:1]
	global_load_dwordx4 v[76:79], v125, s[72:73] offset:48
	global_load_dwordx4 v[92:95], v125, s[72:73] offset:32
	global_load_dwordx4 v[116:119], v125, s[72:73] offset:16
	global_load_dwordx4 v[132:135], v125, s[72:73]
	v_add_f32_e32 v125, 1.0, v142
	v_rcp_f32_e32 v125, v125
	s_waitcnt lgkmcnt(0)
	v_fma_f32 v137, v143, v137, -v156
	v_mul_f32_e32 v137, v157, v137
	s_waitcnt vmcnt(24)
	v_fma_f32 v137, v158, v137, v192
	v_fma_f32 v108, v125, v108, -v156
	v_cvt_pk_bf16_f32 v125, v137, v145
	v_mul_u32_u24_e32 v137, 0x10c, v173
	v_add3_u32 v171, v126, v137, v172
	ds_write_b16 v171, v125 offset:1024
	v_lshlrev_b32_e32 v125, 16, v109
	v_mul_f32_e32 v137, v125, v125
	v_and_b32_e32 v109, 0xffff0000, v109
	v_fmamk_f32 v137, v137, 0xbdd2d3e8, v245
	v_mul_f32_e32 v142, v109, v109
	v_mul_f32_e32 v137, v137, v125
	v_fmamk_f32 v142, v142, 0xbdd2d3e8, v245
	v_mul_f32_e32 v142, v142, v109
	v_exp_f32_e32 v137, v137
	v_exp_f32_e32 v142, v142
	v_mul_f32_e32 v108, v157, v108
	v_fma_f32 v108, v159, v108, v193
	v_cvt_pk_bf16_f32 v108, v108, v145
	v_add_f32_e32 v137, 1.0, v137
	v_rcp_f32_e32 v137, v137
	ds_write_b16 v171, v108 offset:1296
	v_add_f32_e32 v108, 1.0, v142
	v_rcp_f32_e32 v108, v108
	v_fma_f32 v125, v137, v125, -v156
	v_mul_f32_e32 v125, v157, v125
	v_fma_f32 v125, v160, v125, v194
	v_fma_f32 v108, v108, v109, -v156
	v_mul_f32_e32 v108, v157, v108
	v_lshlrev_b32_e32 v109, 16, v110
	v_fmac_f32_e32 v195, v161, v108
	v_cvt_pk_bf16_f32 v108, v125, v145
	v_mul_f32_e32 v125, v109, v109
	v_fmamk_f32 v125, v125, 0xbdd2d3e8, v245
	v_mul_f32_e32 v125, v125, v109
	v_and_b32_e32 v110, 0xffff0000, v110
	v_exp_f32_e32 v125, v125
	v_mul_f32_e32 v137, v110, v110
	v_fmamk_f32 v137, v137, 0xbdd2d3e8, v245
	v_mul_f32_e32 v137, v137, v110
	v_add_f32_e32 v125, 1.0, v125
	v_exp_f32_e32 v137, v137
	v_rcp_f32_e32 v125, v125
	ds_write_b16 v171, v108 offset:1568
	v_cvt_pk_bf16_f32 v108, v195, v145
	ds_write_b16 v171, v108 offset:1840
	v_add_f32_e32 v108, 1.0, v137
	v_fma_f32 v109, v125, v109, -v156
	v_rcp_f32_e32 v108, v108
	v_mul_f32_e32 v109, v157, v109
	v_fma_f32 v109, v138, v109, v188
	v_cvt_pk_bf16_f32 v109, v109, v145
	ds_write_b16 v171, v109 offset:2112
	v_lshlrev_b32_e32 v109, 16, v111
	v_fma_f32 v108, v108, v110, -v156
	v_mul_f32_e32 v110, v109, v109
	v_and_b32_e32 v111, 0xffff0000, v111
	v_fmamk_f32 v110, v110, 0xbdd2d3e8, v245
	v_mul_f32_e32 v125, v111, v111
	v_mul_f32_e32 v110, v110, v109
	v_fmamk_f32 v125, v125, 0xbdd2d3e8, v245
	v_mul_f32_e32 v125, v125, v111
	v_exp_f32_e32 v110, v110
	v_exp_f32_e32 v125, v125
	v_mul_f32_e32 v108, v157, v108
	v_fma_f32 v108, v139, v108, v189
	v_cvt_pk_bf16_f32 v108, v108, v145
	v_add_f32_e32 v110, 1.0, v110
	v_rcp_f32_e32 v110, v110
	ds_write_b16 v171, v108 offset:2384
	v_add_f32_e32 v108, 1.0, v125
	v_rcp_f32_e32 v108, v108
	v_fma_f32 v109, v110, v109, -v156
	v_mul_f32_e32 v109, v157, v109
	v_fma_f32 v109, v140, v109, v190
	v_fma_f32 v108, v108, v111, -v156
	v_mul_f32_e32 v108, v157, v108
	v_fmac_f32_e32 v191, v141, v108
	v_cvt_pk_bf16_f32 v108, v109, v145
	v_lshlrev_b32_e32 v109, 16, v72
	v_mul_f32_e32 v110, v109, v109
	v_fmamk_f32 v110, v110, 0xbdd2d3e8, v245
	v_mul_f32_e32 v110, v110, v109
	v_and_b32_e32 v72, 0xffff0000, v72
	v_mul_f32_e32 v111, v72, v72
	v_fmamk_f32 v111, v111, 0xbdd2d3e8, v245
	v_exp_f32_e32 v110, v110
	v_mul_f32_e32 v111, v111, v72
	v_exp_f32_e32 v111, v111
	v_add_f32_e32 v110, 1.0, v110
	v_rcp_f32_e32 v110, v110
	ds_write_b16 v171, v108 offset:2656
	v_cvt_pk_bf16_f32 v108, v191, v145
	ds_write_b16 v171, v108 offset:2928
	v_add_f32_e32 v108, 1.0, v111
	v_rcp_f32_e32 v108, v108
	v_fma_f32 v109, v110, v109, -v156
	v_mul_f32_e32 v109, v157, v109
	s_waitcnt vmcnt(19)
	v_fma_f32 v96, v109, v100, v96
	v_fma_f32 v72, v108, v72, -v156
	v_cvt_pk_bf16_f32 v96, v96, v145
	v_mul_f32_e32 v72, v157, v72
	ds_write_b16 v171, v96 offset:3200
	v_lshlrev_b32_e32 v96, 16, v73
	v_fma_f32 v72, v72, v101, v97
	v_mul_f32_e32 v97, v96, v96
	v_and_b32_e32 v73, 0xffff0000, v73
	v_fmamk_f32 v97, v97, 0xbdd2d3e8, v245
	v_mul_f32_e32 v100, v73, v73
	v_mul_f32_e32 v97, v97, v96
	v_fmamk_f32 v100, v100, 0xbdd2d3e8, v245
	v_mul_f32_e32 v100, v100, v73
	v_exp_f32_e32 v97, v97
	v_exp_f32_e32 v100, v100
	v_cvt_pk_bf16_f32 v72, v72, v145
	v_add_f32_e32 v97, 1.0, v97
	v_rcp_f32_e32 v97, v97
	ds_write_b16 v171, v72 offset:3472
	v_add_f32_e32 v72, 1.0, v100
	v_rcp_f32_e32 v72, v72
	v_fma_f32 v96, v97, v96, -v156
	v_mul_f32_e32 v96, v157, v96
	v_fma_f32 v96, v96, v102, v98
	v_fma_f32 v72, v72, v73, -v156
	v_mul_f32_e32 v72, v157, v72
	v_lshlrev_b32_e32 v73, 16, v74
	v_fmac_f32_e32 v99, v72, v103
	v_cvt_pk_bf16_f32 v72, v96, v145
	v_mul_f32_e32 v96, v73, v73
	v_fmamk_f32 v96, v96, 0xbdd2d3e8, v245
	v_mul_f32_e32 v96, v96, v73
	v_and_b32_e32 v74, 0xffff0000, v74
	v_exp_f32_e32 v96, v96
	v_mul_f32_e32 v97, v74, v74
	v_fmamk_f32 v97, v97, 0xbdd2d3e8, v245
	v_mul_f32_e32 v97, v97, v74
	v_add_f32_e32 v96, 1.0, v96
	v_exp_f32_e32 v97, v97
	v_rcp_f32_e32 v96, v96
	ds_write_b16 v171, v72 offset:3744
	v_cvt_pk_bf16_f32 v72, v99, v145
	ds_write_b16 v171, v72 offset:4016
	v_add_f32_e32 v72, 1.0, v97
	v_fma_f32 v73, v96, v73, -v156
	v_rcp_f32_e32 v72, v72
	v_mul_f32_e32 v73, v157, v73
	v_fma_f32 v73, v73, v84, v80
	v_cvt_pk_bf16_f32 v73, v73, v145
	ds_write_b16 v171, v73 offset:4288
	v_lshlrev_b32_e32 v73, 16, v75
	v_and_b32_e32 v75, 0xffff0000, v75
	v_fma_f32 v72, v72, v74, -v156
	v_mul_f32_e32 v74, v73, v73
	v_mul_f32_e32 v80, v75, v75
	v_fmamk_f32 v74, v74, 0xbdd2d3e8, v245
	v_fmamk_f32 v80, v80, 0xbdd2d3e8, v245
	v_mul_f32_e32 v74, v74, v73
	v_mul_f32_e32 v80, v80, v75
	v_exp_f32_e32 v74, v74
	v_exp_f32_e32 v80, v80
	v_mul_f32_e32 v72, v157, v72
	v_fma_f32 v72, v72, v85, v81
	v_cvt_pk_bf16_f32 v72, v72, v145
	v_add_f32_e32 v74, 1.0, v74
	ds_write_b16 v171, v72 offset:4560
	v_add_f32_e32 v72, 1.0, v80
	v_rcp_f32_e32 v74, v74
	v_rcp_f32_e32 v72, v72
	v_ashrrev_i32_e32 v125, 31, v124
	v_mul_u32_u24_e32 v189, 0x110, v173
	v_fma_f32 v73, v74, v73, -v156
	v_fma_f32 v72, v72, v75, -v156
	v_mul_f32_e32 v73, v157, v73
	v_mul_f32_e32 v72, v157, v72
	v_fma_f32 v73, v73, v86, v82
	v_fmac_f32_e32 v83, v72, v87
	v_cvt_pk_bf16_f32 v72, v73, v145
	ds_write_b16 v171, v72 offset:4832
	v_cvt_pk_bf16_f32 v72, v83, v145
	ds_write_b16 v171, v72 offset:5104
	v_mul_u32_u24_e32 v72, 0x110, v136
	v_add3_u32 v170, 0, v121, v72
	s_waitcnt lgkmcnt(0)
	s_barrier
	ds_read_b128 v[72:75], v170 offset:1024
	ds_read_b128 v[80:83], v170 offset:1088
	ds_read_b128 v[84:87], v170 offset:5376
	ds_read_b128 v[96:99], v170 offset:5440
	ds_read_b128 v[100:103], v170 offset:9728
	ds_read_b128 v[108:111], v170 offset:9792
	ds_read_b128 v[138:141], v170 offset:14080
	ds_read_b128 v[158:161], v170 offset:14144
	s_waitcnt lgkmcnt(7)
	v_mfma_f32_16x16x32_bf16 v[72:75], v[60:63], v[72:75], 0
	v_add3_u32 v172, 0, v189, v172
	s_waitcnt lgkmcnt(5)
	v_mfma_f32_16x16x32_bf16 v[84:87], v[60:63], v[84:87], 0
	s_waitcnt lgkmcnt(3)
	v_mfma_f32_16x16x32_bf16 v[100:103], v[60:63], v[100:103], 0
	s_waitcnt lgkmcnt(1)
	v_mfma_f32_16x16x32_bf16 v[60:63], v[60:63], v[138:141], 0
	v_mfma_f32_16x16x32_bf16 v[72:75], v[56:59], v[80:83], v[72:75]
	v_mfma_f32_16x16x32_bf16 v[80:83], v[56:59], v[96:99], v[84:87]
	v_mfma_f32_16x16x32_bf16 v[84:87], v[56:59], v[108:111], v[100:103]
	s_waitcnt lgkmcnt(0)
	v_mfma_f32_16x16x32_bf16 v[56:59], v[56:59], v[158:161], v[60:63]
	s_nop 2
	ds_read_b128 v[60:63], v170 offset:1152
	ds_read_b128 v[96:99], v170 offset:1216
	v_mad_u64_u32 v[158:159], s[6:7], v122, s4, v[126:127]
	s_waitcnt lgkmcnt(1)
	v_mfma_f32_16x16x32_bf16 v[60:63], v[44:47], v[60:63], v[72:75]
	s_nop 2
	ds_read_b128 v[72:75], v170 offset:5504
	ds_read_b128 v[100:103], v170 offset:5568
	s_mov_b64 s[6:7], 0x11b80c00
	s_waitcnt lgkmcnt(1)
	v_mfma_f32_16x16x32_bf16 v[72:75], v[44:47], v[72:75], v[80:83]
	s_nop 2
	ds_read_b128 v[80:83], v170 offset:9856
	ds_read_b128 v[108:111], v170 offset:9920
	s_waitcnt lgkmcnt(1)
	v_mfma_f32_16x16x32_bf16 v[80:83], v[44:47], v[80:83], v[84:87]
	s_nop 2
	ds_read_b128 v[84:87], v170 offset:14208
	ds_read_b128 v[138:141], v170 offset:14272
	s_waitcnt lgkmcnt(1)
	v_mfma_f32_16x16x32_bf16 v[56:59], v[44:47], v[84:87], v[56:59]
	v_lshrrev_b32_e32 v44, 2, v127
	v_and_or_b32 v46, v44, 12, v120
	v_lshlrev_b32_e32 v47, 2, v136
	v_mul_lo_u32 v46, v46, s4
	v_add3_u32 v46, 0, v47, v46
	v_lshlrev_b32_e32 v47, 16, v28
	v_mfma_f32_16x16x32_bf16 v[60:63], v[40:43], v[96:99], v[60:63]
	v_add_u32_e32 v159, 0x8c00, v46
	v_lshlrev_b32_e32 v46, 16, v24
	v_lshlrev_b64 v[44:45], 12, v[124:125]
	v_mfma_f32_16x16x32_bf16 v[72:75], v[40:43], v[100:103], v[72:75]
	v_lshl_add_u64 v[44:45], s[48:49], 0, v[44:45]
	s_or_b32 s4, s5, 2
	s_lshl_b32 s92, s4, 7
	v_mfma_f32_16x16x32_bf16 v[80:83], v[40:43], v[108:111], v[80:83]
	s_waitcnt lgkmcnt(0)
	v_mfma_f32_16x16x32_bf16 v[40:43], v[40:43], v[138:141], v[56:59]
	s_nop 1
	ds_write2_b32 v159, v60, v72 offset1:16
	s_nop 4
	ds_write2_b32 v159, v80, v40 offset0:32 offset1:48
	ds_write2_b32 v159, v61, v73 offset0:68 offset1:84
	ds_write2_b32 v159, v81, v41 offset0:100 offset1:116
	ds_write2_b32 v159, v62, v74 offset0:136 offset1:152
	ds_write2_b32 v159, v82, v42 offset0:168 offset1:184
	ds_write2_b32 v159, v63, v75 offset0:204 offset1:220
	ds_write2_b32 v159, v83, v43 offset0:236 offset1:252
	v_mul_f32_e32 v56, v47, v47
	v_fmamk_f32 v56, v56, 0xbdd2d3e8, v245
	v_mov_b32_e32 v57, v47
	v_mul_f32_e32 v56, v56, v57
	v_exp_f32_e32 v56, v56
	v_mul_f32_e32 v57, 0xbfb8aa3b, v46
	v_exp_f32_e32 v58, v57
	v_and_b32_e32 v59, 0xffff0000, v28
	v_add_f32_e32 v56, 1.0, v56
	v_rcp_f32_e32 v57, v56
	v_add_f32_e32 v56, 1.0, v58
	v_and_b32_e32 v58, 0xffff0000, v24
	v_mul_f32_e32 v24, v59, v59
	v_fmamk_f32 v24, v24, 0xbdd2d3e8, v245
	v_mov_b32_e32 v28, v59
	v_mul_f32_e32 v24, v24, v28
	v_exp_f32_e32 v24, v24
	v_mul_f32_e32 v28, 0xbfb8aa3b, v58
	v_rcp_f32_e32 v56, v56
	v_exp_f32_e32 v28, v28
	s_waitcnt lgkmcnt(0)
	s_barrier
	ds_read_b128 v[40:43], v158 offset:35840
	v_add_f32_e32 v24, 1.0, v24
	v_pk_mul_f32 v[46:47], v[56:57], v[46:47]
	v_rcp_f32_e32 v57, v24
	v_add_f32_e32 v24, 1.0, v28
	v_rcp_f32_e32 v56, v24
	s_waitcnt lgkmcnt(0)
	v_add_f32_e32 v40, v123, v40
	v_mul_f32_e32 v24, v47, v40
	v_add_f32_e32 v28, v123, v41
	v_pk_mul_f32 v[40:41], v[56:57], v[58:59]
	v_mul_f32_e32 v24, v46, v24
	v_mul_f32_e32 v28, v41, v28
	v_mul_f32_e32 v28, v40, v28
	v_lshlrev_b32_e32 v41, 16, v29
	v_cvt_pk_bf16_f32 v24, v24, v28
	v_mul_f32_e32 v28, v41, v41
	v_fmamk_f32 v28, v28, 0xbdd2d3e8, v245
	v_mov_b32_e32 v46, v41
	v_mul_f32_e32 v28, v28, v46
	v_lshlrev_b32_e32 v40, 16, v25
	v_exp_f32_e32 v28, v28
	v_mul_f32_e32 v46, 0xbfb8aa3b, v40
	v_exp_f32_e32 v46, v46
	v_and_b32_e32 v29, 0xffff0000, v29
	v_add_f32_e32 v28, 1.0, v28
	v_rcp_f32_e32 v47, v28
	v_add_f32_e32 v28, 1.0, v46
	v_rcp_f32_e32 v46, v28
	v_and_b32_e32 v28, 0xffff0000, v25
	v_mul_f32_e32 v25, v29, v29
	v_fmamk_f32 v25, v25, 0xbdd2d3e8, v245
	v_mov_b32_e32 v56, v29
	v_mul_f32_e32 v25, v25, v56
	v_exp_f32_e32 v25, v25
	v_mul_f32_e32 v56, 0xbfb8aa3b, v28
	v_exp_f32_e32 v56, v56
	v_pk_mul_f32 v[40:41], v[46:47], v[40:41]
	v_add_f32_e32 v25, 1.0, v25
	v_rcp_f32_e32 v47, v25
	v_add_f32_e32 v25, 1.0, v56
	v_rcp_f32_e32 v46, v25
	v_add_f32_e32 v42, v123, v42
	v_mul_f32_e32 v25, v41, v42
	v_mul_f32_e32 v25, v40, v25
	v_add_f32_e32 v40, v123, v43
	v_pk_mul_f32 v[28:29], v[46:47], v[28:29]
	v_and_b32_e32 v57, 0xffff0000, v30
	v_mul_f32_e32 v29, v29, v40
	v_mul_f32_e32 v28, v28, v29
	v_lshlrev_b32_e32 v29, 16, v30
	v_mul_f32_e32 v46, v29, v29
	v_fmamk_f32 v46, v46, 0xbdd2d3e8, v245
	v_mov_b32_e32 v47, v29
	v_mul_f32_e32 v46, v46, v47
	v_cvt_pk_bf16_f32 v25, v25, v28
	v_lshlrev_b32_e32 v28, 16, v26
	v_exp_f32_e32 v46, v46
	v_mul_f32_e32 v47, 0xbfb8aa3b, v28
	v_exp_f32_e32 v56, v47
	v_mov_b32_e32 v30, v57
	v_add_f32_e32 v46, 1.0, v46
	v_rcp_f32_e32 v47, v46
	v_add_f32_e32 v46, 1.0, v56
	v_and_b32_e32 v56, 0xffff0000, v26
	v_mul_f32_e32 v26, 0x3d372713, v57
	v_mul_f32_e32 v26, v26, v57
	v_fmac_f32_e32 v30, v26, v30
	v_mul_f32_e32 v26, 0x3fcc422a, v30
	v_mul_f32_e32 v26, 0xbfb8aa3b, v26
	v_exp_f32_e32 v26, v26
	v_mul_f32_e32 v30, 0xbfb8aa3b, v56
	v_rcp_f32_e32 v46, v46
	v_exp_f32_e32 v30, v30
	ds_read_b128 v[40:43], v158 offset:35856
	v_add_f32_e32 v26, 1.0, v26
	v_pk_mul_f32 v[28:29], v[46:47], v[28:29]
	v_rcp_f32_e32 v47, v26
	v_add_f32_e32 v26, 1.0, v30
	v_rcp_f32_e32 v46, v26
	s_waitcnt lgkmcnt(0)
	v_add_f32_e32 v40, v123, v40
	v_mul_f32_e32 v26, v29, v40
	v_mul_f32_e32 v26, v28, v26
	v_add_f32_e32 v30, v123, v41
	v_pk_mul_f32 v[28:29], v[46:47], v[56:57]
	v_add_f32_e32 v42, v123, v42
	v_mul_f32_e32 v29, v29, v30
	v_mul_f32_e32 v28, v28, v29
	v_lshlrev_b32_e32 v29, 16, v31
	v_mul_f32_e32 v30, v29, v29
	v_fmamk_f32 v30, v30, 0xbdd2d3e8, v245
	v_mov_b32_e32 v40, v29
	v_mul_f32_e32 v30, v30, v40
	v_cvt_pk_bf16_f32 v26, v26, v28
	v_lshlrev_b32_e32 v28, 16, v27
	v_exp_f32_e32 v30, v30
	v_mul_f32_e32 v40, 0xbfb8aa3b, v28
	v_exp_f32_e32 v40, v40
	v_and_b32_e32 v31, 0xffff0000, v31
	v_add_f32_e32 v30, 1.0, v30
	v_rcp_f32_e32 v41, v30
	v_add_f32_e32 v30, 1.0, v40
	v_rcp_f32_e32 v40, v30
	v_and_b32_e32 v30, 0xffff0000, v27
	v_mul_f32_e32 v27, v31, v31
	v_fmamk_f32 v27, v27, 0xbdd2d3e8, v245
	v_mov_b32_e32 v46, v31
	v_mul_f32_e32 v27, v27, v46
	v_exp_f32_e32 v27, v27
	v_mul_f32_e32 v46, 0xbfb8aa3b, v30
	v_exp_f32_e32 v46, v46
	v_pk_mul_f32 v[28:29], v[40:41], v[28:29]
	v_add_f32_e32 v27, 1.0, v27
	v_rcp_f32_e32 v41, v27
	v_add_f32_e32 v27, 1.0, v46
	v_rcp_f32_e32 v40, v27
	v_mul_f32_e32 v27, v29, v42
	v_mul_f32_e32 v27, v28, v27
	v_add_f32_e32 v42, v123, v43
	v_pk_mul_f32 v[28:29], v[40:41], v[30:31]
	v_lshlrev_b32_e32 v41, 16, v8
	v_mul_f32_e32 v29, v29, v42
	v_mul_f32_e32 v42, v41, v41
	v_fmamk_f32 v42, v42, 0xbdd2d3e8, v245
	v_mov_b32_e32 v43, v41
	v_mul_f32_e32 v42, v42, v43
	v_lshlrev_b32_e32 v40, 16, v12
	v_exp_f32_e32 v42, v42
	v_mul_f32_e32 v43, 0xbfb8aa3b, v40
	v_exp_f32_e32 v46, v43
	v_and_b32_e32 v47, 0xffff0000, v8
	v_add_f32_e32 v42, 1.0, v42
	v_mul_f32_e32 v8, v47, v47
	v_rcp_f32_e32 v43, v42
	v_add_f32_e32 v42, 1.0, v46
	v_and_b32_e32 v46, 0xffff0000, v12
	v_fmamk_f32 v8, v8, 0xbdd2d3e8, v245
	v_mov_b32_e32 v12, v47
	v_mul_f32_e32 v8, v8, v12
	v_exp_f32_e32 v8, v8
	v_mul_f32_e32 v12, 0xbfb8aa3b, v46
	v_rcp_f32_e32 v42, v42
	v_exp_f32_e32 v12, v12
	v_mul_f32_e32 v28, v28, v29
	v_cvt_pk_bf16_f32 v27, v27, v28
	ds_read_b128 v[28:31], v158 offset:35872
	v_add_f32_e32 v8, 1.0, v8
	v_pk_mul_f32 v[40:41], v[42:43], v[40:41]
	v_rcp_f32_e32 v43, v8
	v_add_f32_e32 v8, 1.0, v12
	v_rcp_f32_e32 v42, v8
	s_waitcnt lgkmcnt(0)
	v_add_f32_e32 v28, v123, v28
	v_mul_f32_e32 v8, v41, v28
	v_add_f32_e32 v12, v123, v29
	v_pk_mul_f32 v[28:29], v[42:43], v[46:47]
	v_mul_f32_e32 v8, v40, v8
	v_mul_f32_e32 v12, v29, v12
	v_mul_f32_e32 v12, v28, v12
	v_lshlrev_b32_e32 v29, 16, v9
	v_cvt_pk_bf16_f32 v8, v8, v12
	v_mul_f32_e32 v12, v29, v29
	v_fmamk_f32 v12, v12, 0xbdd2d3e8, v245
	v_mov_b32_e32 v40, v29
	v_mul_f32_e32 v12, v12, v40
	v_lshlrev_b32_e32 v28, 16, v13
	v_exp_f32_e32 v12, v12
	v_mul_f32_e32 v40, 0xbfb8aa3b, v28
	v_exp_f32_e32 v40, v40
	v_and_b32_e32 v43, 0xffff0000, v9
	v_add_f32_e32 v12, 1.0, v12
	v_rcp_f32_e32 v41, v12
	v_add_f32_e32 v12, 1.0, v40
	v_mul_f32_e32 v9, v43, v43
	v_rcp_f32_e32 v40, v12
	v_fmamk_f32 v9, v9, 0xbdd2d3e8, v245
	v_mov_b32_e32 v12, v43
	v_mul_f32_e32 v9, v9, v12
	v_and_b32_e32 v42, 0xffff0000, v13
	v_exp_f32_e32 v9, v9
	v_mul_f32_e32 v12, 0xbfb8aa3b, v42
	v_exp_f32_e32 v46, v12
	v_pk_mul_f32 v[12:13], v[40:41], v[28:29]
	v_add_f32_e32 v9, 1.0, v9
	v_rcp_f32_e32 v29, v9
	v_add_f32_e32 v9, 1.0, v46
	v_rcp_f32_e32 v28, v9
	v_add_f32_e32 v30, v123, v30
	v_mul_f32_e32 v9, v13, v30
	v_mul_f32_e32 v9, v12, v9
	v_add_f32_e32 v30, v123, v31
	v_pk_mul_f32 v[12:13], v[28:29], v[42:43]
	v_and_b32_e32 v43, 0xffff0000, v10
	v_mul_f32_e32 v13, v13, v30
	v_mul_f32_e32 v12, v12, v13
	v_lshlrev_b32_e32 v13, 16, v10
	v_mul_f32_e32 v40, v13, v13
	v_fmamk_f32 v40, v40, 0xbdd2d3e8, v245
	v_mov_b32_e32 v41, v13
	v_mul_f32_e32 v40, v40, v41
	v_cvt_pk_bf16_f32 v9, v9, v12
	v_lshlrev_b32_e32 v12, 16, v14
	v_exp_f32_e32 v40, v40
	v_mul_f32_e32 v41, 0xbfb8aa3b, v12
	v_exp_f32_e32 v42, v41
	v_mul_f32_e32 v10, v43, v43
	v_add_f32_e32 v40, 1.0, v40
	v_rcp_f32_e32 v41, v40
	v_add_f32_e32 v40, 1.0, v42
	v_and_b32_e32 v42, 0xffff0000, v14
	v_fmamk_f32 v10, v10, 0xbdd2d3e8, v245
	v_mov_b32_e32 v14, v43
	v_mul_f32_e32 v10, v10, v14
	v_exp_f32_e32 v10, v10
	v_mul_f32_e32 v14, 0xbfb8aa3b, v42
	v_rcp_f32_e32 v40, v40
	v_exp_f32_e32 v14, v14
	ds_read_b128 v[28:31], v158 offset:35888
	v_add_f32_e32 v10, 1.0, v10
	v_pk_mul_f32 v[12:13], v[40:41], v[12:13]
	v_rcp_f32_e32 v41, v10
	v_add_f32_e32 v10, 1.0, v14
	v_rcp_f32_e32 v40, v10
	s_waitcnt lgkmcnt(0)
	v_add_f32_e32 v28, v123, v28
	v_mul_f32_e32 v10, v13, v28
	v_mul_f32_e32 v10, v12, v10
	v_add_f32_e32 v14, v123, v29
	v_pk_mul_f32 v[12:13], v[40:41], v[42:43]
	v_and_b32_e32 v41, 0xffff0000, v11
	v_mul_f32_e32 v13, v13, v14
	v_mul_f32_e32 v12, v12, v13
	v_lshlrev_b32_e32 v13, 16, v11
	v_mul_f32_e32 v14, v13, v13
	v_fmamk_f32 v14, v14, 0xbdd2d3e8, v245
	v_mov_b32_e32 v28, v13
	v_mul_f32_e32 v14, v14, v28
	v_cvt_pk_bf16_f32 v10, v10, v12
	v_lshlrev_b32_e32 v12, 16, v15
	v_exp_f32_e32 v14, v14
	v_mul_f32_e32 v28, 0xbfb8aa3b, v12
	v_exp_f32_e32 v28, v28
	v_mul_f32_e32 v11, v41, v41
	v_add_f32_e32 v14, 1.0, v14
	v_rcp_f32_e32 v29, v14
	v_add_f32_e32 v14, 1.0, v28
	v_rcp_f32_e32 v28, v14
	v_fmamk_f32 v11, v11, 0xbdd2d3e8, v245
	v_mov_b32_e32 v14, v41
	v_mul_f32_e32 v11, v11, v14
	v_and_b32_e32 v40, 0xffff0000, v15
	v_exp_f32_e32 v11, v11
	v_mul_f32_e32 v14, 0xbfb8aa3b, v40
	v_exp_f32_e32 v14, v14
	v_add_f32_e32 v30, v123, v30
	v_add_f32_e32 v11, 1.0, v11
	v_rcp_f32_e32 v15, v11
	v_add_f32_e32 v11, 1.0, v14
	v_rcp_f32_e32 v14, v11
	v_pk_mul_f32 v[12:13], v[28:29], v[12:13]
	v_add_f32_e32 v28, v123, v31
	v_mul_f32_e32 v11, v13, v30
	v_mul_f32_e32 v11, v12, v11
	v_pk_mul_f32 v[12:13], v[14:15], v[40:41]
	v_lshl_or_b32 v82, s4, 6, v173
	v_mul_f32_e32 v13, v13, v28
	v_mul_f32_e32 v12, v12, v13
	v_cvt_pk_bf16_f32 v11, v11, v12
	v_lshl_add_u64 v[12:13], v[44:45], 0, v[144:145]
	v_lshl_add_u64 v[160:161], v[12:13], 0, s[6:7]
	v_add_co_u32_e32 v12, vcc, s89, v12
	v_lshlrev_b32_e32 v144, 1, v82
	s_nop 0
	v_addc_co_u32_e32 v13, vcc, 0, v13, vcc
	global_store_dwordx4 v[12:13], v[24:27], off offset:3072
	global_store_dwordx4 v[160:161], v[8:11], off offset:16
	s_or_b32 s4, s4, s53
	v_lshlrev_b32_e32 v140, 2, v82
	v_lshl_add_u64 v[8:9], v[162:163], 0, v[144:145]
	s_waitcnt vmcnt(20)
	v_lshlrev_b32_e32 v144, 16, v104
	v_mul_f32_e32 v84, v144, v144
	v_fmamk_f32 v84, v84, 0xbdd2d3e8, v245
	v_mul_f32_e32 v84, v84, v144
	v_and_b32_e32 v104, 0xffff0000, v104
	v_mul_f32_e32 v125, v104, v104
	v_fmamk_f32 v125, v125, 0xbdd2d3e8, v245
	v_exp_f32_e32 v124, v84
	v_mul_f32_e32 v125, v125, v104
	v_exp_f32_e32 v190, v125
	v_add_f32_e32 v124, 1.0, v124
	v_add_co_u32_e32 v12, vcc, s3, v8
	v_rcp_f32_e32 v191, v124
	s_nop 0
	v_addc_co_u32_e32 v13, vcc, 0, v9, vcc
	v_lshl_add_u64 v[10:11], v[8:9], 0, s[14:15]
	v_add_co_u32_e32 v14, vcc, s74, v8
	v_add_f32_e32 v190, 1.0, v190
	global_load_dwordx4 v[108:111], v[12:13], off
	global_load_dwordx4 v[72:75], v[10:11], off offset:16
	v_lshl_add_u64 v[10:11], v[8:9], 0, s[16:17]
	v_addc_co_u32_e32 v15, vcc, 0, v9, vcc
	v_lshl_add_u64 v[40:41], v[8:9], 0, s[8:9]
	v_rcp_f32_e32 v190, v190
	global_load_dwordx4 v[8:11], v[10:11], off offset:16
	s_nop 0
	global_load_dwordx4 v[24:27], v[12:13], off offset:1024
	global_load_dwordx4 v[28:31], v[14:15], off offset:3072
	s_nop 0
	global_load_dwordx4 v[12:15], v[40:41], off offset:16
	v_lshl_add_u64 v[40:41], v[166:167], 0, s[92:93]
	v_fma_f32 v144, v191, v144, -v156
	v_lshlrev_b64 v[40:41], 8, v[40:41]
	s_lshl_b32 s92, s4, 7
	v_mul_f32_e32 v144, v157, v144
	v_lshl_add_u64 v[40:41], v[168:169], 0, v[40:41]
	v_lshl_add_u64 v[80:81], s[92:93], 2, v[164:165]
	s_waitcnt vmcnt(8)
	v_fma_f32 v128, v128, v144, v132
	global_load_dwordx4 v[60:63], v[40:41], off
	global_load_dwordx4 v[56:59], v[40:41], off offset:64
	global_load_dwordx4 v[44:47], v[40:41], off offset:128
	s_nop 0
	global_load_dwordx4 v[40:43], v[40:41], off offset:192
	v_fma_f32 v104, v190, v104, -v156
	global_load_dword v188, v[80:81], off
	s_nop 0
	global_load_dwordx4 v[80:83], v140, s[0:1] offset:48
	global_load_dwordx4 v[96:99], v140, s[0:1] offset:32
	global_load_dwordx4 v[120:123], v140, s[0:1] offset:16
	global_load_dwordx4 v[136:139], v140, s[0:1]
	global_load_dwordx4 v[84:87], v140, s[72:73] offset:48
	global_load_dwordx4 v[100:103], v140, s[72:73] offset:32
	global_load_dwordx4 v[124:127], v140, s[72:73] offset:16
	s_nop 0
	global_load_dwordx4 v[140:143], v140, s[72:73]
	v_cvt_pk_bf16_f32 v128, v128, v145
	v_mul_f32_e32 v104, v157, v104
	ds_write_b16 v172, v128 offset:18432
	v_lshlrev_b32_e32 v128, 16, v105
	v_fma_f32 v104, v129, v104, v133
	v_mul_f32_e32 v129, v128, v128
	v_and_b32_e32 v105, 0xffff0000, v105
	v_fmamk_f32 v129, v129, 0xbdd2d3e8, v245
	v_mul_f32_e32 v132, v105, v105
	v_mul_f32_e32 v129, v129, v128
	v_fmamk_f32 v132, v132, 0xbdd2d3e8, v245
	v_mul_f32_e32 v132, v132, v105
	v_exp_f32_e32 v129, v129
	v_exp_f32_e32 v132, v132
	v_cvt_pk_bf16_f32 v104, v104, v145
	v_add_f32_e32 v129, 1.0, v129
	v_rcp_f32_e32 v129, v129
	ds_write_b16 v172, v104 offset:18704
	v_add_f32_e32 v104, 1.0, v132
	v_rcp_f32_e32 v104, v104
	v_fma_f32 v128, v129, v128, -v156
	v_mul_f32_e32 v128, v157, v128
	v_fma_f32 v128, v130, v128, v134
	v_fma_f32 v104, v104, v105, -v156
	v_mul_f32_e32 v104, v157, v104
	v_lshlrev_b32_e32 v105, 16, v106
	v_fmac_f32_e32 v135, v131, v104
	v_cvt_pk_bf16_f32 v104, v128, v145
	v_mul_f32_e32 v128, v105, v105
	v_fmamk_f32 v128, v128, 0xbdd2d3e8, v245
	v_mul_f32_e32 v128, v128, v105
	v_and_b32_e32 v106, 0xffff0000, v106
	v_exp_f32_e32 v128, v128
	v_mul_f32_e32 v129, v106, v106
	v_fmamk_f32 v129, v129, 0xbdd2d3e8, v245
	v_mul_f32_e32 v129, v129, v106
	v_add_f32_e32 v128, 1.0, v128
	v_exp_f32_e32 v129, v129
	v_rcp_f32_e32 v128, v128
	ds_write_b16 v172, v104 offset:18976
	v_cvt_pk_bf16_f32 v104, v135, v145
	ds_write_b16 v172, v104 offset:19248
	v_add_f32_e32 v104, 1.0, v129
	v_fma_f32 v105, v128, v105, -v156
	v_rcp_f32_e32 v104, v104
	v_mul_f32_e32 v105, v157, v105
	v_fma_f32 v105, v112, v105, v116
	v_cvt_pk_bf16_f32 v105, v105, v145
	ds_write_b16 v172, v105 offset:19520
	v_lshlrev_b32_e32 v105, 16, v107
	v_fma_f32 v104, v104, v106, -v156
	v_mul_f32_e32 v106, v105, v105
	v_and_b32_e32 v107, 0xffff0000, v107
	v_fmamk_f32 v106, v106, 0xbdd2d3e8, v245
	v_mul_f32_e32 v112, v107, v107
	v_mul_f32_e32 v106, v106, v105
	v_fmamk_f32 v112, v112, 0xbdd2d3e8, v245
	v_mul_f32_e32 v112, v112, v107
	v_exp_f32_e32 v106, v106
	v_exp_f32_e32 v112, v112
	v_mul_f32_e32 v104, v157, v104
	v_fma_f32 v104, v113, v104, v117
	v_cvt_pk_bf16_f32 v104, v104, v145
	v_add_f32_e32 v106, 1.0, v106
	v_rcp_f32_e32 v106, v106
	ds_write_b16 v172, v104 offset:19792
	v_add_f32_e32 v104, 1.0, v112
	v_rcp_f32_e32 v104, v104
	v_fma_f32 v105, v106, v105, -v156
	v_mul_f32_e32 v105, v157, v105
	v_fma_f32 v105, v114, v105, v118
	v_fma_f32 v104, v104, v107, -v156
	v_mul_f32_e32 v104, v157, v104
	v_fmac_f32_e32 v119, v115, v104
	v_cvt_pk_bf16_f32 v104, v105, v145
	v_lshlrev_b32_e32 v105, 16, v64
	v_mul_f32_e32 v106, v105, v105
	v_fmamk_f32 v106, v106, 0xbdd2d3e8, v245
	v_mul_f32_e32 v106, v106, v105
	v_and_b32_e32 v64, 0xffff0000, v64
	v_mul_f32_e32 v107, v64, v64
	v_fmamk_f32 v107, v107, 0xbdd2d3e8, v245
	v_exp_f32_e32 v106, v106
	v_mul_f32_e32 v107, v107, v64
	v_exp_f32_e32 v107, v107
	v_add_f32_e32 v106, 1.0, v106
	v_rcp_f32_e32 v106, v106
	ds_write_b16 v172, v104 offset:20064
	v_cvt_pk_bf16_f32 v104, v119, v145
	ds_write_b16 v172, v104 offset:20336
	v_add_f32_e32 v104, 1.0, v107
	v_rcp_f32_e32 v104, v104
	v_fma_f32 v105, v106, v105, -v156
	v_mul_f32_e32 v105, v157, v105
	v_fma_f32 v88, v105, v88, v92
	v_fma_f32 v64, v104, v64, -v156
	v_cvt_pk_bf16_f32 v88, v88, v145
	v_mul_f32_e32 v64, v157, v64
	ds_write_b16 v172, v88 offset:20608
	v_lshlrev_b32_e32 v88, 16, v65
	v_fma_f32 v64, v64, v89, v93
	v_mul_f32_e32 v89, v88, v88
	v_and_b32_e32 v65, 0xffff0000, v65
	v_fmamk_f32 v89, v89, 0xbdd2d3e8, v245
	v_mul_f32_e32 v92, v65, v65
	v_mul_f32_e32 v89, v89, v88
	v_fmamk_f32 v92, v92, 0xbdd2d3e8, v245
	v_mul_f32_e32 v92, v92, v65
	v_exp_f32_e32 v89, v89
	v_exp_f32_e32 v92, v92
	v_cvt_pk_bf16_f32 v64, v64, v145
	v_add_f32_e32 v89, 1.0, v89
	v_rcp_f32_e32 v89, v89
	ds_write_b16 v172, v64 offset:20880
	v_add_f32_e32 v64, 1.0, v92
	v_rcp_f32_e32 v64, v64
	v_fma_f32 v88, v89, v88, -v156
	v_mul_f32_e32 v88, v157, v88
	v_fma_f32 v88, v88, v90, v94
	v_fma_f32 v64, v64, v65, -v156
	v_mul_f32_e32 v64, v157, v64
	v_lshlrev_b32_e32 v65, 16, v66
	v_fmac_f32_e32 v95, v64, v91
	v_cvt_pk_bf16_f32 v64, v88, v145
	v_mul_f32_e32 v88, v65, v65
	v_fmamk_f32 v88, v88, 0xbdd2d3e8, v245
	v_mul_f32_e32 v88, v88, v65
	v_and_b32_e32 v66, 0xffff0000, v66
	v_exp_f32_e32 v88, v88
	v_mul_f32_e32 v89, v66, v66
	v_fmamk_f32 v89, v89, 0xbdd2d3e8, v245
	v_mul_f32_e32 v89, v89, v66
	v_add_f32_e32 v88, 1.0, v88
	v_exp_f32_e32 v89, v89
	v_rcp_f32_e32 v88, v88
	ds_write_b16 v172, v64 offset:21152
	v_cvt_pk_bf16_f32 v64, v95, v145
	ds_write_b16 v172, v64 offset:21424
	v_add_f32_e32 v64, 1.0, v89
	v_fma_f32 v65, v88, v65, -v156
	v_rcp_f32_e32 v64, v64
	v_mul_f32_e32 v65, v157, v65
	v_fma_f32 v65, v65, v68, v76
	v_cvt_pk_bf16_f32 v65, v65, v145
	ds_write_b16 v172, v65 offset:21696
	v_lshlrev_b32_e32 v65, 16, v67
	v_and_b32_e32 v67, 0xffff0000, v67
	v_fma_f32 v64, v64, v66, -v156
	v_mul_f32_e32 v66, v65, v65
	v_mul_f32_e32 v68, v67, v67
	v_fmamk_f32 v66, v66, 0xbdd2d3e8, v245
	v_fmamk_f32 v68, v68, 0xbdd2d3e8, v245
	v_mul_f32_e32 v66, v66, v65
	v_mul_f32_e32 v68, v68, v67
	v_exp_f32_e32 v66, v66
	v_exp_f32_e32 v68, v68
	v_mul_f32_e32 v64, v157, v64
	v_fma_f32 v64, v64, v69, v77
	v_cvt_pk_bf16_f32 v64, v64, v145
	v_add_f32_e32 v66, 1.0, v66
	ds_write_b16 v172, v64 offset:21968
	v_add_f32_e32 v64, 1.0, v68
	v_rcp_f32_e32 v66, v66
	v_rcp_f32_e32 v64, v64
	s_or_b32 s4, s5, 3
	s_lshl_b32 s92, s4, 7
	v_fma_f32 v65, v66, v65, -v156
	v_fma_f32 v64, v64, v67, -v156
	v_mul_f32_e32 v65, v157, v65
	v_mul_f32_e32 v64, v157, v64
	v_fma_f32 v65, v65, v70, v78
	v_fmac_f32_e32 v79, v64, v71
	v_cvt_pk_bf16_f32 v64, v65, v145
	ds_write_b16 v172, v64 offset:22240
	v_cvt_pk_bf16_f32 v64, v79, v145
	ds_write_b16 v172, v64 offset:22512
	s_waitcnt lgkmcnt(0)
	s_barrier
	ds_read_b128 v[64:67], v170 offset:18432
	ds_read_b128 v[68:71], v170 offset:18496
	ds_read_b128 v[76:79], v170 offset:22784
	ds_read_b128 v[88:91], v170 offset:22848
	ds_read_b128 v[92:95], v170 offset:27136
	ds_read_b128 v[104:107], v170 offset:27200
	ds_read_b128 v[112:115], v170 offset:31488
	ds_read_b128 v[116:119], v170 offset:31552
	s_waitcnt lgkmcnt(7)
	v_mfma_f32_16x16x32_bf16 v[64:67], v[52:55], v[64:67], 0
	s_waitcnt lgkmcnt(5)
	v_mfma_f32_16x16x32_bf16 v[76:79], v[52:55], v[76:79], 0
	s_waitcnt lgkmcnt(3)
	v_mfma_f32_16x16x32_bf16 v[92:95], v[52:55], v[92:95], 0
	s_waitcnt lgkmcnt(1)
	v_mfma_f32_16x16x32_bf16 v[52:55], v[52:55], v[112:115], 0
	v_mfma_f32_16x16x32_bf16 v[64:67], v[48:51], v[68:71], v[64:67]
	v_mfma_f32_16x16x32_bf16 v[68:71], v[48:51], v[88:91], v[76:79]
	v_mfma_f32_16x16x32_bf16 v[76:79], v[48:51], v[104:107], v[92:95]
	s_waitcnt lgkmcnt(0)
	v_mfma_f32_16x16x32_bf16 v[48:51], v[48:51], v[116:119], v[52:55]
	s_nop 2
	ds_read_b128 v[52:55], v170 offset:18560
	ds_read_b128 v[88:91], v170 offset:18624
	s_waitcnt lgkmcnt(1)
	v_mfma_f32_16x16x32_bf16 v[52:55], v[36:39], v[52:55], v[64:67]
	s_nop 2
	ds_read_b128 v[64:67], v170 offset:22912
	ds_read_b128 v[92:95], v170 offset:22976
	s_waitcnt lgkmcnt(1)
	v_mfma_f32_16x16x32_bf16 v[64:67], v[36:39], v[64:67], v[68:71]
	s_nop 2
	ds_read_b128 v[68:71], v170 offset:27264
	ds_read_b128 v[104:107], v170 offset:27328
	s_waitcnt lgkmcnt(1)
	v_mfma_f32_16x16x32_bf16 v[68:71], v[36:39], v[68:71], v[76:79]
	s_nop 2
	ds_read_b128 v[76:79], v170 offset:31616
	ds_read_b128 v[112:115], v170 offset:31680
	s_waitcnt lgkmcnt(1)
	v_mfma_f32_16x16x32_bf16 v[36:39], v[36:39], v[76:79], v[48:51]
	v_mfma_f32_16x16x32_bf16 v[48:51], v[32:35], v[88:91], v[52:55]
	v_mfma_f32_16x16x32_bf16 v[52:55], v[32:35], v[92:95], v[64:67]
	v_mfma_f32_16x16x32_bf16 v[64:67], v[32:35], v[104:107], v[68:71]
	s_waitcnt lgkmcnt(0)
	v_mfma_f32_16x16x32_bf16 v[32:35], v[32:35], v[112:115], v[36:39]
	s_nop 4
	ds_write2_b32 v159, v48, v52 offset1:16
	s_nop 1
	ds_write2_b32 v159, v64, v32 offset0:32 offset1:48
	ds_write2_b32 v159, v49, v53 offset0:68 offset1:84
	ds_write2_b32 v159, v65, v33 offset0:100 offset1:116
	ds_write2_b32 v159, v50, v54 offset0:136 offset1:152
	ds_write2_b32 v159, v66, v34 offset0:168 offset1:184
	ds_write2_b32 v159, v51, v55 offset0:204 offset1:220
	ds_write2_b32 v159, v67, v35 offset0:236 offset1:252
	v_lshlrev_b32_e32 v37, 16, v20
	v_mul_f32_e32 v38, v37, v37
	v_fmamk_f32 v38, v38, 0xbdd2d3e8, v245
	v_mov_b32_e32 v39, v37
	v_mul_f32_e32 v38, v38, v39
	v_lshlrev_b32_e32 v36, 16, v16
	v_exp_f32_e32 v38, v38
	v_mul_f32_e32 v39, 0xbfb8aa3b, v36
	v_exp_f32_e32 v48, v39
	v_and_b32_e32 v49, 0xffff0000, v20
	v_add_f32_e32 v38, 1.0, v38
	v_rcp_f32_e32 v39, v38
	v_add_f32_e32 v38, 1.0, v48
	v_and_b32_e32 v48, 0xffff0000, v16
	v_mul_f32_e32 v16, v49, v49
	v_fmamk_f32 v16, v16, 0xbdd2d3e8, v245
	v_mov_b32_e32 v20, v49
	v_mul_f32_e32 v16, v16, v20
	v_exp_f32_e32 v16, v16
	v_mul_f32_e32 v20, 0xbfb8aa3b, v48
	v_rcp_f32_e32 v38, v38
	v_exp_f32_e32 v20, v20
	s_waitcnt lgkmcnt(0)
	s_barrier
	ds_read_b128 v[32:35], v158 offset:35840
	v_add_f32_e32 v16, 1.0, v16
	v_pk_mul_f32 v[36:37], v[38:39], v[36:37]
	v_rcp_f32_e32 v39, v16
	v_add_f32_e32 v16, 1.0, v20
	v_rcp_f32_e32 v38, v16
	s_waitcnt lgkmcnt(0)
	v_add_f32_e32 v32, v174, v32
	v_mul_f32_e32 v16, v37, v32
	v_add_f32_e32 v20, v174, v33
	v_pk_mul_f32 v[32:33], v[38:39], v[48:49]
	v_mul_f32_e32 v16, v36, v16
	v_mul_f32_e32 v20, v33, v20
	v_mul_f32_e32 v20, v32, v20
	v_lshlrev_b32_e32 v33, 16, v21
	v_cvt_pk_bf16_f32 v16, v16, v20
	v_mul_f32_e32 v20, v33, v33
	v_fmamk_f32 v20, v20, 0xbdd2d3e8, v245
	v_mov_b32_e32 v36, v33
	v_mul_f32_e32 v20, v20, v36
	v_lshlrev_b32_e32 v32, 16, v17
	v_exp_f32_e32 v20, v20
	v_mul_f32_e32 v36, 0xbfb8aa3b, v32
	v_exp_f32_e32 v36, v36
	v_and_b32_e32 v21, 0xffff0000, v21
	v_add_f32_e32 v20, 1.0, v20
	v_rcp_f32_e32 v37, v20
	v_add_f32_e32 v20, 1.0, v36
	v_rcp_f32_e32 v36, v20
	v_and_b32_e32 v20, 0xffff0000, v17
	v_mul_f32_e32 v17, v21, v21
	v_fmamk_f32 v17, v17, 0xbdd2d3e8, v245
	v_mov_b32_e32 v38, v21
	v_mul_f32_e32 v17, v17, v38
	v_exp_f32_e32 v17, v17
	v_mul_f32_e32 v38, 0xbfb8aa3b, v20
	v_exp_f32_e32 v38, v38
	v_pk_mul_f32 v[32:33], v[36:37], v[32:33]
	v_add_f32_e32 v17, 1.0, v17
	v_rcp_f32_e32 v37, v17
	v_add_f32_e32 v17, 1.0, v38
	v_rcp_f32_e32 v36, v17
	v_add_f32_e32 v34, v174, v34
	v_mul_f32_e32 v17, v33, v34
	v_mul_f32_e32 v17, v32, v17
	v_add_f32_e32 v32, v174, v35
	v_pk_mul_f32 v[20:21], v[36:37], v[20:21]
	v_and_b32_e32 v39, 0xffff0000, v22
	v_mul_f32_e32 v21, v21, v32
	v_mul_f32_e32 v20, v20, v21
	v_lshlrev_b32_e32 v21, 16, v22
	v_mul_f32_e32 v36, v21, v21
	v_fmamk_f32 v36, v36, 0xbdd2d3e8, v245
	v_mov_b32_e32 v37, v21
	v_mul_f32_e32 v36, v36, v37
	v_cvt_pk_bf16_f32 v17, v17, v20
	v_lshlrev_b32_e32 v20, 16, v18
	v_exp_f32_e32 v36, v36
	v_mul_f32_e32 v37, 0xbfb8aa3b, v20
	v_exp_f32_e32 v38, v37
	v_mov_b32_e32 v22, v39
	v_add_f32_e32 v36, 1.0, v36
	v_rcp_f32_e32 v37, v36
	v_add_f32_e32 v36, 1.0, v38
	v_and_b32_e32 v38, 0xffff0000, v18
	v_mul_f32_e32 v18, 0x3d372713, v39
	v_mul_f32_e32 v18, v18, v39
	v_fmac_f32_e32 v22, v18, v22
	v_mul_f32_e32 v18, 0x3fcc422a, v22
	v_mul_f32_e32 v18, 0xbfb8aa3b, v18
	v_exp_f32_e32 v18, v18
	v_mul_f32_e32 v22, 0xbfb8aa3b, v38
	v_rcp_f32_e32 v36, v36
	v_exp_f32_e32 v22, v22
	ds_read_b128 v[32:35], v158 offset:35856
	v_add_f32_e32 v18, 1.0, v18
	v_pk_mul_f32 v[20:21], v[36:37], v[20:21]
	v_rcp_f32_e32 v37, v18
	v_add_f32_e32 v18, 1.0, v22
	v_rcp_f32_e32 v36, v18
	s_waitcnt lgkmcnt(0)
	v_add_f32_e32 v32, v174, v32
	v_mul_f32_e32 v18, v21, v32
	v_mul_f32_e32 v18, v20, v18
	v_add_f32_e32 v22, v174, v33
	v_pk_mul_f32 v[20:21], v[36:37], v[38:39]
	v_add_f32_e32 v34, v174, v34
	v_mul_f32_e32 v21, v21, v22
	v_mul_f32_e32 v20, v20, v21
	v_lshlrev_b32_e32 v21, 16, v23
	v_mul_f32_e32 v22, v21, v21
	v_fmamk_f32 v22, v22, 0xbdd2d3e8, v245
	v_mov_b32_e32 v32, v21
	v_mul_f32_e32 v22, v22, v32
	v_cvt_pk_bf16_f32 v18, v18, v20
	v_lshlrev_b32_e32 v20, 16, v19
	v_exp_f32_e32 v22, v22
	v_mul_f32_e32 v32, 0xbfb8aa3b, v20
	v_exp_f32_e32 v32, v32
	v_and_b32_e32 v23, 0xffff0000, v23
	v_add_f32_e32 v22, 1.0, v22
	v_rcp_f32_e32 v33, v22
	v_add_f32_e32 v22, 1.0, v32
	v_rcp_f32_e32 v32, v22
	v_and_b32_e32 v22, 0xffff0000, v19
	v_mul_f32_e32 v19, v23, v23
	v_fmamk_f32 v19, v19, 0xbdd2d3e8, v245
	v_mov_b32_e32 v36, v23
	v_mul_f32_e32 v19, v19, v36
	v_exp_f32_e32 v19, v19
	v_mul_f32_e32 v36, 0xbfb8aa3b, v22
	v_exp_f32_e32 v36, v36
	v_pk_mul_f32 v[20:21], v[32:33], v[20:21]
	v_add_f32_e32 v19, 1.0, v19
	v_rcp_f32_e32 v33, v19
	v_add_f32_e32 v19, 1.0, v36
	v_rcp_f32_e32 v32, v19
	v_mul_f32_e32 v19, v21, v34
	v_mul_f32_e32 v19, v20, v19
	v_add_f32_e32 v34, v174, v35
	v_pk_mul_f32 v[20:21], v[32:33], v[22:23]
	v_lshlrev_b32_e32 v33, 16, v0
	v_mul_f32_e32 v21, v21, v34
	v_mul_f32_e32 v34, v33, v33
	v_fmamk_f32 v34, v34, 0xbdd2d3e8, v245
	v_mov_b32_e32 v35, v33
	v_mul_f32_e32 v34, v34, v35
	v_lshlrev_b32_e32 v32, 16, v4
	v_exp_f32_e32 v34, v34
	v_mul_f32_e32 v35, 0xbfb8aa3b, v32
	v_exp_f32_e32 v36, v35
	v_and_b32_e32 v37, 0xffff0000, v0
	v_add_f32_e32 v34, 1.0, v34
	v_mul_f32_e32 v0, v37, v37
	v_rcp_f32_e32 v35, v34
	v_add_f32_e32 v34, 1.0, v36
	v_and_b32_e32 v36, 0xffff0000, v4
	v_fmamk_f32 v0, v0, 0xbdd2d3e8, v245
	v_mov_b32_e32 v4, v37
	v_mul_f32_e32 v0, v0, v4
	v_exp_f32_e32 v0, v0
	v_mul_f32_e32 v4, 0xbfb8aa3b, v36
	v_rcp_f32_e32 v34, v34
	v_exp_f32_e32 v4, v4
	v_mul_f32_e32 v20, v20, v21
	v_cvt_pk_bf16_f32 v19, v19, v20
	ds_read_b128 v[20:23], v158 offset:35872
	v_add_f32_e32 v0, 1.0, v0
	v_pk_mul_f32 v[32:33], v[34:35], v[32:33]
	v_rcp_f32_e32 v35, v0
	v_add_f32_e32 v0, 1.0, v4
	v_rcp_f32_e32 v34, v0
	s_waitcnt lgkmcnt(0)
	v_add_f32_e32 v20, v174, v20
	v_mul_f32_e32 v0, v33, v20
	v_add_f32_e32 v4, v174, v21
	v_pk_mul_f32 v[20:21], v[34:35], v[36:37]
	v_mul_f32_e32 v0, v32, v0
	v_mul_f32_e32 v4, v21, v4
	v_mul_f32_e32 v4, v20, v4
	v_lshlrev_b32_e32 v21, 16, v1
	v_cvt_pk_bf16_f32 v0, v0, v4
	v_mul_f32_e32 v4, v21, v21
	v_fmamk_f32 v4, v4, 0xbdd2d3e8, v245
	v_mov_b32_e32 v32, v21
	v_mul_f32_e32 v4, v4, v32
	v_lshlrev_b32_e32 v20, 16, v5
	v_exp_f32_e32 v4, v4
	v_mul_f32_e32 v32, 0xbfb8aa3b, v20
	v_exp_f32_e32 v32, v32
	v_and_b32_e32 v35, 0xffff0000, v1
	v_add_f32_e32 v4, 1.0, v4
	v_rcp_f32_e32 v33, v4
	v_add_f32_e32 v4, 1.0, v32
	v_mul_f32_e32 v1, v35, v35
	v_rcp_f32_e32 v32, v4
	v_fmamk_f32 v1, v1, 0xbdd2d3e8, v245
	v_mov_b32_e32 v4, v35
	v_mul_f32_e32 v1, v1, v4
	v_and_b32_e32 v34, 0xffff0000, v5
	v_exp_f32_e32 v1, v1
	v_mul_f32_e32 v4, 0xbfb8aa3b, v34
	v_exp_f32_e32 v36, v4
	v_pk_mul_f32 v[4:5], v[32:33], v[20:21]
	v_add_f32_e32 v1, 1.0, v1
	v_rcp_f32_e32 v21, v1
	v_add_f32_e32 v1, 1.0, v36
	v_rcp_f32_e32 v20, v1
	v_add_f32_e32 v22, v174, v22
	v_mul_f32_e32 v1, v5, v22
	v_mul_f32_e32 v1, v4, v1
	v_add_f32_e32 v22, v174, v23
	v_pk_mul_f32 v[4:5], v[20:21], v[34:35]
	v_and_b32_e32 v35, 0xffff0000, v2
	v_mul_f32_e32 v5, v5, v22
	v_mul_f32_e32 v4, v4, v5
	v_lshlrev_b32_e32 v5, 16, v2
	v_mul_f32_e32 v32, v5, v5
	v_fmamk_f32 v32, v32, 0xbdd2d3e8, v245
	v_mov_b32_e32 v33, v5
	v_mul_f32_e32 v32, v32, v33
	v_cvt_pk_bf16_f32 v1, v1, v4
	v_lshlrev_b32_e32 v4, 16, v6
	v_exp_f32_e32 v32, v32
	v_mul_f32_e32 v33, 0xbfb8aa3b, v4
	v_exp_f32_e32 v34, v33
	v_mul_f32_e32 v2, v35, v35
	v_add_f32_e32 v32, 1.0, v32
	v_rcp_f32_e32 v33, v32
	v_add_f32_e32 v32, 1.0, v34
	v_and_b32_e32 v34, 0xffff0000, v6
	v_fmamk_f32 v2, v2, 0xbdd2d3e8, v245
	v_mov_b32_e32 v6, v35
	v_mul_f32_e32 v2, v2, v6
	v_exp_f32_e32 v2, v2
	v_mul_f32_e32 v6, 0xbfb8aa3b, v34
	v_rcp_f32_e32 v32, v32
	v_exp_f32_e32 v6, v6
	ds_read_b128 v[20:23], v158 offset:35888
	v_add_f32_e32 v2, 1.0, v2
	v_pk_mul_f32 v[4:5], v[32:33], v[4:5]
	v_rcp_f32_e32 v33, v2
	v_add_f32_e32 v2, 1.0, v6
	v_rcp_f32_e32 v32, v2
	s_waitcnt lgkmcnt(0)
	v_add_f32_e32 v20, v174, v20
	v_mul_f32_e32 v2, v5, v20
	v_mul_f32_e32 v2, v4, v2
	v_add_f32_e32 v6, v174, v21
	v_pk_mul_f32 v[4:5], v[32:33], v[34:35]
	v_and_b32_e32 v33, 0xffff0000, v3
	v_mul_f32_e32 v5, v5, v6
	v_mul_f32_e32 v4, v4, v5
	v_lshlrev_b32_e32 v5, 16, v3
	v_mul_f32_e32 v6, v5, v5
	v_fmamk_f32 v6, v6, 0xbdd2d3e8, v245
	v_mov_b32_e32 v20, v5
	v_mul_f32_e32 v6, v6, v20
	v_cvt_pk_bf16_f32 v2, v2, v4
	v_lshlrev_b32_e32 v4, 16, v7
	v_exp_f32_e32 v6, v6
	v_mul_f32_e32 v20, 0xbfb8aa3b, v4
	v_exp_f32_e32 v20, v20
	v_mul_f32_e32 v3, v33, v33
	v_add_f32_e32 v6, 1.0, v6
	v_rcp_f32_e32 v21, v6
	v_add_f32_e32 v6, 1.0, v20
	v_rcp_f32_e32 v20, v6
	v_fmamk_f32 v3, v3, 0xbdd2d3e8, v245
	v_mov_b32_e32 v6, v33
	v_mul_f32_e32 v3, v3, v6
	v_and_b32_e32 v32, 0xffff0000, v7
	v_exp_f32_e32 v3, v3
	v_mul_f32_e32 v6, 0xbfb8aa3b, v32
	v_exp_f32_e32 v6, v6
	v_add_f32_e32 v22, v174, v22
	v_add_f32_e32 v3, 1.0, v3
	v_rcp_f32_e32 v7, v3
	v_add_f32_e32 v3, 1.0, v6
	v_rcp_f32_e32 v6, v3
	v_pk_mul_f32 v[4:5], v[20:21], v[4:5]
	v_add_f32_e32 v20, v174, v23
	v_mul_f32_e32 v3, v5, v22
	v_mul_f32_e32 v3, v4, v3
	v_pk_mul_f32 v[4:5], v[6:7], v[32:33]
	v_lshl_or_b32 v70, s4, 6, v173
	v_mul_f32_e32 v5, v5, v20
	v_lshlrev_b32_e32 v144, 1, v70
	v_mul_f32_e32 v4, v4, v5
	v_cvt_pk_bf16_f32 v3, v3, v4
	global_store_dwordx4 v[160:161], v[16:19], off offset:128
	global_store_dwordx4 v[160:161], v[0:3], off offset:144
	s_or_b32 s4, s4, s53
	v_lshlrev_b32_e32 v132, 2, v70
	v_lshl_add_u64 v[0:1], v[162:163], 0, v[144:145]
	s_waitcnt vmcnt(20)
	v_lshlrev_b32_e32 v162, 16, v108
	v_mul_f32_e32 v76, v162, v162
	v_fmamk_f32 v76, v76, 0xbdd2d3e8, v245
	v_mul_f32_e32 v76, v76, v162
	v_and_b32_e32 v108, 0xffff0000, v108
	v_mul_f32_e32 v117, v108, v108
	v_fmamk_f32 v117, v117, 0xbdd2d3e8, v245
	v_add_co_u32_e32 v4, vcc, s3, v0
	v_exp_f32_e32 v116, v76
	v_mul_f32_e32 v117, v117, v108
	v_addc_co_u32_e32 v5, vcc, 0, v1, vcc
	v_lshl_add_u64 v[2:3], v[0:1], 0, s[14:15]
	v_add_co_u32_e32 v6, vcc, s74, v0
	global_load_dwordx4 v[104:107], v[4:5], off
	global_load_dwordx4 v[64:67], v[2:3], off offset:16
	v_lshl_add_u64 v[2:3], v[0:1], 0, s[16:17]
	v_addc_co_u32_e32 v7, vcc, 0, v1, vcc
	v_lshl_add_u64 v[32:33], v[0:1], 0, s[8:9]
	v_exp_f32_e32 v163, v117
	global_load_dwordx4 v[0:3], v[2:3], off offset:16
	s_nop 0
	global_load_dwordx4 v[16:19], v[4:5], off offset:1024
	global_load_dwordx4 v[20:23], v[6:7], off offset:3072
	s_nop 0
	global_load_dwordx4 v[4:7], v[32:33], off offset:16
	v_lshl_add_u64 v[32:33], v[166:167], 0, s[92:93]
	s_lshl_b32 s92, s4, 7
	v_add_f32_e32 v116, 1.0, v116
	v_lshl_add_u64 v[68:69], s[92:93], 2, v[164:165]
	v_rcp_f32_e32 v164, v116
	v_add_f32_e32 v163, 1.0, v163
	v_rcp_f32_e32 v163, v163
	v_lshlrev_b64 v[32:33], 8, v[32:33]
	v_fma_f32 v162, v164, v162, -v156
	v_mul_f32_e32 v162, v157, v162
	v_lshl_add_u64 v[32:33], v[168:169], 0, v[32:33]
	s_waitcnt vmcnt(8)
	v_fma_f32 v136, v136, v162, v140
	global_load_dwordx4 v[52:55], v[32:33], off
	global_load_dwordx4 v[48:51], v[32:33], off offset:64
	global_load_dwordx4 v[36:39], v[32:33], off offset:128
	s_nop 0
	global_load_dwordx4 v[32:35], v[32:33], off offset:192
	v_fma_f32 v108, v163, v108, -v156
	global_load_dword v144, v[68:69], off
	s_nop 0
	global_load_dwordx4 v[68:71], v132, s[0:1] offset:48
	global_load_dwordx4 v[88:91], v132, s[0:1] offset:32
	global_load_dwordx4 v[112:115], v132, s[0:1] offset:16
	global_load_dwordx4 v[128:131], v132, s[0:1]
	global_load_dwordx4 v[76:79], v132, s[72:73] offset:48
	global_load_dwordx4 v[92:95], v132, s[72:73] offset:32
	global_load_dwordx4 v[116:119], v132, s[72:73] offset:16
	s_nop 0
	global_load_dwordx4 v[132:135], v132, s[72:73]
	v_cvt_pk_bf16_f32 v136, v136, v145
	v_mul_f32_e32 v108, v157, v108
	ds_write_b16 v171, v136 offset:1024
	v_lshlrev_b32_e32 v136, 16, v109
	v_fma_f32 v108, v137, v108, v141
	v_mul_f32_e32 v137, v136, v136
	v_and_b32_e32 v109, 0xffff0000, v109
	v_fmamk_f32 v137, v137, 0xbdd2d3e8, v245
	v_mul_f32_e32 v140, v109, v109
	v_mul_f32_e32 v137, v137, v136
	v_fmamk_f32 v140, v140, 0xbdd2d3e8, v245
	v_mul_f32_e32 v140, v140, v109
	v_exp_f32_e32 v137, v137
	v_exp_f32_e32 v140, v140
	v_cvt_pk_bf16_f32 v108, v108, v145
	v_add_f32_e32 v137, 1.0, v137
	v_rcp_f32_e32 v137, v137
	ds_write_b16 v171, v108 offset:1296
	v_add_f32_e32 v108, 1.0, v140
	v_rcp_f32_e32 v108, v108
	v_fma_f32 v136, v137, v136, -v156
	v_mul_f32_e32 v136, v157, v136
	v_fma_f32 v136, v138, v136, v142
	v_fma_f32 v108, v108, v109, -v156
	v_mul_f32_e32 v108, v157, v108
	v_lshlrev_b32_e32 v109, 16, v110
	v_fmac_f32_e32 v143, v139, v108
	v_cvt_pk_bf16_f32 v108, v136, v145
	v_mul_f32_e32 v136, v109, v109
	v_fmamk_f32 v136, v136, 0xbdd2d3e8, v245
	v_mul_f32_e32 v136, v136, v109
	v_and_b32_e32 v110, 0xffff0000, v110
	v_exp_f32_e32 v136, v136
	v_mul_f32_e32 v137, v110, v110
	v_fmamk_f32 v137, v137, 0xbdd2d3e8, v245
	v_mul_f32_e32 v137, v137, v110
	v_add_f32_e32 v136, 1.0, v136
	v_exp_f32_e32 v137, v137
	v_rcp_f32_e32 v136, v136
	ds_write_b16 v171, v108 offset:1568
	v_cvt_pk_bf16_f32 v108, v143, v145
	ds_write_b16 v171, v108 offset:1840
	v_add_f32_e32 v108, 1.0, v137
	v_fma_f32 v109, v136, v109, -v156
	v_rcp_f32_e32 v108, v108
	v_mul_f32_e32 v109, v157, v109
	v_fma_f32 v109, v120, v109, v124
	v_cvt_pk_bf16_f32 v109, v109, v145
	ds_write_b16 v171, v109 offset:2112
	v_lshlrev_b32_e32 v109, 16, v111
	v_fma_f32 v108, v108, v110, -v156
	v_mul_f32_e32 v110, v109, v109
	v_and_b32_e32 v111, 0xffff0000, v111
	v_fmamk_f32 v110, v110, 0xbdd2d3e8, v245
	v_mul_f32_e32 v120, v111, v111
	v_mul_f32_e32 v110, v110, v109
	v_fmamk_f32 v120, v120, 0xbdd2d3e8, v245
	v_mul_f32_e32 v120, v120, v111
	v_exp_f32_e32 v110, v110
	v_exp_f32_e32 v120, v120
	v_mul_f32_e32 v108, v157, v108
	v_fma_f32 v108, v121, v108, v125
	v_cvt_pk_bf16_f32 v108, v108, v145
	v_add_f32_e32 v110, 1.0, v110
	v_rcp_f32_e32 v110, v110
	ds_write_b16 v171, v108 offset:2384
	v_add_f32_e32 v108, 1.0, v120
	v_rcp_f32_e32 v108, v108
	v_fma_f32 v109, v110, v109, -v156
	v_mul_f32_e32 v109, v157, v109
	v_fma_f32 v109, v122, v109, v126
	v_fma_f32 v108, v108, v111, -v156
	v_mul_f32_e32 v108, v157, v108
	v_fmac_f32_e32 v127, v123, v108
	v_cvt_pk_bf16_f32 v108, v109, v145
	v_lshlrev_b32_e32 v109, 16, v72
	v_mul_f32_e32 v110, v109, v109
	v_fmamk_f32 v110, v110, 0xbdd2d3e8, v245
	v_mul_f32_e32 v110, v110, v109
	v_and_b32_e32 v72, 0xffff0000, v72
	v_mul_f32_e32 v111, v72, v72
	v_fmamk_f32 v111, v111, 0xbdd2d3e8, v245
	v_exp_f32_e32 v110, v110
	v_mul_f32_e32 v111, v111, v72
	v_exp_f32_e32 v111, v111
	v_add_f32_e32 v110, 1.0, v110
	v_rcp_f32_e32 v110, v110
	ds_write_b16 v171, v108 offset:2656
	v_cvt_pk_bf16_f32 v108, v127, v145
	ds_write_b16 v171, v108 offset:2928
	v_add_f32_e32 v108, 1.0, v111
	v_rcp_f32_e32 v108, v108
	v_fma_f32 v109, v110, v109, -v156
	v_mul_f32_e32 v109, v157, v109
	v_fma_f32 v96, v109, v96, v100
	v_fma_f32 v72, v108, v72, -v156
	v_cvt_pk_bf16_f32 v96, v96, v145
	v_mul_f32_e32 v72, v157, v72
	ds_write_b16 v171, v96 offset:3200
	v_lshlrev_b32_e32 v96, 16, v73
	v_fma_f32 v72, v72, v97, v101
	v_mul_f32_e32 v97, v96, v96
	v_and_b32_e32 v73, 0xffff0000, v73
	v_fmamk_f32 v97, v97, 0xbdd2d3e8, v245
	v_mul_f32_e32 v100, v73, v73
	v_mul_f32_e32 v97, v97, v96
	v_fmamk_f32 v100, v100, 0xbdd2d3e8, v245
	v_mul_f32_e32 v100, v100, v73
	v_exp_f32_e32 v97, v97
	v_exp_f32_e32 v100, v100
	v_cvt_pk_bf16_f32 v72, v72, v145
	v_add_f32_e32 v97, 1.0, v97
	v_rcp_f32_e32 v97, v97
	ds_write_b16 v171, v72 offset:3472
	v_add_f32_e32 v72, 1.0, v100
	v_rcp_f32_e32 v72, v72
	v_fma_f32 v96, v97, v96, -v156
	v_mul_f32_e32 v96, v157, v96
	v_fma_f32 v96, v96, v98, v102
	v_fma_f32 v72, v72, v73, -v156
	v_mul_f32_e32 v72, v157, v72
	v_lshlrev_b32_e32 v73, 16, v74
	v_fmac_f32_e32 v103, v72, v99
	v_cvt_pk_bf16_f32 v72, v96, v145
	v_mul_f32_e32 v96, v73, v73
	v_fmamk_f32 v96, v96, 0xbdd2d3e8, v245
	v_mul_f32_e32 v96, v96, v73
	v_and_b32_e32 v74, 0xffff0000, v74
	v_exp_f32_e32 v96, v96
	v_mul_f32_e32 v97, v74, v74
	v_fmamk_f32 v97, v97, 0xbdd2d3e8, v245
	v_mul_f32_e32 v97, v97, v74
	v_add_f32_e32 v96, 1.0, v96
	v_exp_f32_e32 v97, v97
	v_rcp_f32_e32 v96, v96
	ds_write_b16 v171, v72 offset:3744
	v_cvt_pk_bf16_f32 v72, v103, v145
	ds_write_b16 v171, v72 offset:4016
	v_add_f32_e32 v72, 1.0, v97
	v_fma_f32 v73, v96, v73, -v156
	v_rcp_f32_e32 v72, v72
	v_mul_f32_e32 v73, v157, v73
	v_fma_f32 v73, v73, v80, v84
	v_cvt_pk_bf16_f32 v73, v73, v145
	ds_write_b16 v171, v73 offset:4288
	v_lshlrev_b32_e32 v73, 16, v75
	v_and_b32_e32 v75, 0xffff0000, v75
	v_fma_f32 v72, v72, v74, -v156
	v_mul_f32_e32 v74, v73, v73
	v_mul_f32_e32 v80, v75, v75
	v_fmamk_f32 v74, v74, 0xbdd2d3e8, v245
	v_fmamk_f32 v80, v80, 0xbdd2d3e8, v245
	v_mul_f32_e32 v74, v74, v73
	v_mul_f32_e32 v80, v80, v75
	v_exp_f32_e32 v74, v74
	v_exp_f32_e32 v80, v80
	v_mul_f32_e32 v72, v157, v72
	v_fma_f32 v72, v72, v81, v85
	v_cvt_pk_bf16_f32 v72, v72, v145
	v_add_f32_e32 v74, 1.0, v74
	ds_write_b16 v171, v72 offset:4560
	v_add_f32_e32 v72, 1.0, v80
	v_rcp_f32_e32 v74, v74
	v_rcp_f32_e32 v72, v72
	v_fma_f32 v73, v74, v73, -v156
	v_fma_f32 v72, v72, v75, -v156
	v_mul_f32_e32 v73, v157, v73
	v_mul_f32_e32 v72, v157, v72
	v_fma_f32 v73, v73, v82, v86
	v_fmac_f32_e32 v87, v72, v83
	v_cvt_pk_bf16_f32 v72, v73, v145
	ds_write_b16 v171, v72 offset:4832
	v_cvt_pk_bf16_f32 v72, v87, v145
	ds_write_b16 v171, v72 offset:5104
	s_waitcnt lgkmcnt(0)
	s_barrier
	ds_read_b128 v[72:75], v170 offset:1024
	ds_read_b128 v[80:83], v170 offset:1088
	ds_read_b128 v[84:87], v170 offset:5376
	ds_read_b128 v[96:99], v170 offset:5440
	ds_read_b128 v[100:103], v170 offset:9728
	ds_read_b128 v[108:111], v170 offset:9792
	ds_read_b128 v[120:123], v170 offset:14080
	ds_read_b128 v[124:127], v170 offset:14144
	s_waitcnt lgkmcnt(7)
	v_mfma_f32_16x16x32_bf16 v[72:75], v[60:63], v[72:75], 0
	s_waitcnt lgkmcnt(5)
	v_mfma_f32_16x16x32_bf16 v[84:87], v[60:63], v[84:87], 0
	s_waitcnt lgkmcnt(3)
	v_mfma_f32_16x16x32_bf16 v[100:103], v[60:63], v[100:103], 0
	s_waitcnt lgkmcnt(1)
	v_mfma_f32_16x16x32_bf16 v[60:63], v[60:63], v[120:123], 0
	v_mfma_f32_16x16x32_bf16 v[72:75], v[56:59], v[80:83], v[72:75]
	v_mfma_f32_16x16x32_bf16 v[80:83], v[56:59], v[96:99], v[84:87]
	v_mfma_f32_16x16x32_bf16 v[84:87], v[56:59], v[108:111], v[100:103]
	s_waitcnt lgkmcnt(0)
	v_mfma_f32_16x16x32_bf16 v[56:59], v[56:59], v[124:127], v[60:63]
	s_nop 2
	ds_read_b128 v[60:63], v170 offset:1152
	ds_read_b128 v[96:99], v170 offset:1216
	s_waitcnt lgkmcnt(1)
	v_mfma_f32_16x16x32_bf16 v[60:63], v[44:47], v[60:63], v[72:75]
	s_nop 2
	ds_read_b128 v[72:75], v170 offset:5504
	ds_read_b128 v[100:103], v170 offset:5568
	s_waitcnt lgkmcnt(1)
	v_mfma_f32_16x16x32_bf16 v[72:75], v[44:47], v[72:75], v[80:83]
	s_nop 2
	ds_read_b128 v[80:83], v170 offset:9856
	ds_read_b128 v[108:111], v170 offset:9920
	s_waitcnt lgkmcnt(1)
	v_mfma_f32_16x16x32_bf16 v[80:83], v[44:47], v[80:83], v[84:87]
	s_nop 2
	ds_read_b128 v[84:87], v170 offset:14208
	ds_read_b128 v[120:123], v170 offset:14272
	s_waitcnt lgkmcnt(1)
	v_mfma_f32_16x16x32_bf16 v[44:47], v[44:47], v[84:87], v[56:59]
	v_mfma_f32_16x16x32_bf16 v[56:59], v[40:43], v[96:99], v[60:63]
	v_mfma_f32_16x16x32_bf16 v[60:63], v[40:43], v[100:103], v[72:75]
	v_mfma_f32_16x16x32_bf16 v[72:75], v[40:43], v[108:111], v[80:83]
	s_waitcnt lgkmcnt(0)
	v_mfma_f32_16x16x32_bf16 v[40:43], v[40:43], v[120:123], v[44:47]
	s_nop 4
	ds_write2_b32 v159, v56, v60 offset1:16
	s_nop 1
	ds_write2_b32 v159, v72, v40 offset0:32 offset1:48
	ds_write2_b32 v159, v57, v61 offset0:68 offset1:84
	ds_write2_b32 v159, v73, v41 offset0:100 offset1:116
	ds_write2_b32 v159, v58, v62 offset0:136 offset1:152
	ds_write2_b32 v159, v74, v42 offset0:168 offset1:184
	ds_write2_b32 v159, v59, v63 offset0:204 offset1:220
	ds_write2_b32 v159, v75, v43 offset0:236 offset1:252
	v_lshlrev_b32_e32 v45, 16, v28
	v_mul_f32_e32 v46, v45, v45
	v_fmamk_f32 v46, v46, 0xbdd2d3e8, v245
	v_mov_b32_e32 v47, v45
	v_mul_f32_e32 v46, v46, v47
	v_lshlrev_b32_e32 v44, 16, v24
	v_exp_f32_e32 v46, v46
	v_mul_f32_e32 v47, 0xbfb8aa3b, v44
	v_exp_f32_e32 v56, v47
	v_and_b32_e32 v57, 0xffff0000, v28
	v_add_f32_e32 v46, 1.0, v46
	v_rcp_f32_e32 v47, v46
	v_add_f32_e32 v46, 1.0, v56
	v_and_b32_e32 v56, 0xffff0000, v24
	v_mul_f32_e32 v24, v57, v57
	v_fmamk_f32 v24, v24, 0xbdd2d3e8, v245
	v_mov_b32_e32 v28, v57
	v_mul_f32_e32 v24, v24, v28
	v_exp_f32_e32 v24, v24
	v_mul_f32_e32 v28, 0xbfb8aa3b, v56
	v_rcp_f32_e32 v46, v46
	v_exp_f32_e32 v28, v28
	s_waitcnt lgkmcnt(0)
	s_barrier
	ds_read_b128 v[40:43], v158 offset:35840
	v_add_f32_e32 v24, 1.0, v24
	v_pk_mul_f32 v[44:45], v[46:47], v[44:45]
	v_rcp_f32_e32 v47, v24
	v_add_f32_e32 v24, 1.0, v28
	v_rcp_f32_e32 v46, v24
	s_waitcnt lgkmcnt(0)
	v_add_f32_e32 v40, v188, v40
	v_mul_f32_e32 v24, v45, v40
	v_add_f32_e32 v28, v188, v41
	v_pk_mul_f32 v[40:41], v[46:47], v[56:57]
	v_mul_f32_e32 v24, v44, v24
	v_mul_f32_e32 v28, v41, v28
	v_mul_f32_e32 v28, v40, v28
	v_lshlrev_b32_e32 v41, 16, v29
	v_cvt_pk_bf16_f32 v24, v24, v28
	v_mul_f32_e32 v28, v41, v41
	v_fmamk_f32 v28, v28, 0xbdd2d3e8, v245
	v_mov_b32_e32 v44, v41
	v_mul_f32_e32 v28, v28, v44
	v_lshlrev_b32_e32 v40, 16, v25
	v_exp_f32_e32 v28, v28
	v_mul_f32_e32 v44, 0xbfb8aa3b, v40
	v_exp_f32_e32 v44, v44
	v_and_b32_e32 v29, 0xffff0000, v29
	v_add_f32_e32 v28, 1.0, v28
	v_rcp_f32_e32 v45, v28
	v_add_f32_e32 v28, 1.0, v44
	v_rcp_f32_e32 v44, v28
	v_and_b32_e32 v28, 0xffff0000, v25
	v_mul_f32_e32 v25, v29, v29
	v_fmamk_f32 v25, v25, 0xbdd2d3e8, v245
	v_mov_b32_e32 v46, v29
	v_mul_f32_e32 v25, v25, v46
	v_exp_f32_e32 v25, v25
	v_mul_f32_e32 v46, 0xbfb8aa3b, v28
	v_exp_f32_e32 v46, v46
	v_pk_mul_f32 v[40:41], v[44:45], v[40:41]
	v_add_f32_e32 v25, 1.0, v25
	v_rcp_f32_e32 v45, v25
	v_add_f32_e32 v25, 1.0, v46
	v_rcp_f32_e32 v44, v25
	v_add_f32_e32 v42, v188, v42
	v_mul_f32_e32 v25, v41, v42
	v_mul_f32_e32 v25, v40, v25
	v_add_f32_e32 v40, v188, v43
	v_pk_mul_f32 v[28:29], v[44:45], v[28:29]
	v_and_b32_e32 v47, 0xffff0000, v30
	v_mul_f32_e32 v29, v29, v40
	v_mul_f32_e32 v28, v28, v29
	v_lshlrev_b32_e32 v29, 16, v30
	v_mul_f32_e32 v44, v29, v29
	v_fmamk_f32 v44, v44, 0xbdd2d3e8, v245
	v_mov_b32_e32 v45, v29
	v_mul_f32_e32 v44, v44, v45
	v_cvt_pk_bf16_f32 v25, v25, v28
	v_lshlrev_b32_e32 v28, 16, v26
	v_exp_f32_e32 v44, v44
	v_mul_f32_e32 v45, 0xbfb8aa3b, v28
	v_exp_f32_e32 v46, v45
	v_mov_b32_e32 v30, v47
	v_add_f32_e32 v44, 1.0, v44
	v_rcp_f32_e32 v45, v44
	v_add_f32_e32 v44, 1.0, v46
	v_and_b32_e32 v46, 0xffff0000, v26
	v_mul_f32_e32 v26, 0x3d372713, v47
	v_mul_f32_e32 v26, v26, v47
	v_fmac_f32_e32 v30, v26, v30
	v_mul_f32_e32 v26, 0x3fcc422a, v30
	v_mul_f32_e32 v26, 0xbfb8aa3b, v26
	v_exp_f32_e32 v26, v26
	v_mul_f32_e32 v30, 0xbfb8aa3b, v46
	v_rcp_f32_e32 v44, v44
	v_exp_f32_e32 v30, v30
	ds_read_b128 v[40:43], v158 offset:35856
	v_add_f32_e32 v26, 1.0, v26
	v_pk_mul_f32 v[28:29], v[44:45], v[28:29]
	v_rcp_f32_e32 v45, v26
	v_add_f32_e32 v26, 1.0, v30
	v_rcp_f32_e32 v44, v26
	s_waitcnt lgkmcnt(0)
	v_add_f32_e32 v40, v188, v40
	v_mul_f32_e32 v26, v29, v40
	v_mul_f32_e32 v26, v28, v26
	v_add_f32_e32 v30, v188, v41
	v_pk_mul_f32 v[28:29], v[44:45], v[46:47]
	v_add_f32_e32 v42, v188, v42
	v_mul_f32_e32 v29, v29, v30
	v_mul_f32_e32 v28, v28, v29
	v_lshlrev_b32_e32 v29, 16, v31
	v_mul_f32_e32 v30, v29, v29
	v_fmamk_f32 v30, v30, 0xbdd2d3e8, v245
	v_mov_b32_e32 v40, v29
	v_mul_f32_e32 v30, v30, v40
	v_cvt_pk_bf16_f32 v26, v26, v28
	v_lshlrev_b32_e32 v28, 16, v27
	v_exp_f32_e32 v30, v30
	v_mul_f32_e32 v40, 0xbfb8aa3b, v28
	v_exp_f32_e32 v40, v40
	v_and_b32_e32 v31, 0xffff0000, v31
	v_add_f32_e32 v30, 1.0, v30
	v_rcp_f32_e32 v41, v30
	v_add_f32_e32 v30, 1.0, v40
	v_rcp_f32_e32 v40, v30
	v_and_b32_e32 v30, 0xffff0000, v27
	v_mul_f32_e32 v27, v31, v31
	v_fmamk_f32 v27, v27, 0xbdd2d3e8, v245
	v_mov_b32_e32 v44, v31
	v_mul_f32_e32 v27, v27, v44
	v_exp_f32_e32 v27, v27
	v_mul_f32_e32 v44, 0xbfb8aa3b, v30
	v_exp_f32_e32 v44, v44
	v_pk_mul_f32 v[28:29], v[40:41], v[28:29]
	v_add_f32_e32 v27, 1.0, v27
	v_rcp_f32_e32 v41, v27
	v_add_f32_e32 v27, 1.0, v44
	v_rcp_f32_e32 v40, v27
	v_mul_f32_e32 v27, v29, v42
	v_mul_f32_e32 v27, v28, v27
	v_add_f32_e32 v42, v188, v43
	v_pk_mul_f32 v[28:29], v[40:41], v[30:31]
	v_lshlrev_b32_e32 v41, 16, v8
	v_mul_f32_e32 v29, v29, v42
	v_mul_f32_e32 v42, v41, v41
	v_fmamk_f32 v42, v42, 0xbdd2d3e8, v245
	v_mov_b32_e32 v43, v41
	v_mul_f32_e32 v42, v42, v43
	v_lshlrev_b32_e32 v40, 16, v12
	v_exp_f32_e32 v42, v42
	v_mul_f32_e32 v43, 0xbfb8aa3b, v40
	v_exp_f32_e32 v44, v43
	v_and_b32_e32 v45, 0xffff0000, v8
	v_add_f32_e32 v42, 1.0, v42
	v_mul_f32_e32 v8, v45, v45
	v_rcp_f32_e32 v43, v42
	v_add_f32_e32 v42, 1.0, v44
	v_and_b32_e32 v44, 0xffff0000, v12
	v_fmamk_f32 v8, v8, 0xbdd2d3e8, v245
	v_mov_b32_e32 v12, v45
	v_mul_f32_e32 v8, v8, v12
	v_exp_f32_e32 v8, v8
	v_mul_f32_e32 v12, 0xbfb8aa3b, v44
	v_rcp_f32_e32 v42, v42
	v_exp_f32_e32 v12, v12
	v_mul_f32_e32 v28, v28, v29
	v_cvt_pk_bf16_f32 v27, v27, v28
	ds_read_b128 v[28:31], v158 offset:35872
	v_add_f32_e32 v8, 1.0, v8
	v_pk_mul_f32 v[40:41], v[42:43], v[40:41]
	v_rcp_f32_e32 v43, v8
	v_add_f32_e32 v8, 1.0, v12
	v_rcp_f32_e32 v42, v8
	s_waitcnt lgkmcnt(0)
	v_add_f32_e32 v28, v188, v28
	v_mul_f32_e32 v8, v41, v28
	v_add_f32_e32 v12, v188, v29
	v_pk_mul_f32 v[28:29], v[42:43], v[44:45]
	v_mul_f32_e32 v8, v40, v8
	v_mul_f32_e32 v12, v29, v12
	v_mul_f32_e32 v12, v28, v12
	v_lshlrev_b32_e32 v29, 16, v9
	v_cvt_pk_bf16_f32 v8, v8, v12
	v_mul_f32_e32 v12, v29, v29
	v_fmamk_f32 v12, v12, 0xbdd2d3e8, v245
	v_mov_b32_e32 v40, v29
	v_mul_f32_e32 v12, v12, v40
	v_lshlrev_b32_e32 v28, 16, v13
	v_exp_f32_e32 v12, v12
	v_mul_f32_e32 v40, 0xbfb8aa3b, v28
	v_exp_f32_e32 v40, v40
	v_and_b32_e32 v43, 0xffff0000, v9
	v_add_f32_e32 v12, 1.0, v12
	v_rcp_f32_e32 v41, v12
	v_add_f32_e32 v12, 1.0, v40
	v_mul_f32_e32 v9, v43, v43
	v_rcp_f32_e32 v40, v12
	v_fmamk_f32 v9, v9, 0xbdd2d3e8, v245
	v_mov_b32_e32 v12, v43
	v_mul_f32_e32 v9, v9, v12
	v_and_b32_e32 v42, 0xffff0000, v13
	v_exp_f32_e32 v9, v9
	v_mul_f32_e32 v12, 0xbfb8aa3b, v42
	v_exp_f32_e32 v44, v12
	v_pk_mul_f32 v[12:13], v[40:41], v[28:29]
	v_add_f32_e32 v9, 1.0, v9
	v_rcp_f32_e32 v29, v9
	v_add_f32_e32 v9, 1.0, v44
	v_rcp_f32_e32 v28, v9
	v_add_f32_e32 v30, v188, v30
	v_mul_f32_e32 v9, v13, v30
	v_mul_f32_e32 v9, v12, v9
	v_add_f32_e32 v30, v188, v31
	v_pk_mul_f32 v[12:13], v[28:29], v[42:43]
	v_and_b32_e32 v43, 0xffff0000, v10
	v_mul_f32_e32 v13, v13, v30
	v_mul_f32_e32 v12, v12, v13
	v_lshlrev_b32_e32 v13, 16, v10
	v_mul_f32_e32 v40, v13, v13
	v_fmamk_f32 v40, v40, 0xbdd2d3e8, v245
	v_mov_b32_e32 v41, v13
	v_mul_f32_e32 v40, v40, v41
	v_cvt_pk_bf16_f32 v9, v9, v12
	v_lshlrev_b32_e32 v12, 16, v14
	v_exp_f32_e32 v40, v40
	v_mul_f32_e32 v41, 0xbfb8aa3b, v12
	v_exp_f32_e32 v42, v41
	v_mul_f32_e32 v10, v43, v43
	v_add_f32_e32 v40, 1.0, v40
	v_rcp_f32_e32 v41, v40
	v_add_f32_e32 v40, 1.0, v42
	v_and_b32_e32 v42, 0xffff0000, v14
	v_fmamk_f32 v10, v10, 0xbdd2d3e8, v245
	v_mov_b32_e32 v14, v43
	v_mul_f32_e32 v10, v10, v14
	v_exp_f32_e32 v10, v10
	v_mul_f32_e32 v14, 0xbfb8aa3b, v42
	v_rcp_f32_e32 v40, v40
	v_exp_f32_e32 v14, v14
	ds_read_b128 v[28:31], v158 offset:35888
	v_add_f32_e32 v10, 1.0, v10
	v_pk_mul_f32 v[12:13], v[40:41], v[12:13]
	v_rcp_f32_e32 v41, v10
	v_add_f32_e32 v10, 1.0, v14
	v_rcp_f32_e32 v40, v10
	s_waitcnt lgkmcnt(0)
	v_add_f32_e32 v28, v188, v28
	v_mul_f32_e32 v10, v13, v28
	v_mul_f32_e32 v10, v12, v10
	v_add_f32_e32 v14, v188, v29
	v_pk_mul_f32 v[12:13], v[40:41], v[42:43]
	v_and_b32_e32 v41, 0xffff0000, v11
	v_mul_f32_e32 v13, v13, v14
	v_mul_f32_e32 v12, v12, v13
	v_lshlrev_b32_e32 v13, 16, v11
	v_mul_f32_e32 v14, v13, v13
	v_fmamk_f32 v14, v14, 0xbdd2d3e8, v245
	v_mov_b32_e32 v28, v13
	v_mul_f32_e32 v14, v14, v28
	v_cvt_pk_bf16_f32 v10, v10, v12
	v_lshlrev_b32_e32 v12, 16, v15
	v_exp_f32_e32 v14, v14
	v_mul_f32_e32 v28, 0xbfb8aa3b, v12
	v_exp_f32_e32 v28, v28
	v_mul_f32_e32 v11, v41, v41
	v_add_f32_e32 v14, 1.0, v14
	v_rcp_f32_e32 v29, v14
	v_add_f32_e32 v14, 1.0, v28
	v_rcp_f32_e32 v28, v14
	v_fmamk_f32 v11, v11, 0xbdd2d3e8, v245
	v_mov_b32_e32 v14, v41
	v_mul_f32_e32 v11, v11, v14
	v_and_b32_e32 v40, 0xffff0000, v15
	v_exp_f32_e32 v11, v11
	v_mul_f32_e32 v14, 0xbfb8aa3b, v40
	v_exp_f32_e32 v14, v14
	v_add_f32_e32 v30, v188, v30
	v_add_f32_e32 v11, 1.0, v11
	v_rcp_f32_e32 v15, v11
	v_add_f32_e32 v11, 1.0, v14
	v_rcp_f32_e32 v14, v11
	v_pk_mul_f32 v[12:13], v[28:29], v[12:13]
	v_add_f32_e32 v28, v188, v31
	v_mul_f32_e32 v11, v13, v30
	v_mul_f32_e32 v11, v12, v11
	v_pk_mul_f32 v[12:13], v[14:15], v[40:41]
	s_waitcnt vmcnt(18)
	v_and_b32_e32 v14, 0xffff0000, v104
	v_mul_f32_e32 v13, v13, v28
	v_mul_f32_e32 v12, v12, v13
	v_cvt_pk_bf16_f32 v11, v11, v12
	v_lshlrev_b32_e32 v12, 16, v104
	v_mul_f32_e32 v13, v12, v12
	v_fmamk_f32 v13, v13, 0xbdd2d3e8, v245
	v_mul_f32_e32 v13, v13, v12
	v_exp_f32_e32 v13, v13
	v_mul_f32_e32 v15, v14, v14
	v_fmamk_f32 v15, v15, 0xbdd2d3e8, v245
	v_mul_f32_e32 v15, v15, v14
	v_add_f32_e32 v13, 1.0, v13
	v_rcp_f32_e32 v13, v13
	global_store_dwordx4 v[160:161], v[8:11], off offset:272
	v_exp_f32_e32 v15, v15
	s_nop 0
	v_fma_f32 v9, v13, v12, -v156
	v_mul_f32_e32 v9, v157, v9
	s_waitcnt vmcnt(1)
	v_fma_f32 v9, v128, v9, v132
	global_store_dwordx4 v[160:161], v[24:27], off offset:256
	v_cvt_pk_bf16_f32 v9, v9, v145
	ds_write_b16 v172, v9 offset:18432
	v_lshlrev_b32_e32 v9, 16, v105
	v_mul_f32_e32 v10, v9, v9
	v_and_b32_e32 v11, 0xffff0000, v105
	v_add_f32_e32 v8, 1.0, v15
	v_fmamk_f32 v10, v10, 0xbdd2d3e8, v245
	v_mul_f32_e32 v12, v11, v11
	v_rcp_f32_e32 v8, v8
	v_mul_f32_e32 v10, v10, v9
	v_fmamk_f32 v12, v12, 0xbdd2d3e8, v245
	v_mul_f32_e32 v12, v12, v11
	v_exp_f32_e32 v10, v10
	v_fma_f32 v8, v8, v14, -v156
	v_exp_f32_e32 v12, v12
	v_mul_f32_e32 v8, v157, v8
	v_fma_f32 v8, v129, v8, v133
	v_cvt_pk_bf16_f32 v8, v8, v145
	v_add_f32_e32 v10, 1.0, v10
	v_rcp_f32_e32 v10, v10
	ds_write_b16 v172, v8 offset:18704
	v_add_f32_e32 v8, 1.0, v12
	v_rcp_f32_e32 v8, v8
	v_fma_f32 v9, v10, v9, -v156
	v_mul_f32_e32 v9, v157, v9
	v_fma_f32 v9, v130, v9, v134
	v_fma_f32 v8, v8, v11, -v156
	v_mul_f32_e32 v8, v157, v8
	v_fmac_f32_e32 v135, v131, v8
	v_cvt_pk_bf16_f32 v8, v9, v145
	v_lshlrev_b32_e32 v9, 16, v106
	v_mul_f32_e32 v10, v9, v9
	v_fmamk_f32 v10, v10, 0xbdd2d3e8, v245
	v_mul_f32_e32 v10, v10, v9
	v_and_b32_e32 v11, 0xffff0000, v106
	v_exp_f32_e32 v10, v10
	v_mul_f32_e32 v12, v11, v11
	v_fmamk_f32 v12, v12, 0xbdd2d3e8, v245
	v_mul_f32_e32 v12, v12, v11
	v_add_f32_e32 v10, 1.0, v10
	v_exp_f32_e32 v12, v12
	v_rcp_f32_e32 v10, v10
	ds_write_b16 v172, v8 offset:18976
	v_cvt_pk_bf16_f32 v8, v135, v145
	ds_write_b16 v172, v8 offset:19248
	v_add_f32_e32 v8, 1.0, v12
	v_fma_f32 v9, v10, v9, -v156
	v_rcp_f32_e32 v8, v8
	v_mul_f32_e32 v9, v157, v9
	v_fma_f32 v9, v112, v9, v116
	v_cvt_pk_bf16_f32 v9, v9, v145
	ds_write_b16 v172, v9 offset:19520
	v_lshlrev_b32_e32 v9, 16, v107
	v_fma_f32 v8, v8, v11, -v156
	v_mul_f32_e32 v10, v9, v9
	v_and_b32_e32 v11, 0xffff0000, v107
	v_fmamk_f32 v10, v10, 0xbdd2d3e8, v245
	v_mul_f32_e32 v12, v11, v11
	v_mul_f32_e32 v10, v10, v9
	v_fmamk_f32 v12, v12, 0xbdd2d3e8, v245
	v_mul_f32_e32 v12, v12, v11
	v_exp_f32_e32 v10, v10
	v_exp_f32_e32 v12, v12
	v_mul_f32_e32 v8, v157, v8
	v_fma_f32 v8, v113, v8, v117
	v_cvt_pk_bf16_f32 v8, v8, v145
	v_add_f32_e32 v10, 1.0, v10
	v_rcp_f32_e32 v10, v10
	ds_write_b16 v172, v8 offset:19792
	v_add_f32_e32 v8, 1.0, v12
	v_rcp_f32_e32 v8, v8
	v_fma_f32 v9, v10, v9, -v156
	v_mul_f32_e32 v9, v157, v9
	v_fma_f32 v9, v114, v9, v118
	v_fma_f32 v8, v8, v11, -v156
	v_mul_f32_e32 v8, v157, v8
	v_fmac_f32_e32 v119, v115, v8
	v_cvt_pk_bf16_f32 v8, v9, v145
	v_lshlrev_b32_e32 v9, 16, v64
	v_mul_f32_e32 v10, v9, v9
	v_fmamk_f32 v10, v10, 0xbdd2d3e8, v245
	v_mul_f32_e32 v10, v10, v9
	v_and_b32_e32 v11, 0xffff0000, v64
	v_exp_f32_e32 v10, v10
	v_mul_f32_e32 v12, v11, v11
	v_fmamk_f32 v12, v12, 0xbdd2d3e8, v245
	v_mul_f32_e32 v12, v12, v11
	v_add_f32_e32 v10, 1.0, v10
	v_exp_f32_e32 v12, v12
	v_rcp_f32_e32 v10, v10
	ds_write_b16 v172, v8 offset:20064
	v_cvt_pk_bf16_f32 v8, v119, v145
	ds_write_b16 v172, v8 offset:20336
	v_add_f32_e32 v8, 1.0, v12
	v_fma_f32 v9, v10, v9, -v156
	v_rcp_f32_e32 v8, v8
	v_mul_f32_e32 v9, v157, v9
	v_fma_f32 v9, v9, v88, v92
	v_cvt_pk_bf16_f32 v9, v9, v145
	ds_write_b16 v172, v9 offset:20608
	v_lshlrev_b32_e32 v9, 16, v65
	v_fma_f32 v8, v8, v11, -v156
	v_mul_f32_e32 v10, v9, v9
	v_and_b32_e32 v11, 0xffff0000, v65
	v_fmamk_f32 v10, v10, 0xbdd2d3e8, v245
	v_mul_f32_e32 v12, v11, v11
	v_mul_f32_e32 v10, v10, v9
	v_fmamk_f32 v12, v12, 0xbdd2d3e8, v245
	v_mul_f32_e32 v12, v12, v11
	v_exp_f32_e32 v10, v10
	v_exp_f32_e32 v12, v12
	v_mul_f32_e32 v8, v157, v8
	v_fma_f32 v8, v8, v89, v93
	v_cvt_pk_bf16_f32 v8, v8, v145
	v_add_f32_e32 v10, 1.0, v10
	v_rcp_f32_e32 v10, v10
	ds_write_b16 v172, v8 offset:20880
	v_add_f32_e32 v8, 1.0, v12
	v_rcp_f32_e32 v8, v8
	v_fma_f32 v9, v10, v9, -v156
	v_mul_f32_e32 v9, v157, v9
	v_fma_f32 v9, v9, v90, v94
	v_fma_f32 v8, v8, v11, -v156
	v_mul_f32_e32 v8, v157, v8
	v_fmac_f32_e32 v95, v8, v91
	v_cvt_pk_bf16_f32 v8, v9, v145
	v_lshlrev_b32_e32 v9, 16, v66
	v_mul_f32_e32 v10, v9, v9
	v_fmamk_f32 v10, v10, 0xbdd2d3e8, v245
	v_mul_f32_e32 v10, v10, v9
	v_and_b32_e32 v11, 0xffff0000, v66
	v_mul_f32_e32 v12, v11, v11
	v_exp_f32_e32 v10, v10
	v_fmamk_f32 v12, v12, 0xbdd2d3e8, v245
	v_mul_f32_e32 v12, v12, v11
	v_exp_f32_e32 v12, v12
	v_add_f32_e32 v10, 1.0, v10
	v_rcp_f32_e32 v10, v10
	ds_write_b16 v172, v8 offset:21152
	v_cvt_pk_bf16_f32 v8, v95, v145
	ds_write_b16 v172, v8 offset:21424
	v_add_f32_e32 v8, 1.0, v12
	v_rcp_f32_e32 v8, v8
	v_fma_f32 v9, v10, v9, -v156
	v_mul_f32_e32 v9, v157, v9
	v_fma_f32 v9, v9, v68, v76
	v_cvt_pk_bf16_f32 v9, v9, v145
	v_fma_f32 v8, v8, v11, -v156
	ds_write_b16 v172, v9 offset:21696
	v_lshlrev_b32_e32 v9, 16, v67
	v_and_b32_e32 v11, 0xffff0000, v67
	v_mul_f32_e32 v10, v9, v9
	v_mul_f32_e32 v12, v11, v11
	v_fmamk_f32 v10, v10, 0xbdd2d3e8, v245
	v_fmamk_f32 v12, v12, 0xbdd2d3e8, v245
	v_mul_f32_e32 v10, v10, v9
	v_mul_f32_e32 v12, v12, v11
	v_exp_f32_e32 v10, v10
	v_exp_f32_e32 v12, v12
	v_mul_f32_e32 v8, v157, v8
	v_fma_f32 v8, v8, v69, v77
	v_cvt_pk_bf16_f32 v8, v8, v145
	v_add_f32_e32 v10, 1.0, v10
	ds_write_b16 v172, v8 offset:21968
	v_add_f32_e32 v8, 1.0, v12
	v_rcp_f32_e32 v10, v10
	v_rcp_f32_e32 v8, v8
	v_fma_f32 v9, v10, v9, -v156
	v_fma_f32 v8, v8, v11, -v156
	v_mul_f32_e32 v9, v157, v9
	v_mul_f32_e32 v8, v157, v8
	v_fma_f32 v9, v9, v70, v78
	v_fmac_f32_e32 v79, v8, v71
	v_cvt_pk_bf16_f32 v8, v9, v145
	ds_write_b16 v172, v8 offset:22240
	v_cvt_pk_bf16_f32 v8, v79, v145
	ds_write_b16 v172, v8 offset:22512
	s_waitcnt lgkmcnt(0)
	s_barrier
	ds_read_b128 v[8:11], v170 offset:18432
	ds_read_b128 v[12:15], v170 offset:18496
	ds_read_b128 v[24:27], v170 offset:22784
	ds_read_b128 v[28:31], v170 offset:22848
	ds_read_b128 v[40:43], v170 offset:27136
	ds_read_b128 v[44:47], v170 offset:27200
	s_waitcnt lgkmcnt(5)
	v_mfma_f32_16x16x32_bf16 v[8:11], v[52:55], v[8:11], 0
	ds_read_b128 v[56:59], v170 offset:31488
	ds_read_b128 v[60:63], v170 offset:31552
	s_waitcnt lgkmcnt(5)
	v_mfma_f32_16x16x32_bf16 v[24:27], v[52:55], v[24:27], 0
	s_waitcnt lgkmcnt(3)
	v_mfma_f32_16x16x32_bf16 v[40:43], v[52:55], v[40:43], 0
	s_waitcnt lgkmcnt(1)
	v_mfma_f32_16x16x32_bf16 v[52:55], v[52:55], v[56:59], 0
	v_mfma_f32_16x16x32_bf16 v[8:11], v[48:51], v[12:15], v[8:11]
	v_mfma_f32_16x16x32_bf16 v[12:15], v[48:51], v[28:31], v[24:27]
	v_mfma_f32_16x16x32_bf16 v[24:27], v[48:51], v[44:47], v[40:43]
	s_nop 2
	ds_read_b128 v[40:43], v170 offset:18560
	ds_read_b128 v[44:47], v170 offset:18624
	s_waitcnt lgkmcnt(2)
	v_mfma_f32_16x16x32_bf16 v[28:31], v[48:51], v[60:63], v[52:55]
	s_waitcnt lgkmcnt(1)
	v_mfma_f32_16x16x32_bf16 v[8:11], v[36:39], v[40:43], v[8:11]
	ds_read_b128 v[40:43], v170 offset:22912
	ds_read_b128 v[48:51], v170 offset:22976
	s_waitcnt lgkmcnt(1)
	v_mfma_f32_16x16x32_bf16 v[12:15], v[36:39], v[40:43], v[12:15]
	ds_read_b128 v[40:43], v170 offset:27264
	ds_read_b128 v[52:55], v170 offset:27328
	s_waitcnt lgkmcnt(1)
	v_mfma_f32_16x16x32_bf16 v[24:27], v[36:39], v[40:43], v[24:27]
	ds_read_b128 v[40:43], v170 offset:31616
	ds_read_b128 v[56:59], v170 offset:31680
	s_waitcnt lgkmcnt(1)
	v_mfma_f32_16x16x32_bf16 v[28:31], v[36:39], v[40:43], v[28:31]
	v_mfma_f32_16x16x32_bf16 v[8:11], v[32:35], v[44:47], v[8:11]
	v_mfma_f32_16x16x32_bf16 v[12:15], v[32:35], v[48:51], v[12:15]
	v_mfma_f32_16x16x32_bf16 v[24:27], v[32:35], v[52:55], v[24:27]
	s_waitcnt lgkmcnt(0)
	v_mfma_f32_16x16x32_bf16 v[28:31], v[32:35], v[56:59], v[28:31]
	s_nop 4
	ds_write2_b32 v159, v8, v12 offset1:16
	s_nop 1
	ds_write2_b32 v159, v24, v28 offset0:32 offset1:48
	ds_write2_b32 v159, v9, v13 offset0:68 offset1:84
	ds_write2_b32 v159, v25, v29 offset0:100 offset1:116
	ds_write2_b32 v159, v10, v14 offset0:136 offset1:152
	ds_write2_b32 v159, v26, v30 offset0:168 offset1:184
	ds_write2_b32 v159, v11, v15 offset0:204 offset1:220
	ds_write2_b32 v159, v27, v31 offset0:236 offset1:252
	v_lshlrev_b32_e32 v13, 16, v20
	v_mul_f32_e32 v14, v13, v13
	v_fmamk_f32 v14, v14, 0xbdd2d3e8, v245
	v_mov_b32_e32 v15, v13
	v_mul_f32_e32 v14, v14, v15
	v_lshlrev_b32_e32 v12, 16, v16
	v_exp_f32_e32 v14, v14
	v_mul_f32_e32 v15, 0xbfb8aa3b, v12
	v_exp_f32_e32 v24, v15
	v_and_b32_e32 v25, 0xffff0000, v20
	v_add_f32_e32 v14, 1.0, v14
	v_rcp_f32_e32 v15, v14
	v_add_f32_e32 v14, 1.0, v24
	v_and_b32_e32 v24, 0xffff0000, v16
	v_mul_f32_e32 v16, v25, v25
	v_fmamk_f32 v16, v16, 0xbdd2d3e8, v245
	v_mov_b32_e32 v20, v25
	v_mul_f32_e32 v16, v16, v20
	v_rcp_f32_e32 v14, v14
	v_exp_f32_e32 v16, v16
	v_mul_f32_e32 v20, 0xbfb8aa3b, v24
	v_exp_f32_e32 v20, v20
	s_waitcnt lgkmcnt(0)
	s_barrier
	ds_read_b128 v[8:11], v158 offset:35840
	v_pk_mul_f32 v[12:13], v[14:15], v[12:13]
	v_add_f32_e32 v14, 1.0, v16
	v_rcp_f32_e32 v15, v14
	v_add_f32_e32 v14, 1.0, v20
	v_rcp_f32_e32 v14, v14
	s_waitcnt lgkmcnt(0)
	v_add_f32_e32 v8, v144, v8
	v_mul_f32_e32 v8, v13, v8
	v_mul_f32_e32 v12, v12, v8
	v_add_f32_e32 v13, v144, v9
	v_pk_mul_f32 v[8:9], v[14:15], v[24:25]
	v_and_b32_e32 v20, 0xffff0000, v17
	v_mul_f32_e32 v9, v9, v13
	v_lshlrev_b32_e32 v13, 16, v21
	v_mul_f32_e32 v8, v8, v9
	v_mul_f32_e32 v9, v13, v13
	v_fmamk_f32 v9, v9, 0xbdd2d3e8, v245
	v_mov_b32_e32 v14, v13
	v_mul_f32_e32 v9, v9, v14
	v_cvt_pk_bf16_f32 v8, v12, v8
	v_lshlrev_b32_e32 v12, 16, v17
	v_exp_f32_e32 v9, v9
	v_mul_f32_e32 v14, 0xbfb8aa3b, v12
	v_exp_f32_e32 v14, v14
	v_and_b32_e32 v21, 0xffff0000, v21
	v_add_f32_e32 v9, 1.0, v9
	v_rcp_f32_e32 v15, v9
	v_add_f32_e32 v9, 1.0, v14
	v_rcp_f32_e32 v14, v9
	v_mul_f32_e32 v9, v21, v21
	v_fmamk_f32 v9, v9, 0xbdd2d3e8, v245
	v_mov_b32_e32 v16, v21
	v_mul_f32_e32 v9, v9, v16
	v_exp_f32_e32 v9, v9
	v_mul_f32_e32 v16, 0xbfb8aa3b, v20
	v_exp_f32_e32 v16, v16
	v_pk_mul_f32 v[12:13], v[14:15], v[12:13]
	v_add_f32_e32 v9, 1.0, v9
	v_rcp_f32_e32 v15, v9
	v_add_f32_e32 v9, 1.0, v16
	v_rcp_f32_e32 v14, v9
	v_add_f32_e32 v10, v144, v10
	v_mul_f32_e32 v9, v13, v10
	v_mul_f32_e32 v9, v12, v9
	v_add_f32_e32 v12, v144, v11
	v_pk_mul_f32 v[10:11], v[14:15], v[20:21]
	v_lshlrev_b32_e32 v15, 16, v22
	v_mul_f32_e32 v16, v15, v15
	v_fmamk_f32 v16, v16, 0xbdd2d3e8, v245
	v_mov_b32_e32 v17, v15
	v_mul_f32_e32 v16, v16, v17
	v_lshlrev_b32_e32 v14, 16, v18
	v_exp_f32_e32 v16, v16
	v_mul_f32_e32 v17, 0xbfb8aa3b, v14
	v_exp_f32_e32 v20, v17
	v_and_b32_e32 v21, 0xffff0000, v22
	v_add_f32_e32 v16, 1.0, v16
	v_rcp_f32_e32 v17, v16
	v_add_f32_e32 v16, 1.0, v20
	v_and_b32_e32 v20, 0xffff0000, v18
	v_mul_f32_e32 v18, v21, v21
	v_fmamk_f32 v18, v18, 0xbdd2d3e8, v245
	v_mov_b32_e32 v22, v21
	v_mul_f32_e32 v18, v18, v22
	v_rcp_f32_e32 v16, v16
	v_exp_f32_e32 v18, v18
	v_mul_f32_e32 v22, 0xbfb8aa3b, v20
	v_mul_f32_e32 v11, v11, v12
	v_exp_f32_e32 v22, v22
	v_mul_f32_e32 v10, v10, v11
	v_cvt_pk_bf16_f32 v9, v9, v10
	ds_read_b128 v[10:13], v158 offset:35856
	v_pk_mul_f32 v[14:15], v[16:17], v[14:15]
	v_add_f32_e32 v16, 1.0, v18
	v_rcp_f32_e32 v17, v16
	v_add_f32_e32 v16, 1.0, v22
	v_rcp_f32_e32 v16, v16
	s_waitcnt lgkmcnt(0)
	v_add_f32_e32 v10, v144, v10
	v_mul_f32_e32 v10, v15, v10
	v_mul_f32_e32 v14, v14, v10
	v_add_f32_e32 v15, v144, v11
	v_pk_mul_f32 v[10:11], v[16:17], v[20:21]
	v_and_b32_e32 v21, 0xffff0000, v23
	v_mul_f32_e32 v11, v11, v15
	v_lshlrev_b32_e32 v15, 16, v23
	v_mul_f32_e32 v10, v10, v11
	v_mul_f32_e32 v11, v15, v15
	v_fmamk_f32 v11, v11, 0xbdd2d3e8, v245
	v_mov_b32_e32 v16, v15
	v_mul_f32_e32 v11, v11, v16
	v_cvt_pk_bf16_f32 v10, v14, v10
	v_lshlrev_b32_e32 v14, 16, v19
	v_exp_f32_e32 v11, v11
	v_mul_f32_e32 v16, 0xbfb8aa3b, v14
	v_exp_f32_e32 v16, v16
	v_mov_b32_e32 v18, v21
	v_add_f32_e32 v11, 1.0, v11
	v_rcp_f32_e32 v17, v11
	v_add_f32_e32 v11, 1.0, v16
	v_rcp_f32_e32 v16, v11
	v_mul_f32_e32 v11, 0x3d372713, v21
	v_mul_f32_e32 v11, v11, v21
	v_fmac_f32_e32 v18, v11, v18
	v_mul_f32_e32 v11, 0x3fcc422a, v18
	v_and_b32_e32 v20, 0xffff0000, v19
	v_mul_f32_e32 v11, 0xbfb8aa3b, v11
	v_exp_f32_e32 v11, v11
	v_mul_f32_e32 v18, 0xbfb8aa3b, v20
	v_exp_f32_e32 v18, v18
	v_pk_mul_f32 v[14:15], v[16:17], v[14:15]
	v_add_f32_e32 v11, 1.0, v11
	v_rcp_f32_e32 v17, v11
	v_add_f32_e32 v11, 1.0, v18
	v_rcp_f32_e32 v16, v11
	v_add_f32_e32 v12, v144, v12
	v_mul_f32_e32 v11, v15, v12
	v_mul_f32_e32 v11, v14, v11
	v_add_f32_e32 v14, v144, v13
	v_pk_mul_f32 v[12:13], v[16:17], v[20:21]
	v_lshlrev_b32_e32 v17, 16, v0
	v_mul_f32_e32 v18, v17, v17
	v_fmamk_f32 v18, v18, 0xbdd2d3e8, v245
	v_mov_b32_e32 v19, v17
	v_mul_f32_e32 v18, v18, v19
	v_lshlrev_b32_e32 v16, 16, v4
	v_exp_f32_e32 v18, v18
	v_mul_f32_e32 v19, 0xbfb8aa3b, v16
	v_exp_f32_e32 v20, v19
	v_and_b32_e32 v21, 0xffff0000, v0
	v_add_f32_e32 v18, 1.0, v18
	v_mul_f32_e32 v0, v21, v21
	v_rcp_f32_e32 v19, v18
	v_add_f32_e32 v18, 1.0, v20
	v_and_b32_e32 v20, 0xffff0000, v4
	v_fmamk_f32 v0, v0, 0xbdd2d3e8, v245
	v_mov_b32_e32 v4, v21
	v_mul_f32_e32 v0, v0, v4
	v_exp_f32_e32 v0, v0
	v_mul_f32_e32 v4, 0xbfb8aa3b, v20
	v_rcp_f32_e32 v18, v18
	v_exp_f32_e32 v4, v4
	v_mul_f32_e32 v13, v13, v14
	v_mul_f32_e32 v12, v12, v13
	v_cvt_pk_bf16_f32 v11, v11, v12
	ds_read_b128 v[12:15], v158 offset:35872
	v_add_f32_e32 v0, 1.0, v0
	v_pk_mul_f32 v[16:17], v[18:19], v[16:17]
	v_rcp_f32_e32 v19, v0
	v_add_f32_e32 v0, 1.0, v4
	v_rcp_f32_e32 v18, v0
	s_waitcnt lgkmcnt(0)
	v_add_f32_e32 v12, v144, v12
	v_mul_f32_e32 v0, v17, v12
	v_add_f32_e32 v4, v144, v13
	v_pk_mul_f32 v[12:13], v[18:19], v[20:21]
	v_mul_f32_e32 v0, v16, v0
	v_mul_f32_e32 v4, v13, v4
	v_mul_f32_e32 v4, v12, v4
	v_lshlrev_b32_e32 v13, 16, v1
	v_cvt_pk_bf16_f32 v0, v0, v4
	v_mul_f32_e32 v4, v13, v13
	v_fmamk_f32 v4, v4, 0xbdd2d3e8, v245
	v_mov_b32_e32 v16, v13
	v_mul_f32_e32 v4, v4, v16
	v_lshlrev_b32_e32 v12, 16, v5
	v_exp_f32_e32 v4, v4
	v_mul_f32_e32 v16, 0xbfb8aa3b, v12
	v_exp_f32_e32 v16, v16
	v_and_b32_e32 v19, 0xffff0000, v1
	v_add_f32_e32 v4, 1.0, v4
	v_rcp_f32_e32 v17, v4
	v_add_f32_e32 v4, 1.0, v16
	v_mul_f32_e32 v1, v19, v19
	v_rcp_f32_e32 v16, v4
	v_fmamk_f32 v1, v1, 0xbdd2d3e8, v245
	v_mov_b32_e32 v4, v19
	v_mul_f32_e32 v1, v1, v4
	v_and_b32_e32 v18, 0xffff0000, v5
	v_exp_f32_e32 v1, v1
	v_mul_f32_e32 v4, 0xbfb8aa3b, v18
	v_exp_f32_e32 v20, v4
	v_pk_mul_f32 v[4:5], v[16:17], v[12:13]
	v_add_f32_e32 v1, 1.0, v1
	v_rcp_f32_e32 v13, v1
	v_add_f32_e32 v1, 1.0, v20
	v_rcp_f32_e32 v12, v1
	v_add_f32_e32 v14, v144, v14
	v_mul_f32_e32 v1, v5, v14
	v_mul_f32_e32 v1, v4, v1
	v_add_f32_e32 v14, v144, v15
	v_pk_mul_f32 v[4:5], v[12:13], v[18:19]
	v_and_b32_e32 v19, 0xffff0000, v2
	v_mul_f32_e32 v5, v5, v14
	v_mul_f32_e32 v4, v4, v5
	v_lshlrev_b32_e32 v5, 16, v2
	v_mul_f32_e32 v16, v5, v5
	v_fmamk_f32 v16, v16, 0xbdd2d3e8, v245
	v_mov_b32_e32 v17, v5
	v_mul_f32_e32 v16, v16, v17
	v_cvt_pk_bf16_f32 v1, v1, v4
	v_lshlrev_b32_e32 v4, 16, v6
	v_exp_f32_e32 v16, v16
	v_mul_f32_e32 v17, 0xbfb8aa3b, v4
	v_exp_f32_e32 v18, v17
	v_mul_f32_e32 v2, v19, v19
	v_add_f32_e32 v16, 1.0, v16
	v_rcp_f32_e32 v17, v16
	v_add_f32_e32 v16, 1.0, v18
	v_and_b32_e32 v18, 0xffff0000, v6
	v_fmamk_f32 v2, v2, 0xbdd2d3e8, v245
	v_mov_b32_e32 v6, v19
	v_mul_f32_e32 v2, v2, v6
	v_exp_f32_e32 v2, v2
	v_mul_f32_e32 v6, 0xbfb8aa3b, v18
	v_rcp_f32_e32 v16, v16
	v_exp_f32_e32 v6, v6
	ds_read_b128 v[12:15], v158 offset:35888
	v_add_f32_e32 v2, 1.0, v2
	v_pk_mul_f32 v[4:5], v[16:17], v[4:5]
	v_rcp_f32_e32 v17, v2
	v_add_f32_e32 v2, 1.0, v6
	v_rcp_f32_e32 v16, v2
	s_waitcnt lgkmcnt(0)
	v_add_f32_e32 v12, v144, v12
	v_mul_f32_e32 v2, v5, v12
	v_mul_f32_e32 v2, v4, v2
	v_add_f32_e32 v6, v144, v13
	v_pk_mul_f32 v[4:5], v[16:17], v[18:19]
	v_and_b32_e32 v17, 0xffff0000, v3
	v_mul_f32_e32 v5, v5, v6
	v_mul_f32_e32 v4, v4, v5
	v_lshlrev_b32_e32 v5, 16, v3
	v_mul_f32_e32 v6, v5, v5
	v_fmamk_f32 v6, v6, 0xbdd2d3e8, v245
	v_mov_b32_e32 v12, v5
	v_mul_f32_e32 v6, v6, v12
	v_cvt_pk_bf16_f32 v2, v2, v4
	v_lshlrev_b32_e32 v4, 16, v7
	v_exp_f32_e32 v6, v6
	v_mul_f32_e32 v12, 0xbfb8aa3b, v4
	v_exp_f32_e32 v12, v12
	v_mul_f32_e32 v3, v17, v17
	v_add_f32_e32 v6, 1.0, v6
	v_rcp_f32_e32 v13, v6
	v_add_f32_e32 v6, 1.0, v12
	v_rcp_f32_e32 v12, v6
	v_fmamk_f32 v3, v3, 0xbdd2d3e8, v245
	v_mov_b32_e32 v6, v17
	v_mul_f32_e32 v3, v3, v6
	v_and_b32_e32 v16, 0xffff0000, v7
	v_exp_f32_e32 v3, v3
	v_mul_f32_e32 v6, 0xbfb8aa3b, v16
	v_exp_f32_e32 v6, v6
	v_add_f32_e32 v14, v144, v14
	v_add_f32_e32 v3, 1.0, v3
	v_rcp_f32_e32 v7, v3
	v_add_f32_e32 v3, 1.0, v6
	v_rcp_f32_e32 v6, v3
	v_pk_mul_f32 v[4:5], v[12:13], v[4:5]
	v_add_f32_e32 v12, v144, v15
	v_mul_f32_e32 v3, v5, v14
	v_mul_f32_e32 v3, v4, v3
	v_pk_mul_f32 v[4:5], v[6:7], v[16:17]
	s_nop 0
	v_mul_f32_e32 v5, v5, v12
	v_mul_f32_e32 v4, v4, v5
	v_cvt_pk_bf16_f32 v3, v3, v4
	global_store_dwordx4 v[160:161], v[8:11], off offset:384
	global_store_dwordx4 v[160:161], v[0:3], off offset:400

.LBB0_397:
	s_and_b64 vcc, exec, s[42:43]
	s_cbranch_vccz .LBB0_363
	s_add_i32 s4, s92, s87
	s_waitcnt vmcnt(1)
	v_mov_b32_e32 v32, v175
	s_mov_b64 s[48:49], s[68:69]
	s_add_u32 s76, s48, 0x7900000
	v_ashrrev_i32_e32 v4, 6, v32
	s_addc_u32 s77, s49, 0
	s_lshl_b32 s4, s4, 6
	s_and_b32 s4, s4, 0xffffff80
	v_lshlrev_b32_e32 v120, 4, v4
	v_and_b32_e32 v127, 63, v32
	v_add_u32_e32 v31, s4, v120
	v_mov_b64_e32 v[0:1], s[76:77]
	v_mad_i64_i32 v[2:3], s[6:7], v31, s62, v[0:1]
	v_lshlrev_b32_e32 v144, 4, v127
	v_lshl_add_u64 v[2:3], v[2:3], 0, v[144:145]
	v_add_co_u32_e32 v2, vcc, s3, v2
	s_nop 1
	v_addc_co_u32_e32 v3, vcc, 0, v3, vcc
	s_barrier
	global_load_dwordx4 v[34:37], v[2:3], off
	v_or_b32_e32 v2, 1, v31
	v_mad_i64_i32 v[2:3], s[6:7], v2, s62, v[0:1]
	v_lshlrev_b32_e32 v30, 7, v4
	v_or_b32_e32 v4, 2, v31
	v_lshl_add_u64 v[2:3], v[2:3], 0, v[144:145]
	v_mad_i64_i32 v[4:5], s[6:7], v4, s62, v[0:1]
	v_add_co_u32_e32 v2, vcc, s3, v2
	v_or_b32_e32 v6, 3, v31
	v_lshl_add_u64 v[4:5], v[4:5], 0, v[144:145]
	v_addc_co_u32_e32 v3, vcc, 0, v3, vcc
	v_mad_i64_i32 v[6:7], s[6:7], v6, s62, v[0:1]
	v_add_co_u32_e32 v4, vcc, s3, v4
	v_or_b32_e32 v8, 4, v31
	v_lshl_add_u64 v[6:7], v[6:7], 0, v[144:145]
	v_addc_co_u32_e32 v5, vcc, 0, v5, vcc
	v_mad_i64_i32 v[8:9], s[6:7], v8, s62, v[0:1]
	v_add_co_u32_e32 v6, vcc, s3, v6
	v_or_b32_e32 v10, 5, v31
	v_lshl_add_u64 v[8:9], v[8:9], 0, v[144:145]
	v_addc_co_u32_e32 v7, vcc, 0, v7, vcc
	v_mad_i64_i32 v[10:11], s[6:7], v10, s62, v[0:1]
	v_add_co_u32_e32 v8, vcc, s3, v8
	v_or_b32_e32 v12, 6, v31
	v_lshl_add_u64 v[10:11], v[10:11], 0, v[144:145]
	v_addc_co_u32_e32 v9, vcc, 0, v9, vcc
	v_mad_i64_i32 v[12:13], s[6:7], v12, s62, v[0:1]
	v_add_co_u32_e32 v10, vcc, s3, v10
	v_lshl_add_u64 v[12:13], v[12:13], 0, v[144:145]
	s_nop 0
	v_addc_co_u32_e32 v11, vcc, 0, v11, vcc
	v_or_b32_e32 v14, 7, v31
	v_add_co_u32_e32 v28, vcc, s3, v12
	v_mad_i64_i32 v[0:1], s[6:7], v14, s62, v[0:1]
	s_nop 0
	v_addc_co_u32_e32 v29, vcc, 0, v13, vcc
	global_load_dwordx4 v[24:27], v[2:3], off
	global_load_dwordx4 v[20:23], v[4:5], off
	global_load_dwordx4 v[16:19], v[6:7], off
	global_load_dwordx4 v[12:15], v[8:9], off
	s_nop 0
	global_load_dwordx4 v[8:11], v[10:11], off
	v_lshl_add_u64 v[0:1], v[0:1], 0, v[144:145]
	v_add_co_u32_e32 v0, vcc, s3, v0
	v_cmp_eq_u32_e64 s[42:43], 0, v127
	s_nop 0
	v_addc_co_u32_e32 v1, vcc, 0, v1, vcc
	v_add_u32_e32 v30, 0, v30
	s_waitcnt vmcnt(5)
	v_lshlrev_b32_e32 v33, 16, v34
	v_mul_f32_e32 v2, v33, v33
	v_fmamk_f32 v2, v2, 0xbdd2d3e8, v245
	v_mul_f32_e32 v2, v2, v33
	v_and_b32_e32 v34, 0xffff0000, v34
	v_exp_f32_e32 v38, v2
	v_mul_f32_e32 v2, v34, v34
	v_fmamk_f32 v2, v2, 0xbdd2d3e8, v245
	v_mul_f32_e32 v2, v2, v34
	v_exp_f32_e32 v39, v2
	global_load_dwordx4 v[4:7], v[28:29], off
	s_nop 0
	global_load_dwordx4 v[0:3], v[0:1], off
	v_add_f32_e32 v28, 1.0, v38
	v_lshlrev_b32_e32 v38, 16, v35
	v_rcp_f32_e32 v29, v28
	v_add_f32_e32 v28, 1.0, v39
	v_mul_f32_e32 v39, v38, v38
	v_and_b32_e32 v35, 0xffff0000, v35
	v_fmamk_f32 v39, v39, 0xbdd2d3e8, v245
	v_mul_f32_e32 v40, v35, v35
	v_mul_f32_e32 v39, v39, v38
	v_fmamk_f32 v40, v40, 0xbdd2d3e8, v245
	v_mul_f32_e32 v40, v40, v35
	v_exp_f32_e32 v39, v39
	v_exp_f32_e32 v40, v40
	v_rcp_f32_e32 v41, v28
	v_add_f32_e32 v28, 1.0, v39
	v_rcp_f32_e32 v39, v28
	v_add_f32_e32 v28, 1.0, v40
	v_lshlrev_b32_e32 v40, 16, v36
	v_mul_f32_e32 v42, v40, v40
	v_and_b32_e32 v36, 0xffff0000, v36
	v_fmamk_f32 v42, v42, 0xbdd2d3e8, v245
	v_mul_f32_e32 v43, v36, v36
	v_mul_f32_e32 v42, v42, v40
	v_fmamk_f32 v43, v43, 0xbdd2d3e8, v245
	v_mul_f32_e32 v43, v43, v36
	v_exp_f32_e32 v42, v42
	v_exp_f32_e32 v43, v43
	v_rcp_f32_e32 v44, v28
	v_add_f32_e32 v28, 1.0, v42
	v_rcp_f32_e32 v42, v28
	v_add_f32_e32 v28, 1.0, v43
	v_lshlrev_b32_e32 v43, 16, v37
	v_mul_f32_e32 v45, v43, v43
	v_and_b32_e32 v37, 0xffff0000, v37
	v_fmamk_f32 v45, v45, 0xbdd2d3e8, v245
	v_mul_f32_e32 v46, v37, v37
	v_mul_f32_e32 v45, v45, v43
	v_fmamk_f32 v46, v46, 0xbdd2d3e8, v245
	v_mul_f32_e32 v46, v46, v37
	v_exp_f32_e32 v45, v45
	v_exp_f32_e32 v46, v46
	v_rcp_f32_e32 v47, v28
	v_add_f32_e32 v28, 1.0, v45
	v_rcp_f32_e32 v45, v28
	v_add_f32_e32 v28, 1.0, v46
	v_rcp_f32_e32 v46, v28
	v_fma_f32 v28, v29, v33, 0
	v_fmac_f32_e32 v28, v41, v34
	v_fmac_f32_e32 v28, v39, v38
	v_fmac_f32_e32 v28, v44, v35
	v_fmac_f32_e32 v28, v42, v40
	v_fmac_f32_e32 v28, v47, v36
	v_fmac_f32_e32 v28, v45, v43
	v_fmac_f32_e32 v28, v46, v37
	s_nop 1
	v_add_f32_dpp v28, v28, v28 quad_perm:[1,0,3,2] row_mask:0xf bank_mask:0xf bound_ctrl:1
	s_nop 1
	v_add_f32_dpp v28, v28, v28 quad_perm:[2,3,0,1] row_mask:0xf bank_mask:0xf bound_ctrl:1
	s_nop 1
	v_add_f32_dpp v28, v28, v28 row_half_mirror row_mask:0xf bank_mask:0xf bound_ctrl:1
	s_nop 1
	v_add_f32_dpp v28, v28, v28 row_mirror row_mask:0xf bank_mask:0xf bound_ctrl:1
	s_nop 0
	v_readlane_b32 s6, v28, 16
	v_readlane_b32 s5, v28, 0
	s_nop 0
	v_mov_b32_e32 v48, s6
	v_readlane_b32 s6, v28, 48
	v_add_f32_e32 v48, s5, v48
	v_readlane_b32 s5, v28, 32
	v_mov_b32_e32 v28, s6
	s_nop 0
	v_add_f32_e32 v28, s5, v28
	v_add_f32_e32 v28, v48, v28
	v_mul_f32_e32 v28, 0x3b000000, v28
	v_fma_f32 v29, v29, v33, -v28
	v_fma_f32 v33, v41, v34, -v28
	v_mul_f32_e32 v33, v33, v33
	v_fmac_f32_e32 v33, v29, v29
	v_fma_f32 v29, v39, v38, -v28
	v_fmac_f32_e32 v33, v29, v29
	v_fma_f32 v29, v44, v35, -v28
	v_fmac_f32_e32 v33, v29, v29
	v_fma_f32 v29, v42, v40, -v28
	v_fmac_f32_e32 v33, v29, v29
	v_fma_f32 v29, v47, v36, -v28
	v_fmac_f32_e32 v33, v29, v29
	v_fma_f32 v29, v45, v43, -v28
	v_fmac_f32_e32 v33, v29, v29
	v_fma_f32 v29, v46, v37, -v28
	v_fmac_f32_e32 v33, v29, v29
	s_nop 1
	v_add_f32_dpp v29, v33, v33 quad_perm:[1,0,3,2] row_mask:0xf bank_mask:0xf bound_ctrl:1
	s_nop 1
	v_add_f32_dpp v29, v29, v29 quad_perm:[2,3,0,1] row_mask:0xf bank_mask:0xf bound_ctrl:1
	s_nop 1
	v_add_f32_dpp v29, v29, v29 row_half_mirror row_mask:0xf bank_mask:0xf bound_ctrl:1
	s_nop 1
	v_add_f32_dpp v29, v29, v29 row_mirror row_mask:0xf bank_mask:0xf bound_ctrl:1
	s_nop 0
	v_readlane_b32 s44, v29, 0
	v_readlane_b32 s5, v29, 16
	v_readlane_b32 s45, v29, 32
	v_readlane_b32 s6, v29, 48
	s_and_saveexec_b64 s[82:83], s[42:43]
	s_cbranch_execz .LBB0_400
	v_mov_b32_e32 v34, s5
	v_mov_b32_e32 v35, s6
	v_pk_add_f32 v[34:35], s[44:45], v[34:35]
	s_nop 0
	v_add_f32_e32 v29, v34, v35
	v_fmamk_f32 v29, v29, 0x3b000000, v176
	v_mul_f32_e32 v33, 0x4f800000, v29
	v_cmp_gt_f32_e32 vcc, s79, v29
	s_nop 1
	v_cndmask_b32_e32 v29, v29, v33, vcc
	v_sqrt_f32_e32 v33, v29
	s_nop 0
	v_add_u32_e32 v34, -1, v33
	v_fma_f32 v35, -v34, v33, v29
	v_cmp_ge_f32_e64 s[44:45], 0, v35
	v_add_u32_e32 v35, 1, v33
	s_nop 0
	v_cndmask_b32_e64 v34, v33, v34, s[44:45]
	v_fma_f32 v33, -v35, v33, v29
	v_cmp_lt_f32_e64 s[44:45], 0, v33
	s_nop 1
	v_cndmask_b32_e64 v33, v34, v35, s[44:45]
	v_mul_f32_e32 v34, 0x37800000, v33
	v_cndmask_b32_e32 v33, v33, v34, vcc
	v_cmp_class_f32_e32 vcc, v29, v177
	s_nop 1
	v_cndmask_b32_e32 v29, v33, v29, vcc
	v_div_scale_f32 v33, s[6:7], v29, v29, 1.0
	v_rcp_f32_e32 v34, v33
	s_nop 0
	v_fma_f32 v35, -v33, v34, 1.0
	v_fmac_f32_e32 v34, v35, v34
	v_div_scale_f32 v35, vcc, 1.0, v29, 1.0
	v_mul_f32_e32 v36, v35, v34
	v_fma_f32 v37, -v33, v36, v35
	v_fmac_f32_e32 v36, v37, v34
	v_fma_f32 v33, -v33, v36, v35
	v_div_fmas_f32 v33, v33, v34, v36
	v_div_fixup_f32 v29, v33, v29, 1.0
	ds_write_b64 v30, v[28:29]
.LBB0_400:
	s_or_b64 exec, exec, s[82:83]
	s_waitcnt vmcnt(6)
	v_and_b32_e32 v33, 0xffff0000, v24
	v_lshlrev_b32_e32 v28, 16, v24
	v_mul_f32_e32 v24, v33, v33
	v_lshlrev_b32_e32 v34, 16, v25
	v_fmamk_f32 v24, v24, 0xbdd2d3e8, v245
	v_mul_f32_e32 v35, v34, v34
	v_and_b32_e32 v25, 0xffff0000, v25
	v_mul_f32_e32 v24, v24, v33
	v_fmamk_f32 v35, v35, 0xbdd2d3e8, v245
	v_mul_f32_e32 v36, v25, v25
	v_mul_f32_e32 v35, v35, v34
	v_fmamk_f32 v36, v36, 0xbdd2d3e8, v245
	v_mul_f32_e32 v36, v36, v25
	v_exp_f32_e32 v24, v24
	v_exp_f32_e32 v35, v35
	v_exp_f32_e32 v36, v36
	v_add_f32_e32 v24, 1.0, v24
	v_rcp_f32_e32 v37, v24
	v_add_f32_e32 v24, 1.0, v35
	v_rcp_f32_e32 v35, v24
	v_add_f32_e32 v24, 1.0, v36
	v_lshlrev_b32_e32 v36, 16, v26
	v_mul_f32_e32 v38, v36, v36
	v_and_b32_e32 v26, 0xffff0000, v26
	v_fmamk_f32 v38, v38, 0xbdd2d3e8, v245
	v_mul_f32_e32 v39, v26, v26
	v_mul_f32_e32 v38, v38, v36
	v_fmamk_f32 v39, v39, 0xbdd2d3e8, v245
	v_mul_f32_e32 v39, v39, v26
	v_exp_f32_e32 v38, v38
	v_exp_f32_e32 v39, v39
	v_mul_f32_e32 v29, v28, v28
	v_fmamk_f32 v29, v29, 0xbdd2d3e8, v245
	v_rcp_f32_e32 v40, v24
	v_add_f32_e32 v24, 1.0, v38
	v_mul_f32_e32 v29, v29, v28
	v_rcp_f32_e32 v38, v24
	v_add_f32_e32 v24, 1.0, v39
	v_lshlrev_b32_e32 v39, 16, v27
	v_mul_f32_e32 v41, v39, v39
	v_and_b32_e32 v27, 0xffff0000, v27
	v_fmamk_f32 v41, v41, 0xbdd2d3e8, v245
	v_mul_f32_e32 v42, v27, v27
	v_exp_f32_e32 v29, v29
	v_mul_f32_e32 v41, v41, v39
	v_fmamk_f32 v42, v42, 0xbdd2d3e8, v245
	v_mul_f32_e32 v42, v42, v27
	v_exp_f32_e32 v41, v41
	v_add_f32_e32 v29, 1.0, v29
	v_exp_f32_e32 v42, v42
	v_rcp_f32_e32 v29, v29
	v_rcp_f32_e32 v43, v24
	v_add_f32_e32 v24, 1.0, v41
	v_rcp_f32_e32 v41, v24
	v_add_f32_e32 v24, 1.0, v42
	v_rcp_f32_e32 v42, v24
	v_fma_f32 v24, v29, v28, 0
	v_fmac_f32_e32 v24, v37, v33
	v_fmac_f32_e32 v24, v35, v34
	v_fmac_f32_e32 v24, v40, v25
	v_fmac_f32_e32 v24, v38, v36
	v_fmac_f32_e32 v24, v43, v26
	v_fmac_f32_e32 v24, v41, v39
	v_fmac_f32_e32 v24, v42, v27
	s_nop 1
	v_add_f32_dpp v24, v24, v24 quad_perm:[1,0,3,2] row_mask:0xf bank_mask:0xf bound_ctrl:1
	s_nop 1
	v_add_f32_dpp v24, v24, v24 quad_perm:[2,3,0,1] row_mask:0xf bank_mask:0xf bound_ctrl:1
	s_nop 1
	v_add_f32_dpp v24, v24, v24 row_half_mirror row_mask:0xf bank_mask:0xf bound_ctrl:1
	s_nop 1
	v_add_f32_dpp v24, v24, v24 row_mirror row_mask:0xf bank_mask:0xf bound_ctrl:1
	s_nop 0
	v_readlane_b32 s6, v24, 16
	v_readlane_b32 s5, v24, 0
	s_nop 0
	v_mov_b32_e32 v44, s6
	v_readlane_b32 s6, v24, 48
	v_add_f32_e32 v44, s5, v44
	v_readlane_b32 s5, v24, 32
	v_mov_b32_e32 v24, s6
	s_nop 0
	v_add_f32_e32 v24, s5, v24
	v_add_f32_e32 v24, v44, v24
	v_mul_f32_e32 v24, 0x3b000000, v24
	v_fma_f32 v28, v29, v28, -v24
	v_fma_f32 v29, v37, v33, -v24
	v_mul_f32_e32 v29, v29, v29
	v_fmac_f32_e32 v29, v28, v28
	v_fma_f32 v28, v35, v34, -v24
	v_fmac_f32_e32 v29, v28, v28
	v_fma_f32 v25, v40, v25, -v24
	v_fmac_f32_e32 v29, v25, v25
	v_fma_f32 v25, v38, v36, -v24
	v_fmac_f32_e32 v29, v25, v25
	v_fma_f32 v25, v43, v26, -v24
	v_fmac_f32_e32 v29, v25, v25
	v_fma_f32 v25, v41, v39, -v24
	v_fmac_f32_e32 v29, v25, v25
	v_fma_f32 v25, v42, v27, -v24
	v_fmac_f32_e32 v29, v25, v25
	s_nop 1
	v_add_f32_dpp v25, v29, v29 quad_perm:[1,0,3,2] row_mask:0xf bank_mask:0xf bound_ctrl:1
	s_nop 1
	v_add_f32_dpp v25, v25, v25 quad_perm:[2,3,0,1] row_mask:0xf bank_mask:0xf bound_ctrl:1
	s_nop 1
	v_add_f32_dpp v25, v25, v25 row_half_mirror row_mask:0xf bank_mask:0xf bound_ctrl:1
	s_nop 1
	v_add_f32_dpp v25, v25, v25 row_mirror row_mask:0xf bank_mask:0xf bound_ctrl:1
	s_nop 0
	v_readlane_b32 s44, v25, 0
	v_readlane_b32 s5, v25, 16
	v_readlane_b32 s45, v25, 32
	v_readlane_b32 s6, v25, 48
	s_and_saveexec_b64 s[82:83], s[42:43]
	s_cbranch_execz .LBB0_402
	v_mov_b32_e32 v26, s5
	v_mov_b32_e32 v27, s6
	v_pk_add_f32 v[26:27], s[44:45], v[26:27]
	s_nop 0
	v_add_f32_e32 v25, v26, v27
	v_fmamk_f32 v25, v25, 0x3b000000, v176
	v_mul_f32_e32 v26, 0x4f800000, v25
	v_cmp_gt_f32_e32 vcc, s79, v25
	s_nop 1
	v_cndmask_b32_e32 v25, v25, v26, vcc
	v_sqrt_f32_e32 v26, v25
	s_nop 0
	v_add_u32_e32 v27, -1, v26
	v_fma_f32 v28, -v27, v26, v25
	v_cmp_ge_f32_e64 s[44:45], 0, v28
	v_add_u32_e32 v28, 1, v26
	s_nop 0
	v_cndmask_b32_e64 v27, v26, v27, s[44:45]
	v_fma_f32 v26, -v28, v26, v25
	v_cmp_lt_f32_e64 s[44:45], 0, v26
	s_nop 1
	v_cndmask_b32_e64 v26, v27, v28, s[44:45]
	v_mul_f32_e32 v27, 0x37800000, v26
	v_cndmask_b32_e32 v26, v26, v27, vcc
	v_cmp_class_f32_e32 vcc, v25, v177
	s_nop 1
	v_cndmask_b32_e32 v25, v26, v25, vcc
	v_div_scale_f32 v26, s[6:7], v25, v25, 1.0
	v_rcp_f32_e32 v27, v26
	s_nop 0
	v_fma_f32 v28, -v26, v27, 1.0
	v_fmac_f32_e32 v27, v28, v27
	v_div_scale_f32 v28, vcc, 1.0, v25, 1.0
	v_mul_f32_e32 v29, v28, v27
	v_fma_f32 v33, -v26, v29, v28
	v_fmac_f32_e32 v29, v33, v27
	v_fma_f32 v26, -v26, v29, v28
	v_div_fmas_f32 v26, v26, v27, v29
	v_div_fixup_f32 v25, v26, v25, 1.0
	ds_write_b64 v30, v[24:25] offset:8
.LBB0_402:
	s_or_b64 exec, exec, s[82:83]
	s_waitcnt vmcnt(5)
	v_and_b32_e32 v26, 0xffff0000, v20
	v_lshlrev_b32_e32 v24, 16, v20
	v_mul_f32_e32 v20, v26, v26
	v_lshlrev_b32_e32 v27, 16, v21
	v_fmamk_f32 v20, v20, 0xbdd2d3e8, v245
	v_mul_f32_e32 v28, v27, v27
	v_and_b32_e32 v21, 0xffff0000, v21
	v_mul_f32_e32 v20, v20, v26
	v_fmamk_f32 v28, v28, 0xbdd2d3e8, v245
	v_mul_f32_e32 v29, v21, v21
	v_mul_f32_e32 v28, v28, v27
	v_fmamk_f32 v29, v29, 0xbdd2d3e8, v245
	v_mul_f32_e32 v29, v29, v21
	v_exp_f32_e32 v20, v20
	v_exp_f32_e32 v28, v28
	v_exp_f32_e32 v29, v29
	v_add_f32_e32 v20, 1.0, v20
	v_rcp_f32_e32 v33, v20
	v_add_f32_e32 v20, 1.0, v28
	v_rcp_f32_e32 v28, v20
	v_add_f32_e32 v20, 1.0, v29
	v_lshlrev_b32_e32 v29, 16, v22
	v_mul_f32_e32 v34, v29, v29
	v_and_b32_e32 v22, 0xffff0000, v22
	v_fmamk_f32 v34, v34, 0xbdd2d3e8, v245
	v_mul_f32_e32 v35, v22, v22
	v_mul_f32_e32 v34, v34, v29
	v_fmamk_f32 v35, v35, 0xbdd2d3e8, v245
	v_mul_f32_e32 v35, v35, v22
	v_exp_f32_e32 v34, v34
	v_exp_f32_e32 v35, v35
	v_mul_f32_e32 v25, v24, v24
	v_fmamk_f32 v25, v25, 0xbdd2d3e8, v245
	v_rcp_f32_e32 v36, v20
	v_add_f32_e32 v20, 1.0, v34
	v_mul_f32_e32 v25, v25, v24
	v_rcp_f32_e32 v34, v20
	v_add_f32_e32 v20, 1.0, v35
	v_lshlrev_b32_e32 v35, 16, v23
	v_mul_f32_e32 v37, v35, v35
	v_and_b32_e32 v23, 0xffff0000, v23
	v_fmamk_f32 v37, v37, 0xbdd2d3e8, v245
	v_mul_f32_e32 v38, v23, v23
	v_exp_f32_e32 v25, v25
	v_mul_f32_e32 v37, v37, v35
	v_fmamk_f32 v38, v38, 0xbdd2d3e8, v245
	v_mul_f32_e32 v38, v38, v23
	v_exp_f32_e32 v37, v37
	v_add_f32_e32 v25, 1.0, v25
	v_exp_f32_e32 v38, v38
	v_rcp_f32_e32 v25, v25
	v_rcp_f32_e32 v39, v20
	v_add_f32_e32 v20, 1.0, v37
	v_rcp_f32_e32 v37, v20
	v_add_f32_e32 v20, 1.0, v38
	v_rcp_f32_e32 v38, v20
	v_fma_f32 v20, v25, v24, 0
	v_fmac_f32_e32 v20, v33, v26
	v_fmac_f32_e32 v20, v28, v27
	v_fmac_f32_e32 v20, v36, v21
	v_fmac_f32_e32 v20, v34, v29
	v_fmac_f32_e32 v20, v39, v22
	v_fmac_f32_e32 v20, v37, v35
	v_fmac_f32_e32 v20, v38, v23
	s_nop 1
	v_add_f32_dpp v20, v20, v20 quad_perm:[1,0,3,2] row_mask:0xf bank_mask:0xf bound_ctrl:1
	s_nop 1
	v_add_f32_dpp v20, v20, v20 quad_perm:[2,3,0,1] row_mask:0xf bank_mask:0xf bound_ctrl:1
	s_nop 1
	v_add_f32_dpp v20, v20, v20 row_half_mirror row_mask:0xf bank_mask:0xf bound_ctrl:1
	s_nop 1
	v_add_f32_dpp v20, v20, v20 row_mirror row_mask:0xf bank_mask:0xf bound_ctrl:1
	s_nop 0
	v_readlane_b32 s6, v20, 16
	v_readlane_b32 s5, v20, 0
	s_nop 0
	v_mov_b32_e32 v40, s6
	v_readlane_b32 s6, v20, 48
	v_add_f32_e32 v40, s5, v40
	v_readlane_b32 s5, v20, 32
	v_mov_b32_e32 v20, s6
	s_nop 0
	v_add_f32_e32 v20, s5, v20
	v_add_f32_e32 v20, v40, v20
	v_mul_f32_e32 v20, 0x3b000000, v20
	v_fma_f32 v24, v25, v24, -v20
	v_fma_f32 v25, v33, v26, -v20
	v_mul_f32_e32 v25, v25, v25
	v_fmac_f32_e32 v25, v24, v24
	v_fma_f32 v24, v28, v27, -v20
	v_fmac_f32_e32 v25, v24, v24
	v_fma_f32 v21, v36, v21, -v20
	v_fmac_f32_e32 v25, v21, v21
	v_fma_f32 v21, v34, v29, -v20
	v_fmac_f32_e32 v25, v21, v21
	v_fma_f32 v21, v39, v22, -v20
	v_fmac_f32_e32 v25, v21, v21
	v_fma_f32 v21, v37, v35, -v20
	v_fmac_f32_e32 v25, v21, v21
	v_fma_f32 v21, v38, v23, -v20
	v_fmac_f32_e32 v25, v21, v21
	s_nop 1
	v_add_f32_dpp v21, v25, v25 quad_perm:[1,0,3,2] row_mask:0xf bank_mask:0xf bound_ctrl:1
	s_nop 1
	v_add_f32_dpp v21, v21, v21 quad_perm:[2,3,0,1] row_mask:0xf bank_mask:0xf bound_ctrl:1
	s_nop 1
	v_add_f32_dpp v21, v21, v21 row_half_mirror row_mask:0xf bank_mask:0xf bound_ctrl:1
	s_nop 1
	v_add_f32_dpp v21, v21, v21 row_mirror row_mask:0xf bank_mask:0xf bound_ctrl:1
	s_nop 0
	v_readlane_b32 s44, v21, 0
	v_readlane_b32 s5, v21, 16
	v_readlane_b32 s45, v21, 32
	v_readlane_b32 s6, v21, 48
	s_and_saveexec_b64 s[82:83], s[42:43]
	s_cbranch_execz .LBB0_404
	v_mov_b32_e32 v22, s5
	v_mov_b32_e32 v23, s6
	v_pk_add_f32 v[22:23], s[44:45], v[22:23]
	s_nop 0
	v_add_f32_e32 v21, v22, v23
	v_fmamk_f32 v21, v21, 0x3b000000, v176
	v_mul_f32_e32 v22, 0x4f800000, v21
	v_cmp_gt_f32_e32 vcc, s79, v21
	s_nop 1
	v_cndmask_b32_e32 v21, v21, v22, vcc
	v_sqrt_f32_e32 v22, v21
	s_nop 0
	v_add_u32_e32 v23, -1, v22
	v_fma_f32 v24, -v23, v22, v21
	v_cmp_ge_f32_e64 s[44:45], 0, v24
	v_add_u32_e32 v24, 1, v22
	s_nop 0
	v_cndmask_b32_e64 v23, v22, v23, s[44:45]
	v_fma_f32 v22, -v24, v22, v21
	v_cmp_lt_f32_e64 s[44:45], 0, v22
	s_nop 1
	v_cndmask_b32_e64 v22, v23, v24, s[44:45]
	v_mul_f32_e32 v23, 0x37800000, v22
	v_cndmask_b32_e32 v22, v22, v23, vcc
	v_cmp_class_f32_e32 vcc, v21, v177
	s_nop 1
	v_cndmask_b32_e32 v21, v22, v21, vcc
	v_div_scale_f32 v22, s[6:7], v21, v21, 1.0
	v_rcp_f32_e32 v23, v22
	s_nop 0
	v_fma_f32 v24, -v22, v23, 1.0
	v_fmac_f32_e32 v23, v24, v23
	v_div_scale_f32 v24, vcc, 1.0, v21, 1.0
	v_mul_f32_e32 v25, v24, v23
	v_fma_f32 v26, -v22, v25, v24
	v_fmac_f32_e32 v25, v26, v23
	v_fma_f32 v22, -v22, v25, v24
	v_div_fmas_f32 v22, v22, v23, v25
	v_div_fixup_f32 v21, v22, v21, 1.0
	ds_write_b64 v30, v[20:21] offset:16
.LBB0_404:
	s_or_b64 exec, exec, s[82:83]
	s_waitcnt vmcnt(4)
	v_and_b32_e32 v22, 0xffff0000, v16
	v_lshlrev_b32_e32 v20, 16, v16
	v_mul_f32_e32 v16, v22, v22
	v_lshlrev_b32_e32 v23, 16, v17
	v_fmamk_f32 v16, v16, 0xbdd2d3e8, v245
	v_mul_f32_e32 v24, v23, v23
	v_and_b32_e32 v17, 0xffff0000, v17
	v_mul_f32_e32 v16, v16, v22
	v_fmamk_f32 v24, v24, 0xbdd2d3e8, v245
	v_mul_f32_e32 v25, v17, v17
	v_mul_f32_e32 v24, v24, v23
	v_fmamk_f32 v25, v25, 0xbdd2d3e8, v245
	v_mul_f32_e32 v25, v25, v17
	v_exp_f32_e32 v16, v16
	v_exp_f32_e32 v24, v24
	v_exp_f32_e32 v25, v25
	v_add_f32_e32 v16, 1.0, v16
	v_rcp_f32_e32 v26, v16
	v_add_f32_e32 v16, 1.0, v24
	v_rcp_f32_e32 v24, v16
	v_add_f32_e32 v16, 1.0, v25
	v_lshlrev_b32_e32 v25, 16, v18
	v_mul_f32_e32 v27, v25, v25
	v_and_b32_e32 v18, 0xffff0000, v18
	v_fmamk_f32 v27, v27, 0xbdd2d3e8, v245
	v_mul_f32_e32 v28, v18, v18
	v_mul_f32_e32 v27, v27, v25
	v_fmamk_f32 v28, v28, 0xbdd2d3e8, v245
	v_mul_f32_e32 v28, v28, v18
	v_exp_f32_e32 v27, v27
	v_exp_f32_e32 v28, v28
	v_mul_f32_e32 v21, v20, v20
	v_fmamk_f32 v21, v21, 0xbdd2d3e8, v245
	v_rcp_f32_e32 v29, v16
	v_add_f32_e32 v16, 1.0, v27
	v_mul_f32_e32 v21, v21, v20
	v_rcp_f32_e32 v27, v16
	v_add_f32_e32 v16, 1.0, v28
	v_lshlrev_b32_e32 v28, 16, v19
	v_mul_f32_e32 v33, v28, v28
	v_and_b32_e32 v19, 0xffff0000, v19
	v_fmamk_f32 v33, v33, 0xbdd2d3e8, v245
	v_mul_f32_e32 v34, v19, v19
	v_exp_f32_e32 v21, v21
	v_mul_f32_e32 v33, v33, v28
	v_fmamk_f32 v34, v34, 0xbdd2d3e8, v245
	v_mul_f32_e32 v34, v34, v19
	v_exp_f32_e32 v33, v33
	v_add_f32_e32 v21, 1.0, v21
	v_exp_f32_e32 v34, v34
	v_rcp_f32_e32 v21, v21
	v_rcp_f32_e32 v35, v16
	v_add_f32_e32 v16, 1.0, v33
	v_rcp_f32_e32 v33, v16
	v_add_f32_e32 v16, 1.0, v34
	v_rcp_f32_e32 v34, v16
	v_fma_f32 v16, v21, v20, 0
	v_fmac_f32_e32 v16, v26, v22
	v_fmac_f32_e32 v16, v24, v23
	v_fmac_f32_e32 v16, v29, v17
	v_fmac_f32_e32 v16, v27, v25
	v_fmac_f32_e32 v16, v35, v18
	v_fmac_f32_e32 v16, v33, v28
	v_fmac_f32_e32 v16, v34, v19
	s_nop 1
	v_add_f32_dpp v16, v16, v16 quad_perm:[1,0,3,2] row_mask:0xf bank_mask:0xf bound_ctrl:1
	s_nop 1
	v_add_f32_dpp v16, v16, v16 quad_perm:[2,3,0,1] row_mask:0xf bank_mask:0xf bound_ctrl:1
	s_nop 1
	v_add_f32_dpp v16, v16, v16 row_half_mirror row_mask:0xf bank_mask:0xf bound_ctrl:1
	s_nop 1
	v_add_f32_dpp v16, v16, v16 row_mirror row_mask:0xf bank_mask:0xf bound_ctrl:1
	s_nop 0
	v_readlane_b32 s6, v16, 16
	v_readlane_b32 s5, v16, 0
	s_nop 0
	v_mov_b32_e32 v36, s6
	v_readlane_b32 s6, v16, 48
	v_add_f32_e32 v36, s5, v36
	v_readlane_b32 s5, v16, 32
	v_mov_b32_e32 v16, s6
	s_nop 0
	v_add_f32_e32 v16, s5, v16
	v_add_f32_e32 v16, v36, v16
	v_mul_f32_e32 v16, 0x3b000000, v16
	v_fma_f32 v20, v21, v20, -v16
	v_fma_f32 v21, v26, v22, -v16
	v_mul_f32_e32 v21, v21, v21
	v_fmac_f32_e32 v21, v20, v20
	v_fma_f32 v20, v24, v23, -v16
	v_fmac_f32_e32 v21, v20, v20
	v_fma_f32 v17, v29, v17, -v16
	v_fmac_f32_e32 v21, v17, v17
	v_fma_f32 v17, v27, v25, -v16
	v_fmac_f32_e32 v21, v17, v17
	v_fma_f32 v17, v35, v18, -v16
	v_fmac_f32_e32 v21, v17, v17
	v_fma_f32 v17, v33, v28, -v16
	v_fmac_f32_e32 v21, v17, v17
	v_fma_f32 v17, v34, v19, -v16
	v_fmac_f32_e32 v21, v17, v17
	s_nop 1
	v_add_f32_dpp v17, v21, v21 quad_perm:[1,0,3,2] row_mask:0xf bank_mask:0xf bound_ctrl:1
	s_nop 1
	v_add_f32_dpp v17, v17, v17 quad_perm:[2,3,0,1] row_mask:0xf bank_mask:0xf bound_ctrl:1
	s_nop 1
	v_add_f32_dpp v17, v17, v17 row_half_mirror row_mask:0xf bank_mask:0xf bound_ctrl:1
	s_nop 1
	v_add_f32_dpp v17, v17, v17 row_mirror row_mask:0xf bank_mask:0xf bound_ctrl:1
	s_nop 0
	v_readlane_b32 s44, v17, 0
	v_readlane_b32 s5, v17, 16
	v_readlane_b32 s45, v17, 32
	v_readlane_b32 s6, v17, 48
	s_and_saveexec_b64 s[82:83], s[42:43]
	s_cbranch_execz .LBB0_406
	v_mov_b32_e32 v18, s5
	v_mov_b32_e32 v19, s6
	v_pk_add_f32 v[18:19], s[44:45], v[18:19]
	s_nop 0
	v_add_f32_e32 v17, v18, v19
	v_fmamk_f32 v17, v17, 0x3b000000, v176
	v_mul_f32_e32 v18, 0x4f800000, v17
	v_cmp_gt_f32_e32 vcc, s79, v17
	s_nop 1
	v_cndmask_b32_e32 v17, v17, v18, vcc
	v_sqrt_f32_e32 v18, v17
	s_nop 0
	v_add_u32_e32 v19, -1, v18
	v_fma_f32 v20, -v19, v18, v17
	v_cmp_ge_f32_e64 s[44:45], 0, v20
	v_add_u32_e32 v20, 1, v18
	s_nop 0
	v_cndmask_b32_e64 v19, v18, v19, s[44:45]
	v_fma_f32 v18, -v20, v18, v17
	v_cmp_lt_f32_e64 s[44:45], 0, v18
	s_nop 1
	v_cndmask_b32_e64 v18, v19, v20, s[44:45]
	v_mul_f32_e32 v19, 0x37800000, v18
	v_cndmask_b32_e32 v18, v18, v19, vcc
	v_cmp_class_f32_e32 vcc, v17, v177
	s_nop 1
	v_cndmask_b32_e32 v17, v18, v17, vcc
	v_div_scale_f32 v18, s[6:7], v17, v17, 1.0
	v_rcp_f32_e32 v19, v18
	s_nop 0
	v_fma_f32 v20, -v18, v19, 1.0
	v_fmac_f32_e32 v19, v20, v19
	v_div_scale_f32 v20, vcc, 1.0, v17, 1.0
	v_mul_f32_e32 v21, v20, v19
	v_fma_f32 v22, -v18, v21, v20
	v_fmac_f32_e32 v21, v22, v19
	v_fma_f32 v18, -v18, v21, v20
	v_div_fmas_f32 v18, v18, v19, v21
	v_div_fixup_f32 v17, v18, v17, 1.0
	ds_write_b64 v30, v[16:17] offset:24
.LBB0_406:
	s_or_b64 exec, exec, s[82:83]
	s_waitcnt vmcnt(3)
	v_and_b32_e32 v18, 0xffff0000, v12
	v_lshlrev_b32_e32 v16, 16, v12
	v_mul_f32_e32 v12, v18, v18
	v_lshlrev_b32_e32 v19, 16, v13
	v_fmamk_f32 v12, v12, 0xbdd2d3e8, v245
	v_mul_f32_e32 v20, v19, v19
	v_and_b32_e32 v13, 0xffff0000, v13
	v_mul_f32_e32 v12, v12, v18
	v_fmamk_f32 v20, v20, 0xbdd2d3e8, v245
	v_mul_f32_e32 v21, v13, v13
	v_mul_f32_e32 v20, v20, v19
	v_fmamk_f32 v21, v21, 0xbdd2d3e8, v245
	v_mul_f32_e32 v21, v21, v13
	v_exp_f32_e32 v12, v12
	v_exp_f32_e32 v20, v20
	v_exp_f32_e32 v21, v21
	v_add_f32_e32 v12, 1.0, v12
	v_rcp_f32_e32 v22, v12
	v_add_f32_e32 v12, 1.0, v20
	v_rcp_f32_e32 v20, v12
	v_add_f32_e32 v12, 1.0, v21
	v_lshlrev_b32_e32 v21, 16, v14
	v_mul_f32_e32 v23, v21, v21
	v_and_b32_e32 v14, 0xffff0000, v14
	v_fmamk_f32 v23, v23, 0xbdd2d3e8, v245
	v_mul_f32_e32 v24, v14, v14
	v_mul_f32_e32 v23, v23, v21
	v_fmamk_f32 v24, v24, 0xbdd2d3e8, v245
	v_mul_f32_e32 v24, v24, v14
	v_exp_f32_e32 v23, v23
	v_exp_f32_e32 v24, v24
	v_mul_f32_e32 v17, v16, v16
	v_fmamk_f32 v17, v17, 0xbdd2d3e8, v245
	v_rcp_f32_e32 v25, v12
	v_add_f32_e32 v12, 1.0, v23
	v_mul_f32_e32 v17, v17, v16
	v_rcp_f32_e32 v23, v12
	v_add_f32_e32 v12, 1.0, v24
	v_lshlrev_b32_e32 v24, 16, v15
	v_mul_f32_e32 v26, v24, v24
	v_and_b32_e32 v15, 0xffff0000, v15
	v_fmamk_f32 v26, v26, 0xbdd2d3e8, v245
	v_mul_f32_e32 v27, v15, v15
	v_exp_f32_e32 v17, v17
	v_mul_f32_e32 v26, v26, v24
	v_fmamk_f32 v27, v27, 0xbdd2d3e8, v245
	v_mul_f32_e32 v27, v27, v15
	v_exp_f32_e32 v26, v26
	v_add_f32_e32 v17, 1.0, v17
	v_exp_f32_e32 v27, v27
	v_rcp_f32_e32 v17, v17
	v_rcp_f32_e32 v28, v12
	v_add_f32_e32 v12, 1.0, v26
	v_rcp_f32_e32 v26, v12
	v_add_f32_e32 v12, 1.0, v27
	v_rcp_f32_e32 v27, v12
	v_fma_f32 v12, v17, v16, 0
	v_fmac_f32_e32 v12, v22, v18
	v_fmac_f32_e32 v12, v20, v19
	v_fmac_f32_e32 v12, v25, v13
	v_fmac_f32_e32 v12, v23, v21
	v_fmac_f32_e32 v12, v28, v14
	v_fmac_f32_e32 v12, v26, v24
	v_fmac_f32_e32 v12, v27, v15
	s_nop 1
	v_add_f32_dpp v12, v12, v12 quad_perm:[1,0,3,2] row_mask:0xf bank_mask:0xf bound_ctrl:1
	s_nop 1
	v_add_f32_dpp v12, v12, v12 quad_perm:[2,3,0,1] row_mask:0xf bank_mask:0xf bound_ctrl:1
	s_nop 1
	v_add_f32_dpp v12, v12, v12 row_half_mirror row_mask:0xf bank_mask:0xf bound_ctrl:1
	s_nop 1
	v_add_f32_dpp v12, v12, v12 row_mirror row_mask:0xf bank_mask:0xf bound_ctrl:1
	s_nop 0
	v_readlane_b32 s6, v12, 16
	v_readlane_b32 s5, v12, 0
	s_nop 0
	v_mov_b32_e32 v29, s6
	v_readlane_b32 s6, v12, 48
	v_add_f32_e32 v29, s5, v29
	v_readlane_b32 s5, v12, 32
	v_mov_b32_e32 v12, s6
	s_nop 0
	v_add_f32_e32 v12, s5, v12
	v_add_f32_e32 v12, v29, v12
	v_mul_f32_e32 v12, 0x3b000000, v12
	v_fma_f32 v16, v17, v16, -v12
	v_fma_f32 v17, v22, v18, -v12
	v_mul_f32_e32 v17, v17, v17
	v_fmac_f32_e32 v17, v16, v16
	v_fma_f32 v16, v20, v19, -v12
	v_fmac_f32_e32 v17, v16, v16
	v_fma_f32 v13, v25, v13, -v12
	v_fmac_f32_e32 v17, v13, v13
	v_fma_f32 v13, v23, v21, -v12
	v_fmac_f32_e32 v17, v13, v13
	v_fma_f32 v13, v28, v14, -v12
	v_fmac_f32_e32 v17, v13, v13
	v_fma_f32 v13, v26, v24, -v12
	v_fmac_f32_e32 v17, v13, v13
	v_fma_f32 v13, v27, v15, -v12
	v_fmac_f32_e32 v17, v13, v13
	s_nop 1
	v_add_f32_dpp v13, v17, v17 quad_perm:[1,0,3,2] row_mask:0xf bank_mask:0xf bound_ctrl:1
	s_nop 1
	v_add_f32_dpp v13, v13, v13 quad_perm:[2,3,0,1] row_mask:0xf bank_mask:0xf bound_ctrl:1
	s_nop 1
	v_add_f32_dpp v13, v13, v13 row_half_mirror row_mask:0xf bank_mask:0xf bound_ctrl:1
	s_nop 1
	v_add_f32_dpp v13, v13, v13 row_mirror row_mask:0xf bank_mask:0xf bound_ctrl:1
	s_nop 0
	v_readlane_b32 s44, v13, 0
	v_readlane_b32 s5, v13, 16
	v_readlane_b32 s45, v13, 32
	v_readlane_b32 s6, v13, 48
	s_and_saveexec_b64 s[82:83], s[42:43]
	s_cbranch_execz .LBB0_408
	v_mov_b32_e32 v14, s5
	v_mov_b32_e32 v15, s6
	v_pk_add_f32 v[14:15], s[44:45], v[14:15]
	s_nop 0
	v_add_f32_e32 v13, v14, v15
	v_fmamk_f32 v13, v13, 0x3b000000, v176
	v_mul_f32_e32 v14, 0x4f800000, v13
	v_cmp_gt_f32_e32 vcc, s79, v13
	s_nop 1
	v_cndmask_b32_e32 v13, v13, v14, vcc
	v_sqrt_f32_e32 v14, v13
	s_nop 0
	v_add_u32_e32 v15, -1, v14
	v_fma_f32 v16, -v15, v14, v13
	v_cmp_ge_f32_e64 s[44:45], 0, v16
	v_add_u32_e32 v16, 1, v14
	s_nop 0
	v_cndmask_b32_e64 v15, v14, v15, s[44:45]
	v_fma_f32 v14, -v16, v14, v13
	v_cmp_lt_f32_e64 s[44:45], 0, v14
	s_nop 1
	v_cndmask_b32_e64 v14, v15, v16, s[44:45]
	v_mul_f32_e32 v15, 0x37800000, v14
	v_cndmask_b32_e32 v14, v14, v15, vcc
	v_cmp_class_f32_e32 vcc, v13, v177
	s_nop 1
	v_cndmask_b32_e32 v13, v14, v13, vcc
	v_div_scale_f32 v14, s[6:7], v13, v13, 1.0
	v_rcp_f32_e32 v15, v14
	s_nop 0
	v_fma_f32 v16, -v14, v15, 1.0
	v_fmac_f32_e32 v15, v16, v15
	v_div_scale_f32 v16, vcc, 1.0, v13, 1.0
	v_mul_f32_e32 v17, v16, v15
	v_fma_f32 v18, -v14, v17, v16
	v_fmac_f32_e32 v17, v18, v15
	v_fma_f32 v14, -v14, v17, v16
	v_div_fmas_f32 v14, v14, v15, v17
	v_div_fixup_f32 v13, v14, v13, 1.0
	ds_write_b64 v30, v[12:13] offset:32
.LBB0_408:
	s_or_b64 exec, exec, s[82:83]
	s_waitcnt vmcnt(2)
	v_and_b32_e32 v14, 0xffff0000, v8
	v_lshlrev_b32_e32 v12, 16, v8
	v_mul_f32_e32 v8, v14, v14
	v_lshlrev_b32_e32 v15, 16, v9
	v_fmamk_f32 v8, v8, 0xbdd2d3e8, v245
	v_mul_f32_e32 v16, v15, v15
	v_and_b32_e32 v9, 0xffff0000, v9
	v_mul_f32_e32 v8, v8, v14
	v_fmamk_f32 v16, v16, 0xbdd2d3e8, v245
	v_mul_f32_e32 v17, v9, v9
	v_mul_f32_e32 v16, v16, v15
	v_fmamk_f32 v17, v17, 0xbdd2d3e8, v245
	v_mul_f32_e32 v17, v17, v9
	v_exp_f32_e32 v8, v8
	v_exp_f32_e32 v16, v16
	v_exp_f32_e32 v17, v17
	v_add_f32_e32 v8, 1.0, v8
	v_rcp_f32_e32 v18, v8
	v_add_f32_e32 v8, 1.0, v16
	v_rcp_f32_e32 v16, v8
	v_add_f32_e32 v8, 1.0, v17
	v_lshlrev_b32_e32 v17, 16, v10
	v_mul_f32_e32 v19, v17, v17
	v_and_b32_e32 v10, 0xffff0000, v10
	v_fmamk_f32 v19, v19, 0xbdd2d3e8, v245
	v_mul_f32_e32 v20, v10, v10
	v_mul_f32_e32 v19, v19, v17
	v_fmamk_f32 v20, v20, 0xbdd2d3e8, v245
	v_mul_f32_e32 v20, v20, v10
	v_exp_f32_e32 v19, v19
	v_exp_f32_e32 v20, v20
	v_mul_f32_e32 v13, v12, v12
	v_fmamk_f32 v13, v13, 0xbdd2d3e8, v245
	v_rcp_f32_e32 v21, v8
	v_add_f32_e32 v8, 1.0, v19
	v_mul_f32_e32 v13, v13, v12
	v_rcp_f32_e32 v19, v8
	v_add_f32_e32 v8, 1.0, v20
	v_lshlrev_b32_e32 v20, 16, v11
	v_mul_f32_e32 v22, v20, v20
	v_and_b32_e32 v11, 0xffff0000, v11
	v_fmamk_f32 v22, v22, 0xbdd2d3e8, v245
	v_mul_f32_e32 v23, v11, v11
	v_exp_f32_e32 v13, v13
	v_mul_f32_e32 v22, v22, v20
	v_fmamk_f32 v23, v23, 0xbdd2d3e8, v245
	v_mul_f32_e32 v23, v23, v11
	v_exp_f32_e32 v22, v22
	v_add_f32_e32 v13, 1.0, v13
	v_exp_f32_e32 v23, v23
	v_rcp_f32_e32 v13, v13
	v_rcp_f32_e32 v24, v8
	v_add_f32_e32 v8, 1.0, v22
	v_rcp_f32_e32 v22, v8
	v_add_f32_e32 v8, 1.0, v23
	v_rcp_f32_e32 v23, v8
	v_fma_f32 v8, v13, v12, 0
	v_fmac_f32_e32 v8, v18, v14
	v_fmac_f32_e32 v8, v16, v15
	v_fmac_f32_e32 v8, v21, v9
	v_fmac_f32_e32 v8, v19, v17
	v_fmac_f32_e32 v8, v24, v10
	v_fmac_f32_e32 v8, v22, v20
	v_fmac_f32_e32 v8, v23, v11
	s_nop 1
	v_add_f32_dpp v8, v8, v8 quad_perm:[1,0,3,2] row_mask:0xf bank_mask:0xf bound_ctrl:1
	s_nop 1
	v_add_f32_dpp v8, v8, v8 quad_perm:[2,3,0,1] row_mask:0xf bank_mask:0xf bound_ctrl:1
	s_nop 1
	v_add_f32_dpp v8, v8, v8 row_half_mirror row_mask:0xf bank_mask:0xf bound_ctrl:1
	s_nop 1
	v_add_f32_dpp v8, v8, v8 row_mirror row_mask:0xf bank_mask:0xf bound_ctrl:1
	s_nop 0
	v_readlane_b32 s6, v8, 16
	v_readlane_b32 s5, v8, 0
	s_nop 0
	v_mov_b32_e32 v25, s6
	v_readlane_b32 s6, v8, 48
	v_add_f32_e32 v25, s5, v25
	v_readlane_b32 s5, v8, 32
	v_mov_b32_e32 v8, s6
	s_nop 0
	v_add_f32_e32 v8, s5, v8
	v_add_f32_e32 v8, v25, v8
	v_mul_f32_e32 v8, 0x3b000000, v8
	v_fma_f32 v12, v13, v12, -v8
	v_fma_f32 v13, v18, v14, -v8
	v_mul_f32_e32 v13, v13, v13
	v_fmac_f32_e32 v13, v12, v12
	v_fma_f32 v12, v16, v15, -v8
	v_fmac_f32_e32 v13, v12, v12
	v_fma_f32 v9, v21, v9, -v8
	v_fmac_f32_e32 v13, v9, v9
	v_fma_f32 v9, v19, v17, -v8
	v_fmac_f32_e32 v13, v9, v9
	v_fma_f32 v9, v24, v10, -v8
	v_fmac_f32_e32 v13, v9, v9
	v_fma_f32 v9, v22, v20, -v8
	v_fmac_f32_e32 v13, v9, v9
	v_fma_f32 v9, v23, v11, -v8
	v_fmac_f32_e32 v13, v9, v9
	s_nop 1
	v_add_f32_dpp v9, v13, v13 quad_perm:[1,0,3,2] row_mask:0xf bank_mask:0xf bound_ctrl:1
	s_nop 1
	v_add_f32_dpp v9, v9, v9 quad_perm:[2,3,0,1] row_mask:0xf bank_mask:0xf bound_ctrl:1
	s_nop 1
	v_add_f32_dpp v9, v9, v9 row_half_mirror row_mask:0xf bank_mask:0xf bound_ctrl:1
	s_nop 1
	v_add_f32_dpp v9, v9, v9 row_mirror row_mask:0xf bank_mask:0xf bound_ctrl:1
	s_nop 0
	v_readlane_b32 s44, v9, 0
	v_readlane_b32 s5, v9, 16
	v_readlane_b32 s45, v9, 32
	v_readlane_b32 s6, v9, 48
	s_and_saveexec_b64 s[82:83], s[42:43]
	s_cbranch_execz .LBB0_410
	v_mov_b32_e32 v10, s5
	v_mov_b32_e32 v11, s6
	v_pk_add_f32 v[10:11], s[44:45], v[10:11]
	s_nop 0
	v_add_f32_e32 v9, v10, v11
	v_fmamk_f32 v9, v9, 0x3b000000, v176
	v_mul_f32_e32 v10, 0x4f800000, v9
	v_cmp_gt_f32_e32 vcc, s79, v9
	s_nop 1
	v_cndmask_b32_e32 v9, v9, v10, vcc
	v_sqrt_f32_e32 v10, v9
	s_nop 0
	v_add_u32_e32 v11, -1, v10
	v_fma_f32 v12, -v11, v10, v9
	v_cmp_ge_f32_e64 s[44:45], 0, v12
	v_add_u32_e32 v12, 1, v10
	s_nop 0
	v_cndmask_b32_e64 v11, v10, v11, s[44:45]
	v_fma_f32 v10, -v12, v10, v9
	v_cmp_lt_f32_e64 s[44:45], 0, v10
	s_nop 1
	v_cndmask_b32_e64 v10, v11, v12, s[44:45]
	v_mul_f32_e32 v11, 0x37800000, v10
	v_cndmask_b32_e32 v10, v10, v11, vcc
	v_cmp_class_f32_e32 vcc, v9, v177
	s_nop 1
	v_cndmask_b32_e32 v9, v10, v9, vcc
	v_div_scale_f32 v10, s[6:7], v9, v9, 1.0
	v_rcp_f32_e32 v11, v10
	s_nop 0
	v_fma_f32 v12, -v10, v11, 1.0
	v_fmac_f32_e32 v11, v12, v11
	v_div_scale_f32 v12, vcc, 1.0, v9, 1.0
	v_mul_f32_e32 v13, v12, v11
	v_fma_f32 v14, -v10, v13, v12
	v_fmac_f32_e32 v13, v14, v11
	v_fma_f32 v10, -v10, v13, v12
	v_div_fmas_f32 v10, v10, v11, v13
	v_div_fixup_f32 v9, v10, v9, 1.0
	ds_write_b64 v30, v[8:9] offset:40
.LBB0_410:
	s_or_b64 exec, exec, s[82:83]
	s_waitcnt vmcnt(1)
	v_and_b32_e32 v10, 0xffff0000, v4
	v_lshlrev_b32_e32 v8, 16, v4
	v_mul_f32_e32 v4, v10, v10
	v_lshlrev_b32_e32 v11, 16, v5
	v_fmamk_f32 v4, v4, 0xbdd2d3e8, v245
	v_mul_f32_e32 v12, v11, v11
	v_and_b32_e32 v5, 0xffff0000, v5
	v_mul_f32_e32 v4, v4, v10
	v_fmamk_f32 v12, v12, 0xbdd2d3e8, v245
	v_mul_f32_e32 v13, v5, v5
	v_mul_f32_e32 v12, v12, v11
	v_fmamk_f32 v13, v13, 0xbdd2d3e8, v245
	v_mul_f32_e32 v13, v13, v5
	v_exp_f32_e32 v4, v4
	v_exp_f32_e32 v12, v12
	v_exp_f32_e32 v13, v13
	v_add_f32_e32 v4, 1.0, v4
	v_rcp_f32_e32 v14, v4
	v_add_f32_e32 v4, 1.0, v12
	v_rcp_f32_e32 v12, v4
	v_add_f32_e32 v4, 1.0, v13
	v_lshlrev_b32_e32 v13, 16, v6
	v_mul_f32_e32 v15, v13, v13
	v_and_b32_e32 v6, 0xffff0000, v6
	v_fmamk_f32 v15, v15, 0xbdd2d3e8, v245
	v_mul_f32_e32 v16, v6, v6
	v_mul_f32_e32 v15, v15, v13
	v_fmamk_f32 v16, v16, 0xbdd2d3e8, v245
	v_mul_f32_e32 v16, v16, v6
	v_exp_f32_e32 v15, v15
	v_exp_f32_e32 v16, v16
	v_mul_f32_e32 v9, v8, v8
	v_fmamk_f32 v9, v9, 0xbdd2d3e8, v245
	v_rcp_f32_e32 v17, v4
	v_add_f32_e32 v4, 1.0, v15
	v_mul_f32_e32 v9, v9, v8
	v_rcp_f32_e32 v15, v4
	v_add_f32_e32 v4, 1.0, v16
	v_lshlrev_b32_e32 v16, 16, v7
	v_mul_f32_e32 v18, v16, v16
	v_and_b32_e32 v7, 0xffff0000, v7
	v_fmamk_f32 v18, v18, 0xbdd2d3e8, v245
	v_mul_f32_e32 v19, v7, v7
	v_exp_f32_e32 v9, v9
	v_mul_f32_e32 v18, v18, v16
	v_fmamk_f32 v19, v19, 0xbdd2d3e8, v245
	v_mul_f32_e32 v19, v19, v7
	v_exp_f32_e32 v18, v18
	v_add_f32_e32 v9, 1.0, v9
	v_exp_f32_e32 v19, v19
	v_rcp_f32_e32 v9, v9
	v_rcp_f32_e32 v20, v4
	v_add_f32_e32 v4, 1.0, v18
	v_rcp_f32_e32 v18, v4
	v_add_f32_e32 v4, 1.0, v19
	v_rcp_f32_e32 v19, v4
	v_fma_f32 v4, v9, v8, 0
	v_fmac_f32_e32 v4, v14, v10
	v_fmac_f32_e32 v4, v12, v11
	v_fmac_f32_e32 v4, v17, v5
	v_fmac_f32_e32 v4, v15, v13
	v_fmac_f32_e32 v4, v20, v6
	v_fmac_f32_e32 v4, v18, v16
	v_fmac_f32_e32 v4, v19, v7
	s_nop 1
	v_add_f32_dpp v4, v4, v4 quad_perm:[1,0,3,2] row_mask:0xf bank_mask:0xf bound_ctrl:1
	s_nop 1
	v_add_f32_dpp v4, v4, v4 quad_perm:[2,3,0,1] row_mask:0xf bank_mask:0xf bound_ctrl:1
	s_nop 1
	v_add_f32_dpp v4, v4, v4 row_half_mirror row_mask:0xf bank_mask:0xf bound_ctrl:1
	s_nop 1
	v_add_f32_dpp v4, v4, v4 row_mirror row_mask:0xf bank_mask:0xf bound_ctrl:1
	s_nop 0
	v_readlane_b32 s6, v4, 16
	v_readlane_b32 s5, v4, 0
	s_nop 0
	v_mov_b32_e32 v21, s6
	v_readlane_b32 s6, v4, 48
	v_add_f32_e32 v21, s5, v21
	v_readlane_b32 s5, v4, 32
	v_mov_b32_e32 v4, s6
	s_nop 0
	v_add_f32_e32 v4, s5, v4
	v_add_f32_e32 v4, v21, v4
	v_mul_f32_e32 v4, 0x3b000000, v4
	v_fma_f32 v8, v9, v8, -v4
	v_fma_f32 v9, v14, v10, -v4
	v_mul_f32_e32 v9, v9, v9
	v_fmac_f32_e32 v9, v8, v8
	v_fma_f32 v8, v12, v11, -v4
	v_fmac_f32_e32 v9, v8, v8
	v_fma_f32 v5, v17, v5, -v4
	v_fmac_f32_e32 v9, v5, v5
	v_fma_f32 v5, v15, v13, -v4
	v_fmac_f32_e32 v9, v5, v5
	v_fma_f32 v5, v20, v6, -v4
	v_fmac_f32_e32 v9, v5, v5
	v_fma_f32 v5, v18, v16, -v4
	v_fmac_f32_e32 v9, v5, v5
	v_fma_f32 v5, v19, v7, -v4
	v_fmac_f32_e32 v9, v5, v5
	s_nop 1
	v_add_f32_dpp v5, v9, v9 quad_perm:[1,0,3,2] row_mask:0xf bank_mask:0xf bound_ctrl:1
	s_nop 1
	v_add_f32_dpp v5, v5, v5 quad_perm:[2,3,0,1] row_mask:0xf bank_mask:0xf bound_ctrl:1
	s_nop 1
	v_add_f32_dpp v5, v5, v5 row_half_mirror row_mask:0xf bank_mask:0xf bound_ctrl:1
	s_nop 1
	v_add_f32_dpp v5, v5, v5 row_mirror row_mask:0xf bank_mask:0xf bound_ctrl:1
	s_nop 0
	v_readlane_b32 s44, v5, 0
	v_readlane_b32 s5, v5, 16
	v_readlane_b32 s45, v5, 32
	v_readlane_b32 s6, v5, 48
	s_and_saveexec_b64 s[82:83], s[42:43]
	s_cbranch_execz .LBB0_412
	v_mov_b32_e32 v6, s5
	v_mov_b32_e32 v7, s6
	v_pk_add_f32 v[6:7], s[44:45], v[6:7]
	s_nop 0
	v_add_f32_e32 v5, v6, v7
	v_fmamk_f32 v5, v5, 0x3b000000, v176
	v_mul_f32_e32 v6, 0x4f800000, v5
	v_cmp_gt_f32_e32 vcc, s79, v5
	s_nop 1
	v_cndmask_b32_e32 v5, v5, v6, vcc
	v_sqrt_f32_e32 v6, v5
	s_nop 0
	v_add_u32_e32 v7, -1, v6
	v_fma_f32 v8, -v7, v6, v5
	v_cmp_ge_f32_e64 s[44:45], 0, v8
	v_add_u32_e32 v8, 1, v6
	s_nop 0
	v_cndmask_b32_e64 v7, v6, v7, s[44:45]
	v_fma_f32 v6, -v8, v6, v5
	v_cmp_lt_f32_e64 s[44:45], 0, v6
	s_nop 1
	v_cndmask_b32_e64 v6, v7, v8, s[44:45]
	v_mul_f32_e32 v7, 0x37800000, v6
	v_cndmask_b32_e32 v6, v6, v7, vcc
	v_cmp_class_f32_e32 vcc, v5, v177
	s_nop 1
	v_cndmask_b32_e32 v5, v6, v5, vcc
	v_div_scale_f32 v6, s[6:7], v5, v5, 1.0
	v_rcp_f32_e32 v7, v6
	s_nop 0
	v_fma_f32 v8, -v6, v7, 1.0
	v_fmac_f32_e32 v7, v8, v7
	v_div_scale_f32 v8, vcc, 1.0, v5, 1.0
	v_mul_f32_e32 v9, v8, v7
	v_fma_f32 v10, -v6, v9, v8
	v_fmac_f32_e32 v9, v10, v7
	v_fma_f32 v6, -v6, v9, v8
	v_div_fmas_f32 v6, v6, v7, v9
	v_div_fixup_f32 v5, v6, v5, 1.0
	ds_write_b64 v30, v[4:5] offset:48
.LBB0_412:
	s_or_b64 exec, exec, s[82:83]
	s_waitcnt vmcnt(0)
	v_and_b32_e32 v6, 0xffff0000, v0
	v_lshlrev_b32_e32 v4, 16, v0
	v_mul_f32_e32 v0, v6, v6
	v_lshlrev_b32_e32 v7, 16, v1
	v_fmamk_f32 v0, v0, 0xbdd2d3e8, v245
	v_mul_f32_e32 v8, v7, v7
	v_and_b32_e32 v1, 0xffff0000, v1
	v_mul_f32_e32 v0, v0, v6
	v_fmamk_f32 v8, v8, 0xbdd2d3e8, v245
	v_mul_f32_e32 v9, v1, v1
	v_mul_f32_e32 v8, v8, v7
	v_fmamk_f32 v9, v9, 0xbdd2d3e8, v245
	v_mul_f32_e32 v9, v9, v1
	v_exp_f32_e32 v0, v0
	v_exp_f32_e32 v8, v8
	v_exp_f32_e32 v9, v9
	v_add_f32_e32 v0, 1.0, v0
	v_rcp_f32_e32 v10, v0
	v_add_f32_e32 v0, 1.0, v8
	v_rcp_f32_e32 v8, v0
	v_add_f32_e32 v0, 1.0, v9
	v_lshlrev_b32_e32 v9, 16, v2
	v_mul_f32_e32 v11, v9, v9
	v_and_b32_e32 v2, 0xffff0000, v2
	v_fmamk_f32 v11, v11, 0xbdd2d3e8, v245
	v_mul_f32_e32 v12, v2, v2
	v_mul_f32_e32 v11, v11, v9
	v_fmamk_f32 v12, v12, 0xbdd2d3e8, v245
	v_mul_f32_e32 v12, v12, v2
	v_exp_f32_e32 v11, v11
	v_exp_f32_e32 v12, v12
	v_mul_f32_e32 v5, v4, v4
	v_fmamk_f32 v5, v5, 0xbdd2d3e8, v245
	v_rcp_f32_e32 v13, v0
	v_add_f32_e32 v0, 1.0, v11
	v_mul_f32_e32 v5, v5, v4
	v_rcp_f32_e32 v11, v0
	v_add_f32_e32 v0, 1.0, v12
	v_lshlrev_b32_e32 v12, 16, v3
	v_mul_f32_e32 v14, v12, v12
	v_and_b32_e32 v3, 0xffff0000, v3
	v_fmamk_f32 v14, v14, 0xbdd2d3e8, v245
	v_mul_f32_e32 v15, v3, v3
	v_exp_f32_e32 v5, v5
	v_mul_f32_e32 v14, v14, v12
	v_fmamk_f32 v15, v15, 0xbdd2d3e8, v245
	v_mul_f32_e32 v15, v15, v3
	v_exp_f32_e32 v14, v14
	v_add_f32_e32 v5, 1.0, v5
	v_exp_f32_e32 v15, v15
	v_rcp_f32_e32 v5, v5
	v_rcp_f32_e32 v16, v0
	v_add_f32_e32 v0, 1.0, v14
	v_rcp_f32_e32 v14, v0
	v_add_f32_e32 v0, 1.0, v15
	v_rcp_f32_e32 v15, v0
	v_fma_f32 v0, v5, v4, 0
	v_fmac_f32_e32 v0, v10, v6
	v_fmac_f32_e32 v0, v8, v7
	v_fmac_f32_e32 v0, v13, v1
	v_fmac_f32_e32 v0, v11, v9
	v_fmac_f32_e32 v0, v16, v2
	v_fmac_f32_e32 v0, v14, v12
	v_fmac_f32_e32 v0, v15, v3
	s_nop 1
	v_add_f32_dpp v0, v0, v0 quad_perm:[1,0,3,2] row_mask:0xf bank_mask:0xf bound_ctrl:1
	s_nop 1
	v_add_f32_dpp v0, v0, v0 quad_perm:[2,3,0,1] row_mask:0xf bank_mask:0xf bound_ctrl:1
	s_nop 1
	v_add_f32_dpp v0, v0, v0 row_half_mirror row_mask:0xf bank_mask:0xf bound_ctrl:1
	s_nop 1
	v_add_f32_dpp v0, v0, v0 row_mirror row_mask:0xf bank_mask:0xf bound_ctrl:1
	s_nop 0
	v_readlane_b32 s6, v0, 16
	v_readlane_b32 s5, v0, 0
	s_nop 0
	v_mov_b32_e32 v17, s6
	v_readlane_b32 s6, v0, 48
	v_add_f32_e32 v17, s5, v17
	v_readlane_b32 s5, v0, 32
	v_mov_b32_e32 v0, s6
	s_nop 0
	v_add_f32_e32 v0, s5, v0
	v_add_f32_e32 v0, v17, v0
	v_mul_f32_e32 v0, 0x3b000000, v0
	v_fma_f32 v4, v5, v4, -v0
	v_fma_f32 v5, v10, v6, -v0
	v_mul_f32_e32 v5, v5, v5
	v_fmac_f32_e32 v5, v4, v4
	v_fma_f32 v4, v8, v7, -v0
	v_fmac_f32_e32 v5, v4, v4
	v_fma_f32 v1, v13, v1, -v0
	v_fmac_f32_e32 v5, v1, v1
	v_fma_f32 v1, v11, v9, -v0
	v_fmac_f32_e32 v5, v1, v1
	v_fma_f32 v1, v16, v2, -v0
	v_fmac_f32_e32 v5, v1, v1
	v_fma_f32 v1, v14, v12, -v0
	v_fmac_f32_e32 v5, v1, v1
	v_fma_f32 v1, v15, v3, -v0
	v_fmac_f32_e32 v5, v1, v1
	s_nop 1
	v_add_f32_dpp v1, v5, v5 quad_perm:[1,0,3,2] row_mask:0xf bank_mask:0xf bound_ctrl:1
	s_nop 1
	v_add_f32_dpp v1, v1, v1 quad_perm:[2,3,0,1] row_mask:0xf bank_mask:0xf bound_ctrl:1
	s_nop 1
	v_add_f32_dpp v1, v1, v1 row_half_mirror row_mask:0xf bank_mask:0xf bound_ctrl:1
	s_nop 1
	v_add_f32_dpp v1, v1, v1 row_mirror row_mask:0xf bank_mask:0xf bound_ctrl:1
	s_nop 0
	v_readlane_b32 s44, v1, 0
	v_readlane_b32 s5, v1, 16
	v_readlane_b32 s45, v1, 32
	v_readlane_b32 s6, v1, 48
	s_and_saveexec_b64 s[82:83], s[42:43]
	s_cbranch_execz .LBB0_414
	v_mov_b32_e32 v2, s5
	v_mov_b32_e32 v3, s6
	v_pk_add_f32 v[2:3], s[44:45], v[2:3]
	s_nop 0
	v_add_f32_e32 v1, v2, v3
	v_fmamk_f32 v1, v1, 0x3b000000, v176
	v_mul_f32_e32 v2, 0x4f800000, v1
	v_cmp_gt_f32_e32 vcc, s79, v1
	s_nop 1
	v_cndmask_b32_e32 v1, v1, v2, vcc
	v_sqrt_f32_e32 v2, v1
	s_nop 0
	v_add_u32_e32 v3, -1, v2
	v_fma_f32 v4, -v3, v2, v1
	v_cmp_ge_f32_e64 s[44:45], 0, v4
	v_add_u32_e32 v4, 1, v2
	s_nop 0
	v_cndmask_b32_e64 v3, v2, v3, s[44:45]
	v_fma_f32 v2, -v4, v2, v1
	v_cmp_lt_f32_e64 s[44:45], 0, v2
	s_nop 1
	v_cndmask_b32_e64 v2, v3, v4, s[44:45]
	v_mul_f32_e32 v3, 0x37800000, v2
	v_cndmask_b32_e32 v2, v2, v3, vcc
	v_cmp_class_f32_e32 vcc, v1, v177
	s_nop 1
	v_cndmask_b32_e32 v1, v2, v1, vcc
	v_div_scale_f32 v2, s[6:7], v1, v1, 1.0
	v_rcp_f32_e32 v3, v2
	s_nop 0
	v_fma_f32 v4, -v2, v3, 1.0
	v_fmac_f32_e32 v3, v4, v3
	v_div_scale_f32 v4, vcc, 1.0, v1, 1.0
	v_mul_f32_e32 v5, v4, v3
	v_fma_f32 v6, -v2, v5, v4
	v_fmac_f32_e32 v5, v6, v3
	v_fma_f32 v2, -v2, v5, v4
	v_div_fmas_f32 v2, v2, v3, v5
	v_div_fixup_f32 v1, v2, v1, 1.0
	ds_write_b64 v30, v[0:1] offset:56
.LBB0_414:
	s_or_b64 exec, exec, s[82:83]
	v_lshlrev_b32_e32 v4, 3, v127
	v_or_b32_e32 v2, 8, v31
	v_mov_b64_e32 v[0:1], s[76:77]
	v_mad_i64_i32 v[2:3], s[6:7], v2, s62, v[0:1]
	v_lshlrev_b32_e32 v144, 1, v4
	v_lshl_add_u64 v[2:3], v[2:3], 0, v[144:145]
	v_add_co_u32_e32 v2, vcc, 0x2000, v2
	v_or_b32_e32 v4, 10, v31
	s_nop 0
	v_addc_co_u32_e32 v3, vcc, 0, v3, vcc
	global_load_dwordx4 v[34:37], v[2:3], off
	v_or_b32_e32 v2, 9, v31
	v_mad_i64_i32 v[2:3], s[6:7], v2, s62, v[0:1]
	v_lshl_add_u64 v[2:3], v[2:3], 0, v[144:145]
	v_mad_i64_i32 v[4:5], s[6:7], v4, s62, v[0:1]
	v_add_co_u32_e32 v2, vcc, 0x2000, v2
	v_or_b32_e32 v6, 11, v31
	v_lshl_add_u64 v[4:5], v[4:5], 0, v[144:145]
	v_addc_co_u32_e32 v3, vcc, 0, v3, vcc
	v_mad_i64_i32 v[6:7], s[6:7], v6, s62, v[0:1]
	v_add_co_u32_e32 v4, vcc, 0x2000, v4
	v_or_b32_e32 v8, 12, v31
	v_lshl_add_u64 v[6:7], v[6:7], 0, v[144:145]
	v_addc_co_u32_e32 v5, vcc, 0, v5, vcc
	v_mad_i64_i32 v[8:9], s[6:7], v8, s62, v[0:1]
	global_load_dwordx4 v[24:27], v[2:3], off
	v_add_co_u32_e32 v2, vcc, 0x2000, v6
	v_or_b32_e32 v10, 13, v31
	v_lshl_add_u64 v[8:9], v[8:9], 0, v[144:145]
	v_addc_co_u32_e32 v3, vcc, 0, v7, vcc
	v_mad_i64_i32 v[10:11], s[6:7], v10, s62, v[0:1]
	v_add_co_u32_e32 v6, vcc, 0x2000, v8
	v_or_b32_e32 v12, 14, v31
	v_lshl_add_u64 v[10:11], v[10:11], 0, v[144:145]
	v_addc_co_u32_e32 v7, vcc, 0, v9, vcc
	v_mad_i64_i32 v[12:13], s[6:7], v12, s62, v[0:1]
	global_load_dwordx4 v[20:23], v[4:5], off
	global_load_dwordx4 v[16:19], v[2:3], off
	v_add_co_u32_e32 v2, vcc, 0x2000, v10
	v_lshl_add_u64 v[28:29], v[12:13], 0, v[144:145]
	s_nop 0
	v_addc_co_u32_e32 v3, vcc, 0, v11, vcc
	v_add_co_u32_e32 v4, vcc, 0x2000, v28
	v_or_b32_e32 v14, 15, v31
	s_nop 0
	v_addc_co_u32_e32 v5, vcc, 0, v29, vcc
	v_mad_i64_i32 v[0:1], s[6:7], v14, s62, v[0:1]
	global_load_dwordx4 v[12:15], v[6:7], off
	global_load_dwordx4 v[8:11], v[2:3], off
	v_lshl_add_u64 v[0:1], v[0:1], 0, v[144:145]
	v_add_co_u32_e32 v0, vcc, 0x2000, v0
	s_waitcnt vmcnt(5)
	v_lshlrev_b32_e32 v29, 16, v34
	v_mul_f32_e32 v2, v29, v29
	v_and_b32_e32 v31, 0xffff0000, v34
	v_fmamk_f32 v2, v2, 0xbdd2d3e8, v245
	v_mul_f32_e32 v3, 0x3d372713, v31
	v_mul_f32_e32 v2, v2, v29
	v_mul_f32_e32 v3, v3, v31
	v_fma_f32 v3, v3, v31, v31
	v_exp_f32_e32 v28, v2
	v_mul_f32_e32 v2, 0x3fcc422a, v3
	v_addc_co_u32_e32 v1, vcc, 0, v1, vcc
	v_mul_f32_e32 v2, 0xbfb8aa3b, v2
	v_exp_f32_e32 v33, v2
	global_load_dwordx4 v[4:7], v[4:5], off
	s_nop 0
	global_load_dwordx4 v[0:3], v[0:1], off
	v_add_f32_e32 v28, 1.0, v28
	v_rcp_f32_e32 v34, v28
	v_add_f32_e32 v28, 1.0, v33
	v_lshlrev_b32_e32 v33, 16, v35
	v_mul_f32_e32 v38, v33, v33
	v_and_b32_e32 v35, 0xffff0000, v35
	v_fmamk_f32 v38, v38, 0xbdd2d3e8, v245
	v_mul_f32_e32 v39, v35, v35
	v_mul_f32_e32 v38, v38, v33
	v_fmamk_f32 v39, v39, 0xbdd2d3e8, v245
	v_mul_f32_e32 v39, v39, v35
	v_exp_f32_e32 v38, v38
	v_exp_f32_e32 v39, v39
	v_rcp_f32_e32 v40, v28
	v_add_f32_e32 v28, 1.0, v38
	v_rcp_f32_e32 v38, v28
	v_add_f32_e32 v28, 1.0, v39
	v_lshlrev_b32_e32 v39, 16, v36
	v_mul_f32_e32 v41, v39, v39
	v_and_b32_e32 v36, 0xffff0000, v36
	v_fmamk_f32 v41, v41, 0xbdd2d3e8, v245
	v_mul_f32_e32 v42, v36, v36
	v_mul_f32_e32 v41, v41, v39
	v_fmamk_f32 v42, v42, 0xbdd2d3e8, v245
	v_mul_f32_e32 v42, v42, v36
	v_exp_f32_e32 v41, v41
	v_exp_f32_e32 v42, v42
	v_rcp_f32_e32 v43, v28
	v_add_f32_e32 v28, 1.0, v41
	v_rcp_f32_e32 v41, v28
	v_add_f32_e32 v28, 1.0, v42
	v_lshlrev_b32_e32 v42, 16, v37
	v_mul_f32_e32 v44, v42, v42
	v_and_b32_e32 v37, 0xffff0000, v37
	v_fmamk_f32 v44, v44, 0xbdd2d3e8, v245
	v_mul_f32_e32 v45, v37, v37
	v_mul_f32_e32 v44, v44, v42
	v_fmamk_f32 v45, v45, 0xbdd2d3e8, v245
	v_mul_f32_e32 v45, v45, v37
	v_exp_f32_e32 v44, v44
	v_exp_f32_e32 v45, v45
	v_rcp_f32_e32 v46, v28
	v_add_f32_e32 v28, 1.0, v44
	v_rcp_f32_e32 v44, v28
	v_add_f32_e32 v28, 1.0, v45
	v_rcp_f32_e32 v45, v28
	v_fma_f32 v28, v34, v29, 0
	v_fmac_f32_e32 v28, v40, v31
	v_fmac_f32_e32 v28, v38, v33
	v_fmac_f32_e32 v28, v43, v35
	v_fmac_f32_e32 v28, v41, v39
	v_fmac_f32_e32 v28, v46, v36
	v_fmac_f32_e32 v28, v44, v42
	v_fmac_f32_e32 v28, v45, v37
	s_nop 1
	v_add_f32_dpp v28, v28, v28 quad_perm:[1,0,3,2] row_mask:0xf bank_mask:0xf bound_ctrl:1
	s_nop 1
	v_add_f32_dpp v28, v28, v28 quad_perm:[2,3,0,1] row_mask:0xf bank_mask:0xf bound_ctrl:1
	s_nop 1
	v_add_f32_dpp v28, v28, v28 row_half_mirror row_mask:0xf bank_mask:0xf bound_ctrl:1
	s_nop 1
	v_add_f32_dpp v28, v28, v28 row_mirror row_mask:0xf bank_mask:0xf bound_ctrl:1
	s_nop 0
	v_readlane_b32 s6, v28, 16
	v_readlane_b32 s5, v28, 0
	s_nop 0
	v_mov_b32_e32 v47, s6
	v_readlane_b32 s6, v28, 48
	v_add_f32_e32 v47, s5, v47
	v_readlane_b32 s5, v28, 32
	v_mov_b32_e32 v28, s6
	s_nop 0
	v_add_f32_e32 v28, s5, v28
	v_add_f32_e32 v28, v47, v28
	v_mul_f32_e32 v28, 0x3b000000, v28
	v_fma_f32 v31, v40, v31, -v28
	v_fma_f32 v29, v34, v29, -v28
	v_mul_f32_e32 v31, v31, v31
	v_fmac_f32_e32 v31, v29, v29
	v_fma_f32 v29, v38, v33, -v28
	v_fmac_f32_e32 v31, v29, v29
	v_fma_f32 v29, v43, v35, -v28
	v_fmac_f32_e32 v31, v29, v29
	v_fma_f32 v29, v41, v39, -v28
	v_fmac_f32_e32 v31, v29, v29
	v_fma_f32 v29, v46, v36, -v28
	v_fmac_f32_e32 v31, v29, v29
	v_fma_f32 v29, v44, v42, -v28
	v_fmac_f32_e32 v31, v29, v29
	v_fma_f32 v29, v45, v37, -v28
	v_fmac_f32_e32 v31, v29, v29
	s_nop 1
	v_add_f32_dpp v29, v31, v31 quad_perm:[1,0,3,2] row_mask:0xf bank_mask:0xf bound_ctrl:1
	s_nop 1
	v_add_f32_dpp v29, v29, v29 quad_perm:[2,3,0,1] row_mask:0xf bank_mask:0xf bound_ctrl:1
	s_nop 1
	v_add_f32_dpp v29, v29, v29 row_half_mirror row_mask:0xf bank_mask:0xf bound_ctrl:1
	s_nop 1
	v_add_f32_dpp v29, v29, v29 row_mirror row_mask:0xf bank_mask:0xf bound_ctrl:1
	s_nop 0
	v_readlane_b32 s44, v29, 0
	v_readlane_b32 s5, v29, 16
	v_readlane_b32 s45, v29, 32
	v_readlane_b32 s6, v29, 48
	s_and_saveexec_b64 s[82:83], s[42:43]
	s_cbranch_execz .LBB0_416
	v_mov_b32_e32 v34, s5
	v_mov_b32_e32 v35, s6
	v_pk_add_f32 v[34:35], s[44:45], v[34:35]
	s_nop 0
	v_add_f32_e32 v29, v34, v35
	v_fmamk_f32 v29, v29, 0x3b000000, v176
	v_mul_f32_e32 v31, 0x4f800000, v29
	v_cmp_gt_f32_e32 vcc, s79, v29
	s_nop 1
	v_cndmask_b32_e32 v29, v29, v31, vcc
	v_sqrt_f32_e32 v31, v29
	s_nop 0
	v_add_u32_e32 v33, -1, v31
	v_fma_f32 v34, -v33, v31, v29
	v_cmp_ge_f32_e64 s[44:45], 0, v34
	v_add_u32_e32 v34, 1, v31
	s_nop 0
	v_cndmask_b32_e64 v33, v31, v33, s[44:45]
	v_fma_f32 v31, -v34, v31, v29
	v_cmp_lt_f32_e64 s[44:45], 0, v31
	s_nop 1
	v_cndmask_b32_e64 v31, v33, v34, s[44:45]
	v_mul_f32_e32 v33, 0x37800000, v31
	v_cndmask_b32_e32 v31, v31, v33, vcc
	v_cmp_class_f32_e32 vcc, v29, v177
	s_nop 1
	v_cndmask_b32_e32 v29, v31, v29, vcc
	v_div_scale_f32 v31, s[6:7], v29, v29, 1.0
	v_rcp_f32_e32 v33, v31
	s_nop 0
	v_fma_f32 v34, -v31, v33, 1.0
	v_fmac_f32_e32 v33, v34, v33
	v_div_scale_f32 v34, vcc, 1.0, v29, 1.0
	v_mul_f32_e32 v35, v34, v33
	v_fma_f32 v36, -v31, v35, v34
	v_fmac_f32_e32 v35, v36, v33
	v_fma_f32 v31, -v31, v35, v34
	v_div_fmas_f32 v31, v31, v33, v35
	v_div_fixup_f32 v29, v31, v29, 1.0
	ds_write_b64 v30, v[28:29] offset:64
.LBB0_416:
	s_or_b64 exec, exec, s[82:83]
	s_waitcnt vmcnt(6)
	v_and_b32_e32 v31, 0xffff0000, v24
	v_lshlrev_b32_e32 v28, 16, v24
	v_mul_f32_e32 v24, v31, v31
	v_lshlrev_b32_e32 v33, 16, v25
	v_fmamk_f32 v24, v24, 0xbdd2d3e8, v245
	v_mul_f32_e32 v34, v33, v33
	v_and_b32_e32 v25, 0xffff0000, v25
	v_mul_f32_e32 v24, v24, v31
	v_fmamk_f32 v34, v34, 0xbdd2d3e8, v245
	v_mul_f32_e32 v35, v25, v25
	v_mul_f32_e32 v34, v34, v33
	v_fmamk_f32 v35, v35, 0xbdd2d3e8, v245
	v_mul_f32_e32 v35, v35, v25
	v_exp_f32_e32 v24, v24
	v_exp_f32_e32 v34, v34
	v_exp_f32_e32 v35, v35
	v_add_f32_e32 v24, 1.0, v24
	v_rcp_f32_e32 v36, v24
	v_add_f32_e32 v24, 1.0, v34
	v_rcp_f32_e32 v34, v24
	v_add_f32_e32 v24, 1.0, v35
	v_lshlrev_b32_e32 v35, 16, v26
	v_mul_f32_e32 v37, v35, v35
	v_and_b32_e32 v26, 0xffff0000, v26
	v_fmamk_f32 v37, v37, 0xbdd2d3e8, v245
	v_mul_f32_e32 v38, v26, v26
	v_mul_f32_e32 v37, v37, v35
	v_fmamk_f32 v38, v38, 0xbdd2d3e8, v245
	v_mul_f32_e32 v38, v38, v26
	v_exp_f32_e32 v37, v37
	v_exp_f32_e32 v38, v38
	v_mul_f32_e32 v29, v28, v28
	v_fmamk_f32 v29, v29, 0xbdd2d3e8, v245
	v_rcp_f32_e32 v39, v24
	v_add_f32_e32 v24, 1.0, v37
	v_mul_f32_e32 v29, v29, v28
	v_rcp_f32_e32 v37, v24
	v_add_f32_e32 v24, 1.0, v38
	v_lshlrev_b32_e32 v38, 16, v27
	v_mul_f32_e32 v40, v38, v38
	v_and_b32_e32 v27, 0xffff0000, v27
	v_fmamk_f32 v40, v40, 0xbdd2d3e8, v245
	v_mul_f32_e32 v41, v27, v27
	v_exp_f32_e32 v29, v29
	v_mul_f32_e32 v40, v40, v38
	v_fmamk_f32 v41, v41, 0xbdd2d3e8, v245
	v_mul_f32_e32 v41, v41, v27
	v_exp_f32_e32 v40, v40
	v_add_f32_e32 v29, 1.0, v29
	v_exp_f32_e32 v41, v41
	v_rcp_f32_e32 v29, v29
	v_rcp_f32_e32 v42, v24
	v_add_f32_e32 v24, 1.0, v40
	v_rcp_f32_e32 v40, v24
	v_add_f32_e32 v24, 1.0, v41
	v_rcp_f32_e32 v41, v24
	v_fma_f32 v24, v29, v28, 0
	v_fmac_f32_e32 v24, v36, v31
	v_fmac_f32_e32 v24, v34, v33
	v_fmac_f32_e32 v24, v39, v25
	v_fmac_f32_e32 v24, v37, v35
	v_fmac_f32_e32 v24, v42, v26
	v_fmac_f32_e32 v24, v40, v38
	v_fmac_f32_e32 v24, v41, v27
	s_nop 1
	v_add_f32_dpp v24, v24, v24 quad_perm:[1,0,3,2] row_mask:0xf bank_mask:0xf bound_ctrl:1
	s_nop 1
	v_add_f32_dpp v24, v24, v24 quad_perm:[2,3,0,1] row_mask:0xf bank_mask:0xf bound_ctrl:1
	s_nop 1
	v_add_f32_dpp v24, v24, v24 row_half_mirror row_mask:0xf bank_mask:0xf bound_ctrl:1
	s_nop 1
	v_add_f32_dpp v24, v24, v24 row_mirror row_mask:0xf bank_mask:0xf bound_ctrl:1
	s_nop 0
	v_readlane_b32 s6, v24, 16
	v_readlane_b32 s5, v24, 0
	s_nop 0
	v_mov_b32_e32 v43, s6
	v_readlane_b32 s6, v24, 48
	v_add_f32_e32 v43, s5, v43
	v_readlane_b32 s5, v24, 32
	v_mov_b32_e32 v24, s6
	s_nop 0
	v_add_f32_e32 v24, s5, v24
	v_add_f32_e32 v24, v43, v24
	v_mul_f32_e32 v24, 0x3b000000, v24
	v_fma_f32 v28, v29, v28, -v24
	v_fma_f32 v29, v36, v31, -v24
	v_mul_f32_e32 v29, v29, v29
	v_fmac_f32_e32 v29, v28, v28
	v_fma_f32 v28, v34, v33, -v24
	v_fmac_f32_e32 v29, v28, v28
	v_fma_f32 v25, v39, v25, -v24
	v_fmac_f32_e32 v29, v25, v25
	v_fma_f32 v25, v37, v35, -v24
	v_fmac_f32_e32 v29, v25, v25
	v_fma_f32 v25, v42, v26, -v24
	v_fmac_f32_e32 v29, v25, v25
	v_fma_f32 v25, v40, v38, -v24
	v_fmac_f32_e32 v29, v25, v25
	v_fma_f32 v25, v41, v27, -v24
	v_fmac_f32_e32 v29, v25, v25
	s_nop 1
	v_add_f32_dpp v25, v29, v29 quad_perm:[1,0,3,2] row_mask:0xf bank_mask:0xf bound_ctrl:1
	s_nop 1
	v_add_f32_dpp v25, v25, v25 quad_perm:[2,3,0,1] row_mask:0xf bank_mask:0xf bound_ctrl:1
	s_nop 1
	v_add_f32_dpp v25, v25, v25 row_half_mirror row_mask:0xf bank_mask:0xf bound_ctrl:1
	s_nop 1
	v_add_f32_dpp v25, v25, v25 row_mirror row_mask:0xf bank_mask:0xf bound_ctrl:1
	s_nop 0
	v_readlane_b32 s44, v25, 0
	v_readlane_b32 s5, v25, 16
	v_readlane_b32 s45, v25, 32
	v_readlane_b32 s6, v25, 48
	s_and_saveexec_b64 s[82:83], s[42:43]
	s_cbranch_execz .LBB0_418
	v_mov_b32_e32 v26, s5
	v_mov_b32_e32 v27, s6
	v_pk_add_f32 v[26:27], s[44:45], v[26:27]
	s_nop 0
	v_add_f32_e32 v25, v26, v27
	v_fmamk_f32 v25, v25, 0x3b000000, v176
	v_mul_f32_e32 v26, 0x4f800000, v25
	v_cmp_gt_f32_e32 vcc, s79, v25
	s_nop 1
	v_cndmask_b32_e32 v25, v25, v26, vcc
	v_sqrt_f32_e32 v26, v25
	s_nop 0
	v_add_u32_e32 v27, -1, v26
	v_fma_f32 v28, -v27, v26, v25
	v_cmp_ge_f32_e64 s[44:45], 0, v28
	v_add_u32_e32 v28, 1, v26
	s_nop 0
	v_cndmask_b32_e64 v27, v26, v27, s[44:45]
	v_fma_f32 v26, -v28, v26, v25
	v_cmp_lt_f32_e64 s[44:45], 0, v26
	s_nop 1
	v_cndmask_b32_e64 v26, v27, v28, s[44:45]
	v_mul_f32_e32 v27, 0x37800000, v26
	v_cndmask_b32_e32 v26, v26, v27, vcc
	v_cmp_class_f32_e32 vcc, v25, v177
	s_nop 1
	v_cndmask_b32_e32 v25, v26, v25, vcc
	v_div_scale_f32 v26, s[6:7], v25, v25, 1.0
	v_rcp_f32_e32 v27, v26
	s_nop 0
	v_fma_f32 v28, -v26, v27, 1.0
	v_fmac_f32_e32 v27, v28, v27
	v_div_scale_f32 v28, vcc, 1.0, v25, 1.0
	v_mul_f32_e32 v29, v28, v27
	v_fma_f32 v31, -v26, v29, v28
	v_fmac_f32_e32 v29, v31, v27
	v_fma_f32 v26, -v26, v29, v28
	v_div_fmas_f32 v26, v26, v27, v29
	v_div_fixup_f32 v25, v26, v25, 1.0
	ds_write_b64 v30, v[24:25] offset:72
.LBB0_418:
	s_or_b64 exec, exec, s[82:83]
	s_waitcnt vmcnt(5)
	v_and_b32_e32 v26, 0xffff0000, v20
	v_lshlrev_b32_e32 v24, 16, v20
	v_mul_f32_e32 v20, v26, v26
	v_lshlrev_b32_e32 v27, 16, v21
	v_fmamk_f32 v20, v20, 0xbdd2d3e8, v245
	v_mul_f32_e32 v28, v27, v27
	v_and_b32_e32 v21, 0xffff0000, v21
	v_mul_f32_e32 v20, v20, v26
	v_fmamk_f32 v28, v28, 0xbdd2d3e8, v245
	v_mul_f32_e32 v29, v21, v21
	v_mul_f32_e32 v28, v28, v27
	v_fmamk_f32 v29, v29, 0xbdd2d3e8, v245
	v_mul_f32_e32 v29, v29, v21
	v_exp_f32_e32 v20, v20
	v_exp_f32_e32 v28, v28
	v_exp_f32_e32 v29, v29
	v_add_f32_e32 v20, 1.0, v20
	v_rcp_f32_e32 v31, v20
	v_add_f32_e32 v20, 1.0, v28
	v_rcp_f32_e32 v28, v20
	v_add_f32_e32 v20, 1.0, v29
	v_lshlrev_b32_e32 v29, 16, v22
	v_mul_f32_e32 v33, v29, v29
	v_and_b32_e32 v22, 0xffff0000, v22
	v_fmamk_f32 v33, v33, 0xbdd2d3e8, v245
	v_mul_f32_e32 v34, v22, v22
	v_mul_f32_e32 v33, v33, v29
	v_fmamk_f32 v34, v34, 0xbdd2d3e8, v245
	v_mul_f32_e32 v34, v34, v22
	v_exp_f32_e32 v33, v33
	v_exp_f32_e32 v34, v34
	v_mul_f32_e32 v25, v24, v24
	v_fmamk_f32 v25, v25, 0xbdd2d3e8, v245
	v_rcp_f32_e32 v35, v20
	v_add_f32_e32 v20, 1.0, v33
	v_mul_f32_e32 v25, v25, v24
	v_rcp_f32_e32 v33, v20
	v_add_f32_e32 v20, 1.0, v34
	v_lshlrev_b32_e32 v34, 16, v23
	v_mul_f32_e32 v36, v34, v34
	v_and_b32_e32 v23, 0xffff0000, v23
	v_fmamk_f32 v36, v36, 0xbdd2d3e8, v245
	v_mul_f32_e32 v37, v23, v23
	v_exp_f32_e32 v25, v25
	v_mul_f32_e32 v36, v36, v34
	v_fmamk_f32 v37, v37, 0xbdd2d3e8, v245
	v_mul_f32_e32 v37, v37, v23
	v_exp_f32_e32 v36, v36
	v_add_f32_e32 v25, 1.0, v25
	v_exp_f32_e32 v37, v37
	v_rcp_f32_e32 v25, v25
	v_rcp_f32_e32 v38, v20
	v_add_f32_e32 v20, 1.0, v36
	v_rcp_f32_e32 v36, v20
	v_add_f32_e32 v20, 1.0, v37
	v_rcp_f32_e32 v37, v20
	v_fma_f32 v20, v25, v24, 0
	v_fmac_f32_e32 v20, v31, v26
	v_fmac_f32_e32 v20, v28, v27
	v_fmac_f32_e32 v20, v35, v21
	v_fmac_f32_e32 v20, v33, v29
	v_fmac_f32_e32 v20, v38, v22
	v_fmac_f32_e32 v20, v36, v34
	v_fmac_f32_e32 v20, v37, v23
	s_nop 1
	v_add_f32_dpp v20, v20, v20 quad_perm:[1,0,3,2] row_mask:0xf bank_mask:0xf bound_ctrl:1
	s_nop 1
	v_add_f32_dpp v20, v20, v20 quad_perm:[2,3,0,1] row_mask:0xf bank_mask:0xf bound_ctrl:1
	s_nop 1
	v_add_f32_dpp v20, v20, v20 row_half_mirror row_mask:0xf bank_mask:0xf bound_ctrl:1
	s_nop 1
	v_add_f32_dpp v20, v20, v20 row_mirror row_mask:0xf bank_mask:0xf bound_ctrl:1
	s_nop 0
	v_readlane_b32 s6, v20, 16
	v_readlane_b32 s5, v20, 0
	s_nop 0
	v_mov_b32_e32 v39, s6
	v_readlane_b32 s6, v20, 48
	v_add_f32_e32 v39, s5, v39
	v_readlane_b32 s5, v20, 32
	v_mov_b32_e32 v20, s6
	s_nop 0
	v_add_f32_e32 v20, s5, v20
	v_add_f32_e32 v20, v39, v20
	v_mul_f32_e32 v20, 0x3b000000, v20
	v_fma_f32 v24, v25, v24, -v20
	v_fma_f32 v25, v31, v26, -v20
	v_mul_f32_e32 v25, v25, v25
	v_fmac_f32_e32 v25, v24, v24
	v_fma_f32 v24, v28, v27, -v20
	v_fmac_f32_e32 v25, v24, v24
	v_fma_f32 v21, v35, v21, -v20
	v_fmac_f32_e32 v25, v21, v21
	v_fma_f32 v21, v33, v29, -v20
	v_fmac_f32_e32 v25, v21, v21
	v_fma_f32 v21, v38, v22, -v20
	v_fmac_f32_e32 v25, v21, v21
	v_fma_f32 v21, v36, v34, -v20
	v_fmac_f32_e32 v25, v21, v21
	v_fma_f32 v21, v37, v23, -v20
	v_fmac_f32_e32 v25, v21, v21
	s_nop 1
	v_add_f32_dpp v21, v25, v25 quad_perm:[1,0,3,2] row_mask:0xf bank_mask:0xf bound_ctrl:1
	s_nop 1
	v_add_f32_dpp v21, v21, v21 quad_perm:[2,3,0,1] row_mask:0xf bank_mask:0xf bound_ctrl:1
	s_nop 1
	v_add_f32_dpp v21, v21, v21 row_half_mirror row_mask:0xf bank_mask:0xf bound_ctrl:1
	s_nop 1
	v_add_f32_dpp v21, v21, v21 row_mirror row_mask:0xf bank_mask:0xf bound_ctrl:1
	s_nop 0
	v_readlane_b32 s44, v21, 0
	v_readlane_b32 s5, v21, 16
	v_readlane_b32 s45, v21, 32
	v_readlane_b32 s6, v21, 48
	s_and_saveexec_b64 s[82:83], s[42:43]
	s_cbranch_execz .LBB0_420
	v_mov_b32_e32 v22, s5
	v_mov_b32_e32 v23, s6
	v_pk_add_f32 v[22:23], s[44:45], v[22:23]
	s_nop 0
	v_add_f32_e32 v21, v22, v23
	v_fmamk_f32 v21, v21, 0x3b000000, v176
	v_mul_f32_e32 v22, 0x4f800000, v21
	v_cmp_gt_f32_e32 vcc, s79, v21
	s_nop 1
	v_cndmask_b32_e32 v21, v21, v22, vcc
	v_sqrt_f32_e32 v22, v21
	s_nop 0
	v_add_u32_e32 v23, -1, v22
	v_fma_f32 v24, -v23, v22, v21
	v_cmp_ge_f32_e64 s[44:45], 0, v24
	v_add_u32_e32 v24, 1, v22
	s_nop 0
	v_cndmask_b32_e64 v23, v22, v23, s[44:45]
	v_fma_f32 v22, -v24, v22, v21
	v_cmp_lt_f32_e64 s[44:45], 0, v22
	s_nop 1
	v_cndmask_b32_e64 v22, v23, v24, s[44:45]
	v_mul_f32_e32 v23, 0x37800000, v22
	v_cndmask_b32_e32 v22, v22, v23, vcc
	v_cmp_class_f32_e32 vcc, v21, v177
	s_nop 1
	v_cndmask_b32_e32 v21, v22, v21, vcc
	v_div_scale_f32 v22, s[6:7], v21, v21, 1.0
	v_rcp_f32_e32 v23, v22
	s_nop 0
	v_fma_f32 v24, -v22, v23, 1.0
	v_fmac_f32_e32 v23, v24, v23
	v_div_scale_f32 v24, vcc, 1.0, v21, 1.0
	v_mul_f32_e32 v25, v24, v23
	v_fma_f32 v26, -v22, v25, v24
	v_fmac_f32_e32 v25, v26, v23
	v_fma_f32 v22, -v22, v25, v24
	v_div_fmas_f32 v22, v22, v23, v25
	v_div_fixup_f32 v21, v22, v21, 1.0
	ds_write_b64 v30, v[20:21] offset:80
.LBB0_420:
	s_or_b64 exec, exec, s[82:83]
	s_waitcnt vmcnt(4)
	v_and_b32_e32 v22, 0xffff0000, v16
	v_lshlrev_b32_e32 v20, 16, v16
	v_mul_f32_e32 v16, v22, v22
	v_lshlrev_b32_e32 v23, 16, v17
	v_fmamk_f32 v16, v16, 0xbdd2d3e8, v245
	v_mul_f32_e32 v24, v23, v23
	v_and_b32_e32 v17, 0xffff0000, v17
	v_mul_f32_e32 v16, v16, v22
	v_fmamk_f32 v24, v24, 0xbdd2d3e8, v245
	v_mul_f32_e32 v25, v17, v17
	v_mul_f32_e32 v24, v24, v23
	v_fmamk_f32 v25, v25, 0xbdd2d3e8, v245
	v_mul_f32_e32 v25, v25, v17
	v_exp_f32_e32 v16, v16
	v_exp_f32_e32 v24, v24
	v_exp_f32_e32 v25, v25
	v_add_f32_e32 v16, 1.0, v16
	v_rcp_f32_e32 v26, v16
	v_add_f32_e32 v16, 1.0, v24
	v_rcp_f32_e32 v24, v16
	v_add_f32_e32 v16, 1.0, v25
	v_lshlrev_b32_e32 v25, 16, v18
	v_mul_f32_e32 v27, v25, v25
	v_and_b32_e32 v18, 0xffff0000, v18
	v_fmamk_f32 v27, v27, 0xbdd2d3e8, v245
	v_mul_f32_e32 v28, v18, v18
	v_mul_f32_e32 v27, v27, v25
	v_fmamk_f32 v28, v28, 0xbdd2d3e8, v245
	v_mul_f32_e32 v28, v28, v18
	v_exp_f32_e32 v27, v27
	v_exp_f32_e32 v28, v28
	v_mul_f32_e32 v21, v20, v20
	v_fmamk_f32 v21, v21, 0xbdd2d3e8, v245
	v_rcp_f32_e32 v29, v16
	v_add_f32_e32 v16, 1.0, v27
	v_mul_f32_e32 v21, v21, v20
	v_rcp_f32_e32 v27, v16
	v_add_f32_e32 v16, 1.0, v28
	v_lshlrev_b32_e32 v28, 16, v19
	v_mul_f32_e32 v31, v28, v28
	v_and_b32_e32 v19, 0xffff0000, v19
	v_fmamk_f32 v31, v31, 0xbdd2d3e8, v245
	v_mul_f32_e32 v33, v19, v19
	v_exp_f32_e32 v21, v21
	v_mul_f32_e32 v31, v31, v28
	v_fmamk_f32 v33, v33, 0xbdd2d3e8, v245
	v_mul_f32_e32 v33, v33, v19
	v_exp_f32_e32 v31, v31
	v_add_f32_e32 v21, 1.0, v21
	v_exp_f32_e32 v33, v33
	v_rcp_f32_e32 v21, v21
	v_rcp_f32_e32 v34, v16
	v_add_f32_e32 v16, 1.0, v31
	v_rcp_f32_e32 v31, v16
	v_add_f32_e32 v16, 1.0, v33
	v_rcp_f32_e32 v33, v16
	v_fma_f32 v16, v21, v20, 0
	v_fmac_f32_e32 v16, v26, v22
	v_fmac_f32_e32 v16, v24, v23
	v_fmac_f32_e32 v16, v29, v17
	v_fmac_f32_e32 v16, v27, v25
	v_fmac_f32_e32 v16, v34, v18
	v_fmac_f32_e32 v16, v31, v28
	v_fmac_f32_e32 v16, v33, v19
	s_nop 1
	v_add_f32_dpp v16, v16, v16 quad_perm:[1,0,3,2] row_mask:0xf bank_mask:0xf bound_ctrl:1
	s_nop 1
	v_add_f32_dpp v16, v16, v16 quad_perm:[2,3,0,1] row_mask:0xf bank_mask:0xf bound_ctrl:1
	s_nop 1
	v_add_f32_dpp v16, v16, v16 row_half_mirror row_mask:0xf bank_mask:0xf bound_ctrl:1
	s_nop 1
	v_add_f32_dpp v16, v16, v16 row_mirror row_mask:0xf bank_mask:0xf bound_ctrl:1
	s_nop 0
	v_readlane_b32 s6, v16, 16
	v_readlane_b32 s5, v16, 0
	s_nop 0
	v_mov_b32_e32 v35, s6
	v_readlane_b32 s6, v16, 48
	v_add_f32_e32 v35, s5, v35
	v_readlane_b32 s5, v16, 32
	v_mov_b32_e32 v16, s6
	s_nop 0
	v_add_f32_e32 v16, s5, v16
	v_add_f32_e32 v16, v35, v16
	v_mul_f32_e32 v16, 0x3b000000, v16
	v_fma_f32 v20, v21, v20, -v16
	v_fma_f32 v21, v26, v22, -v16
	v_mul_f32_e32 v21, v21, v21
	v_fmac_f32_e32 v21, v20, v20
	v_fma_f32 v20, v24, v23, -v16
	v_fmac_f32_e32 v21, v20, v20
	v_fma_f32 v17, v29, v17, -v16
	v_fmac_f32_e32 v21, v17, v17
	v_fma_f32 v17, v27, v25, -v16
	v_fmac_f32_e32 v21, v17, v17
	v_fma_f32 v17, v34, v18, -v16
	v_fmac_f32_e32 v21, v17, v17
	v_fma_f32 v17, v31, v28, -v16
	v_fmac_f32_e32 v21, v17, v17
	v_fma_f32 v17, v33, v19, -v16
	v_fmac_f32_e32 v21, v17, v17
	s_nop 1
	v_add_f32_dpp v17, v21, v21 quad_perm:[1,0,3,2] row_mask:0xf bank_mask:0xf bound_ctrl:1
	s_nop 1
	v_add_f32_dpp v17, v17, v17 quad_perm:[2,3,0,1] row_mask:0xf bank_mask:0xf bound_ctrl:1
	s_nop 1
	v_add_f32_dpp v17, v17, v17 row_half_mirror row_mask:0xf bank_mask:0xf bound_ctrl:1
	s_nop 1
	v_add_f32_dpp v17, v17, v17 row_mirror row_mask:0xf bank_mask:0xf bound_ctrl:1
	s_nop 0
	v_readlane_b32 s44, v17, 0
	v_readlane_b32 s5, v17, 16
	v_readlane_b32 s45, v17, 32
	v_readlane_b32 s6, v17, 48
	s_and_saveexec_b64 s[82:83], s[42:43]
	s_cbranch_execz .LBB0_422
	v_mov_b32_e32 v18, s5
	v_mov_b32_e32 v19, s6
	v_pk_add_f32 v[18:19], s[44:45], v[18:19]
	s_nop 0
	v_add_f32_e32 v17, v18, v19
	v_fmamk_f32 v17, v17, 0x3b000000, v176
	v_mul_f32_e32 v18, 0x4f800000, v17
	v_cmp_gt_f32_e32 vcc, s79, v17
	s_nop 1
	v_cndmask_b32_e32 v17, v17, v18, vcc
	v_sqrt_f32_e32 v18, v17
	s_nop 0
	v_add_u32_e32 v19, -1, v18
	v_fma_f32 v20, -v19, v18, v17
	v_cmp_ge_f32_e64 s[44:45], 0, v20
	v_add_u32_e32 v20, 1, v18
	s_nop 0
	v_cndmask_b32_e64 v19, v18, v19, s[44:45]
	v_fma_f32 v18, -v20, v18, v17
	v_cmp_lt_f32_e64 s[44:45], 0, v18
	s_nop 1
	v_cndmask_b32_e64 v18, v19, v20, s[44:45]
	v_mul_f32_e32 v19, 0x37800000, v18
	v_cndmask_b32_e32 v18, v18, v19, vcc
	v_cmp_class_f32_e32 vcc, v17, v177
	s_nop 1
	v_cndmask_b32_e32 v17, v18, v17, vcc
	v_div_scale_f32 v18, s[6:7], v17, v17, 1.0
	v_rcp_f32_e32 v19, v18
	s_nop 0
	v_fma_f32 v20, -v18, v19, 1.0
	v_fmac_f32_e32 v19, v20, v19
	v_div_scale_f32 v20, vcc, 1.0, v17, 1.0
	v_mul_f32_e32 v21, v20, v19
	v_fma_f32 v22, -v18, v21, v20
	v_fmac_f32_e32 v21, v22, v19
	v_fma_f32 v18, -v18, v21, v20
	v_div_fmas_f32 v18, v18, v19, v21
	v_div_fixup_f32 v17, v18, v17, 1.0
	ds_write_b64 v30, v[16:17] offset:88
.LBB0_422:
	s_or_b64 exec, exec, s[82:83]
	s_waitcnt vmcnt(3)
	v_and_b32_e32 v18, 0xffff0000, v12
	v_lshlrev_b32_e32 v16, 16, v12
	v_mul_f32_e32 v12, v18, v18
	v_lshlrev_b32_e32 v19, 16, v13
	v_fmamk_f32 v12, v12, 0xbdd2d3e8, v245
	v_mul_f32_e32 v20, v19, v19
	v_and_b32_e32 v13, 0xffff0000, v13
	v_mul_f32_e32 v12, v12, v18
	v_fmamk_f32 v20, v20, 0xbdd2d3e8, v245
	v_mul_f32_e32 v21, v13, v13
	v_mul_f32_e32 v20, v20, v19
	v_fmamk_f32 v21, v21, 0xbdd2d3e8, v245
	v_mul_f32_e32 v21, v21, v13
	v_exp_f32_e32 v12, v12
	v_exp_f32_e32 v20, v20
	v_exp_f32_e32 v21, v21
	v_add_f32_e32 v12, 1.0, v12
	v_rcp_f32_e32 v22, v12
	v_add_f32_e32 v12, 1.0, v20
	v_rcp_f32_e32 v20, v12
	v_add_f32_e32 v12, 1.0, v21
	v_lshlrev_b32_e32 v21, 16, v14
	v_mul_f32_e32 v23, v21, v21
	v_and_b32_e32 v14, 0xffff0000, v14
	v_fmamk_f32 v23, v23, 0xbdd2d3e8, v245
	v_mul_f32_e32 v24, v14, v14
	v_mul_f32_e32 v23, v23, v21
	v_fmamk_f32 v24, v24, 0xbdd2d3e8, v245
	v_mul_f32_e32 v24, v24, v14
	v_exp_f32_e32 v23, v23
	v_exp_f32_e32 v24, v24
	v_mul_f32_e32 v17, v16, v16
	v_fmamk_f32 v17, v17, 0xbdd2d3e8, v245
	v_rcp_f32_e32 v25, v12
	v_add_f32_e32 v12, 1.0, v23
	v_mul_f32_e32 v17, v17, v16
	v_rcp_f32_e32 v23, v12
	v_add_f32_e32 v12, 1.0, v24
	v_lshlrev_b32_e32 v24, 16, v15
	v_mul_f32_e32 v26, v24, v24
	v_and_b32_e32 v15, 0xffff0000, v15
	v_fmamk_f32 v26, v26, 0xbdd2d3e8, v245
	v_mul_f32_e32 v27, v15, v15
	v_exp_f32_e32 v17, v17
	v_mul_f32_e32 v26, v26, v24
	v_fmamk_f32 v27, v27, 0xbdd2d3e8, v245
	v_mul_f32_e32 v27, v27, v15
	v_exp_f32_e32 v26, v26
	v_add_f32_e32 v17, 1.0, v17
	v_exp_f32_e32 v27, v27
	v_rcp_f32_e32 v17, v17
	v_rcp_f32_e32 v28, v12
	v_add_f32_e32 v12, 1.0, v26
	v_rcp_f32_e32 v26, v12
	v_add_f32_e32 v12, 1.0, v27
	v_rcp_f32_e32 v27, v12
	v_fma_f32 v12, v17, v16, 0
	v_fmac_f32_e32 v12, v22, v18
	v_fmac_f32_e32 v12, v20, v19
	v_fmac_f32_e32 v12, v25, v13
	v_fmac_f32_e32 v12, v23, v21
	v_fmac_f32_e32 v12, v28, v14
	v_fmac_f32_e32 v12, v26, v24
	v_fmac_f32_e32 v12, v27, v15
	s_nop 1
	v_add_f32_dpp v12, v12, v12 quad_perm:[1,0,3,2] row_mask:0xf bank_mask:0xf bound_ctrl:1
	s_nop 1
	v_add_f32_dpp v12, v12, v12 quad_perm:[2,3,0,1] row_mask:0xf bank_mask:0xf bound_ctrl:1
	s_nop 1
	v_add_f32_dpp v12, v12, v12 row_half_mirror row_mask:0xf bank_mask:0xf bound_ctrl:1
	s_nop 1
	v_add_f32_dpp v12, v12, v12 row_mirror row_mask:0xf bank_mask:0xf bound_ctrl:1
	s_nop 0
	v_readlane_b32 s6, v12, 16
	v_readlane_b32 s5, v12, 0
	s_nop 0
	v_mov_b32_e32 v29, s6
	v_readlane_b32 s6, v12, 48
	v_add_f32_e32 v29, s5, v29
	v_readlane_b32 s5, v12, 32
	v_mov_b32_e32 v12, s6
	s_nop 0
	v_add_f32_e32 v12, s5, v12
	v_add_f32_e32 v12, v29, v12
	v_mul_f32_e32 v12, 0x3b000000, v12
	v_fma_f32 v16, v17, v16, -v12
	v_fma_f32 v17, v22, v18, -v12
	v_mul_f32_e32 v17, v17, v17
	v_fmac_f32_e32 v17, v16, v16
	v_fma_f32 v16, v20, v19, -v12
	v_fmac_f32_e32 v17, v16, v16
	v_fma_f32 v13, v25, v13, -v12
	v_fmac_f32_e32 v17, v13, v13
	v_fma_f32 v13, v23, v21, -v12
	v_fmac_f32_e32 v17, v13, v13
	v_fma_f32 v13, v28, v14, -v12
	v_fmac_f32_e32 v17, v13, v13
	v_fma_f32 v13, v26, v24, -v12
	v_fmac_f32_e32 v17, v13, v13
	v_fma_f32 v13, v27, v15, -v12
	v_fmac_f32_e32 v17, v13, v13
	s_nop 1
	v_add_f32_dpp v13, v17, v17 quad_perm:[1,0,3,2] row_mask:0xf bank_mask:0xf bound_ctrl:1
	s_nop 1
	v_add_f32_dpp v13, v13, v13 quad_perm:[2,3,0,1] row_mask:0xf bank_mask:0xf bound_ctrl:1
	s_nop 1
	v_add_f32_dpp v13, v13, v13 row_half_mirror row_mask:0xf bank_mask:0xf bound_ctrl:1
	s_nop 1
	v_add_f32_dpp v13, v13, v13 row_mirror row_mask:0xf bank_mask:0xf bound_ctrl:1
	s_nop 0
	v_readlane_b32 s44, v13, 0
	v_readlane_b32 s5, v13, 16
	v_readlane_b32 s45, v13, 32
	v_readlane_b32 s6, v13, 48
	s_and_saveexec_b64 s[82:83], s[42:43]
	s_cbranch_execz .LBB0_424
	v_mov_b32_e32 v14, s5
	v_mov_b32_e32 v15, s6
	v_pk_add_f32 v[14:15], s[44:45], v[14:15]
	s_nop 0
	v_add_f32_e32 v13, v14, v15
	v_fmamk_f32 v13, v13, 0x3b000000, v176
	v_mul_f32_e32 v14, 0x4f800000, v13
	v_cmp_gt_f32_e32 vcc, s79, v13
	s_nop 1
	v_cndmask_b32_e32 v13, v13, v14, vcc
	v_sqrt_f32_e32 v14, v13
	s_nop 0
	v_add_u32_e32 v15, -1, v14
	v_fma_f32 v16, -v15, v14, v13
	v_cmp_ge_f32_e64 s[44:45], 0, v16
	v_add_u32_e32 v16, 1, v14
	s_nop 0
	v_cndmask_b32_e64 v15, v14, v15, s[44:45]
	v_fma_f32 v14, -v16, v14, v13
	v_cmp_lt_f32_e64 s[44:45], 0, v14
	s_nop 1
	v_cndmask_b32_e64 v14, v15, v16, s[44:45]
	v_mul_f32_e32 v15, 0x37800000, v14
	v_cndmask_b32_e32 v14, v14, v15, vcc
	v_cmp_class_f32_e32 vcc, v13, v177
	s_nop 1
	v_cndmask_b32_e32 v13, v14, v13, vcc
	v_div_scale_f32 v14, s[6:7], v13, v13, 1.0
	v_rcp_f32_e32 v15, v14
	s_nop 0
	v_fma_f32 v16, -v14, v15, 1.0
	v_fmac_f32_e32 v15, v16, v15
	v_div_scale_f32 v16, vcc, 1.0, v13, 1.0
	v_mul_f32_e32 v17, v16, v15
	v_fma_f32 v18, -v14, v17, v16
	v_fmac_f32_e32 v17, v18, v15
	v_fma_f32 v14, -v14, v17, v16
	v_div_fmas_f32 v14, v14, v15, v17
	v_div_fixup_f32 v13, v14, v13, 1.0
	ds_write_b64 v30, v[12:13] offset:96
.LBB0_424:
	s_or_b64 exec, exec, s[82:83]
	s_waitcnt vmcnt(2)
	v_and_b32_e32 v14, 0xffff0000, v8
	v_lshlrev_b32_e32 v12, 16, v8
	v_mul_f32_e32 v8, v14, v14
	v_lshlrev_b32_e32 v15, 16, v9
	v_fmamk_f32 v8, v8, 0xbdd2d3e8, v245
	v_mul_f32_e32 v16, v15, v15
	v_and_b32_e32 v9, 0xffff0000, v9
	v_mul_f32_e32 v8, v8, v14
	v_fmamk_f32 v16, v16, 0xbdd2d3e8, v245
	v_mul_f32_e32 v17, v9, v9
	v_mul_f32_e32 v16, v16, v15
	v_fmamk_f32 v17, v17, 0xbdd2d3e8, v245
	v_mul_f32_e32 v17, v17, v9
	v_exp_f32_e32 v8, v8
	v_exp_f32_e32 v16, v16
	v_exp_f32_e32 v17, v17
	v_add_f32_e32 v8, 1.0, v8
	v_rcp_f32_e32 v18, v8
	v_add_f32_e32 v8, 1.0, v16
	v_rcp_f32_e32 v16, v8
	v_add_f32_e32 v8, 1.0, v17
	v_lshlrev_b32_e32 v17, 16, v10
	v_mul_f32_e32 v19, v17, v17
	v_and_b32_e32 v10, 0xffff0000, v10
	v_fmamk_f32 v19, v19, 0xbdd2d3e8, v245
	v_mul_f32_e32 v20, v10, v10
	v_mul_f32_e32 v19, v19, v17
	v_fmamk_f32 v20, v20, 0xbdd2d3e8, v245
	v_mul_f32_e32 v20, v20, v10
	v_exp_f32_e32 v19, v19
	v_exp_f32_e32 v20, v20
	v_mul_f32_e32 v13, v12, v12
	v_fmamk_f32 v13, v13, 0xbdd2d3e8, v245
	v_rcp_f32_e32 v21, v8
	v_add_f32_e32 v8, 1.0, v19
	v_mul_f32_e32 v13, v13, v12
	v_rcp_f32_e32 v19, v8
	v_add_f32_e32 v8, 1.0, v20
	v_lshlrev_b32_e32 v20, 16, v11
	v_mul_f32_e32 v22, v20, v20
	v_and_b32_e32 v11, 0xffff0000, v11
	v_fmamk_f32 v22, v22, 0xbdd2d3e8, v245
	v_mul_f32_e32 v23, v11, v11
	v_exp_f32_e32 v13, v13
	v_mul_f32_e32 v22, v22, v20
	v_fmamk_f32 v23, v23, 0xbdd2d3e8, v245
	v_mul_f32_e32 v23, v23, v11
	v_exp_f32_e32 v22, v22
	v_add_f32_e32 v13, 1.0, v13
	v_exp_f32_e32 v23, v23
	v_rcp_f32_e32 v13, v13
	v_rcp_f32_e32 v24, v8
	v_add_f32_e32 v8, 1.0, v22
	v_rcp_f32_e32 v22, v8
	v_add_f32_e32 v8, 1.0, v23
	v_rcp_f32_e32 v23, v8
	v_fma_f32 v8, v13, v12, 0
	v_fmac_f32_e32 v8, v18, v14
	v_fmac_f32_e32 v8, v16, v15
	v_fmac_f32_e32 v8, v21, v9
	v_fmac_f32_e32 v8, v19, v17
	v_fmac_f32_e32 v8, v24, v10
	v_fmac_f32_e32 v8, v22, v20
	v_fmac_f32_e32 v8, v23, v11
	s_nop 1
	v_add_f32_dpp v8, v8, v8 quad_perm:[1,0,3,2] row_mask:0xf bank_mask:0xf bound_ctrl:1
	s_nop 1
	v_add_f32_dpp v8, v8, v8 quad_perm:[2,3,0,1] row_mask:0xf bank_mask:0xf bound_ctrl:1
	s_nop 1
	v_add_f32_dpp v8, v8, v8 row_half_mirror row_mask:0xf bank_mask:0xf bound_ctrl:1
	s_nop 1
	v_add_f32_dpp v8, v8, v8 row_mirror row_mask:0xf bank_mask:0xf bound_ctrl:1
	s_nop 0
	v_readlane_b32 s6, v8, 16
	v_readlane_b32 s5, v8, 0
	s_nop 0
	v_mov_b32_e32 v25, s6
	v_readlane_b32 s6, v8, 48
	v_add_f32_e32 v25, s5, v25
	v_readlane_b32 s5, v8, 32
	v_mov_b32_e32 v8, s6
	s_nop 0
	v_add_f32_e32 v8, s5, v8
	v_add_f32_e32 v8, v25, v8
	v_mul_f32_e32 v8, 0x3b000000, v8
	v_fma_f32 v12, v13, v12, -v8
	v_fma_f32 v13, v18, v14, -v8
	v_mul_f32_e32 v13, v13, v13
	v_fmac_f32_e32 v13, v12, v12
	v_fma_f32 v12, v16, v15, -v8
	v_fmac_f32_e32 v13, v12, v12
	v_fma_f32 v9, v21, v9, -v8
	v_fmac_f32_e32 v13, v9, v9
	v_fma_f32 v9, v19, v17, -v8
	v_fmac_f32_e32 v13, v9, v9
	v_fma_f32 v9, v24, v10, -v8
	v_fmac_f32_e32 v13, v9, v9
	v_fma_f32 v9, v22, v20, -v8
	v_fmac_f32_e32 v13, v9, v9
	v_fma_f32 v9, v23, v11, -v8
	v_fmac_f32_e32 v13, v9, v9
	s_nop 1
	v_add_f32_dpp v9, v13, v13 quad_perm:[1,0,3,2] row_mask:0xf bank_mask:0xf bound_ctrl:1
	s_nop 1
	v_add_f32_dpp v9, v9, v9 quad_perm:[2,3,0,1] row_mask:0xf bank_mask:0xf bound_ctrl:1
	s_nop 1
	v_add_f32_dpp v9, v9, v9 row_half_mirror row_mask:0xf bank_mask:0xf bound_ctrl:1
	s_nop 1
	v_add_f32_dpp v9, v9, v9 row_mirror row_mask:0xf bank_mask:0xf bound_ctrl:1
	s_nop 0
	v_readlane_b32 s44, v9, 0
	v_readlane_b32 s5, v9, 16
	v_readlane_b32 s45, v9, 32
	v_readlane_b32 s6, v9, 48
	s_and_saveexec_b64 s[82:83], s[42:43]
	s_cbranch_execz .LBB0_426
	v_mov_b32_e32 v10, s5
	v_mov_b32_e32 v11, s6
	v_pk_add_f32 v[10:11], s[44:45], v[10:11]
	s_nop 0
	v_add_f32_e32 v9, v10, v11
	v_fmamk_f32 v9, v9, 0x3b000000, v176
	v_mul_f32_e32 v10, 0x4f800000, v9
	v_cmp_gt_f32_e32 vcc, s79, v9
	s_nop 1
	v_cndmask_b32_e32 v9, v9, v10, vcc
	v_sqrt_f32_e32 v10, v9
	s_nop 0
	v_add_u32_e32 v11, -1, v10
	v_fma_f32 v12, -v11, v10, v9
	v_cmp_ge_f32_e64 s[44:45], 0, v12
	v_add_u32_e32 v12, 1, v10
	s_nop 0
	v_cndmask_b32_e64 v11, v10, v11, s[44:45]
	v_fma_f32 v10, -v12, v10, v9
	v_cmp_lt_f32_e64 s[44:45], 0, v10
	s_nop 1
	v_cndmask_b32_e64 v10, v11, v12, s[44:45]
	v_mul_f32_e32 v11, 0x37800000, v10
	v_cndmask_b32_e32 v10, v10, v11, vcc
	v_cmp_class_f32_e32 vcc, v9, v177
	s_nop 1
	v_cndmask_b32_e32 v9, v10, v9, vcc
	v_div_scale_f32 v10, s[6:7], v9, v9, 1.0
	v_rcp_f32_e32 v11, v10
	s_nop 0
	v_fma_f32 v12, -v10, v11, 1.0
	v_fmac_f32_e32 v11, v12, v11
	v_div_scale_f32 v12, vcc, 1.0, v9, 1.0
	v_mul_f32_e32 v13, v12, v11
	v_fma_f32 v14, -v10, v13, v12
	v_fmac_f32_e32 v13, v14, v11
	v_fma_f32 v10, -v10, v13, v12
	v_div_fmas_f32 v10, v10, v11, v13
	v_div_fixup_f32 v9, v10, v9, 1.0
	ds_write_b64 v30, v[8:9] offset:104
.LBB0_426:
	s_or_b64 exec, exec, s[82:83]
	s_waitcnt vmcnt(1)
	v_and_b32_e32 v10, 0xffff0000, v4
	v_lshlrev_b32_e32 v8, 16, v4
	v_mul_f32_e32 v4, v10, v10
	v_lshlrev_b32_e32 v11, 16, v5
	v_fmamk_f32 v4, v4, 0xbdd2d3e8, v245
	v_mul_f32_e32 v12, v11, v11
	v_and_b32_e32 v5, 0xffff0000, v5
	v_mul_f32_e32 v4, v4, v10
	v_fmamk_f32 v12, v12, 0xbdd2d3e8, v245
	v_mul_f32_e32 v13, v5, v5
	v_mul_f32_e32 v12, v12, v11
	v_fmamk_f32 v13, v13, 0xbdd2d3e8, v245
	v_mul_f32_e32 v13, v13, v5
	v_exp_f32_e32 v4, v4
	v_exp_f32_e32 v12, v12
	v_exp_f32_e32 v13, v13
	v_add_f32_e32 v4, 1.0, v4
	v_rcp_f32_e32 v14, v4
	v_add_f32_e32 v4, 1.0, v12
	v_rcp_f32_e32 v12, v4
	v_add_f32_e32 v4, 1.0, v13
	v_lshlrev_b32_e32 v13, 16, v6
	v_mul_f32_e32 v15, v13, v13
	v_and_b32_e32 v6, 0xffff0000, v6
	v_fmamk_f32 v15, v15, 0xbdd2d3e8, v245
	v_mul_f32_e32 v16, v6, v6
	v_mul_f32_e32 v15, v15, v13
	v_fmamk_f32 v16, v16, 0xbdd2d3e8, v245
	v_mul_f32_e32 v16, v16, v6
	v_exp_f32_e32 v15, v15
	v_exp_f32_e32 v16, v16
	v_mul_f32_e32 v9, v8, v8
	v_fmamk_f32 v9, v9, 0xbdd2d3e8, v245
	v_rcp_f32_e32 v17, v4
	v_add_f32_e32 v4, 1.0, v15
	v_mul_f32_e32 v9, v9, v8
	v_rcp_f32_e32 v15, v4
	v_add_f32_e32 v4, 1.0, v16
	v_lshlrev_b32_e32 v16, 16, v7
	v_mul_f32_e32 v18, v16, v16
	v_and_b32_e32 v7, 0xffff0000, v7
	v_fmamk_f32 v18, v18, 0xbdd2d3e8, v245
	v_mul_f32_e32 v19, v7, v7
	v_exp_f32_e32 v9, v9
	v_mul_f32_e32 v18, v18, v16
	v_fmamk_f32 v19, v19, 0xbdd2d3e8, v245
	v_mul_f32_e32 v19, v19, v7
	v_exp_f32_e32 v18, v18
	v_add_f32_e32 v9, 1.0, v9
	v_exp_f32_e32 v19, v19
	v_rcp_f32_e32 v9, v9
	v_rcp_f32_e32 v20, v4
	v_add_f32_e32 v4, 1.0, v18
	v_rcp_f32_e32 v18, v4
	v_add_f32_e32 v4, 1.0, v19
	v_rcp_f32_e32 v19, v4
	v_fma_f32 v4, v9, v8, 0
	v_fmac_f32_e32 v4, v14, v10
	v_fmac_f32_e32 v4, v12, v11
	v_fmac_f32_e32 v4, v17, v5
	v_fmac_f32_e32 v4, v15, v13
	v_fmac_f32_e32 v4, v20, v6
	v_fmac_f32_e32 v4, v18, v16
	v_fmac_f32_e32 v4, v19, v7
	s_nop 1
	v_add_f32_dpp v4, v4, v4 quad_perm:[1,0,3,2] row_mask:0xf bank_mask:0xf bound_ctrl:1
	s_nop 1
	v_add_f32_dpp v4, v4, v4 quad_perm:[2,3,0,1] row_mask:0xf bank_mask:0xf bound_ctrl:1
	s_nop 1
	v_add_f32_dpp v4, v4, v4 row_half_mirror row_mask:0xf bank_mask:0xf bound_ctrl:1
	s_nop 1
	v_add_f32_dpp v4, v4, v4 row_mirror row_mask:0xf bank_mask:0xf bound_ctrl:1
	s_nop 0
	v_readlane_b32 s6, v4, 16
	v_readlane_b32 s5, v4, 0
	s_nop 0
	v_mov_b32_e32 v21, s6
	v_readlane_b32 s6, v4, 48
	v_add_f32_e32 v21, s5, v21
	v_readlane_b32 s5, v4, 32
	v_mov_b32_e32 v4, s6
	s_nop 0
	v_add_f32_e32 v4, s5, v4
	v_add_f32_e32 v4, v21, v4
	v_mul_f32_e32 v4, 0x3b000000, v4
	v_fma_f32 v8, v9, v8, -v4
	v_fma_f32 v9, v14, v10, -v4
	v_mul_f32_e32 v9, v9, v9
	v_fmac_f32_e32 v9, v8, v8
	v_fma_f32 v8, v12, v11, -v4
	v_fmac_f32_e32 v9, v8, v8
	v_fma_f32 v5, v17, v5, -v4
	v_fmac_f32_e32 v9, v5, v5
	v_fma_f32 v5, v15, v13, -v4
	v_fmac_f32_e32 v9, v5, v5
	v_fma_f32 v5, v20, v6, -v4
	v_fmac_f32_e32 v9, v5, v5
	v_fma_f32 v5, v18, v16, -v4
	v_fmac_f32_e32 v9, v5, v5
	v_fma_f32 v5, v19, v7, -v4
	v_fmac_f32_e32 v9, v5, v5
	s_nop 1
	v_add_f32_dpp v5, v9, v9 quad_perm:[1,0,3,2] row_mask:0xf bank_mask:0xf bound_ctrl:1
	s_nop 1
	v_add_f32_dpp v5, v5, v5 quad_perm:[2,3,0,1] row_mask:0xf bank_mask:0xf bound_ctrl:1
	s_nop 1
	v_add_f32_dpp v5, v5, v5 row_half_mirror row_mask:0xf bank_mask:0xf bound_ctrl:1
	s_nop 1
	v_add_f32_dpp v5, v5, v5 row_mirror row_mask:0xf bank_mask:0xf bound_ctrl:1
	s_nop 0
	v_readlane_b32 s44, v5, 0
	v_readlane_b32 s5, v5, 16
	v_readlane_b32 s45, v5, 32
	v_readlane_b32 s6, v5, 48
	s_and_saveexec_b64 s[82:83], s[42:43]
	s_cbranch_execz .LBB0_428
	v_mov_b32_e32 v6, s5
	v_mov_b32_e32 v7, s6
	v_pk_add_f32 v[6:7], s[44:45], v[6:7]
	s_nop 0
	v_add_f32_e32 v5, v6, v7
	v_fmamk_f32 v5, v5, 0x3b000000, v176
	v_mul_f32_e32 v6, 0x4f800000, v5
	v_cmp_gt_f32_e32 vcc, s79, v5
	s_nop 1
	v_cndmask_b32_e32 v5, v5, v6, vcc
	v_sqrt_f32_e32 v6, v5
	s_nop 0
	v_add_u32_e32 v7, -1, v6
	v_fma_f32 v8, -v7, v6, v5
	v_cmp_ge_f32_e64 s[44:45], 0, v8
	v_add_u32_e32 v8, 1, v6
	s_nop 0
	v_cndmask_b32_e64 v7, v6, v7, s[44:45]
	v_fma_f32 v6, -v8, v6, v5
	v_cmp_lt_f32_e64 s[44:45], 0, v6
	s_nop 1
	v_cndmask_b32_e64 v6, v7, v8, s[44:45]
	v_mul_f32_e32 v7, 0x37800000, v6
	v_cndmask_b32_e32 v6, v6, v7, vcc
	v_cmp_class_f32_e32 vcc, v5, v177
	s_nop 1
	v_cndmask_b32_e32 v5, v6, v5, vcc
	v_div_scale_f32 v6, s[6:7], v5, v5, 1.0
	v_rcp_f32_e32 v7, v6
	s_nop 0
	v_fma_f32 v8, -v6, v7, 1.0
	v_fmac_f32_e32 v7, v8, v7
	v_div_scale_f32 v8, vcc, 1.0, v5, 1.0
	v_mul_f32_e32 v9, v8, v7
	v_fma_f32 v10, -v6, v9, v8
	v_fmac_f32_e32 v9, v10, v7
	v_fma_f32 v6, -v6, v9, v8
	v_div_fmas_f32 v6, v6, v7, v9
	v_div_fixup_f32 v5, v6, v5, 1.0
	ds_write_b64 v30, v[4:5] offset:112
.LBB0_428:
	s_or_b64 exec, exec, s[82:83]
	s_waitcnt vmcnt(0)
	v_and_b32_e32 v6, 0xffff0000, v0
	v_lshlrev_b32_e32 v4, 16, v0
	v_mul_f32_e32 v0, v6, v6
	v_lshlrev_b32_e32 v7, 16, v1
	v_fmamk_f32 v0, v0, 0xbdd2d3e8, v245
	v_mul_f32_e32 v8, v7, v7
	v_and_b32_e32 v1, 0xffff0000, v1
	v_mul_f32_e32 v0, v0, v6
	v_fmamk_f32 v8, v8, 0xbdd2d3e8, v245
	v_mul_f32_e32 v9, v1, v1
	v_mul_f32_e32 v8, v8, v7
	v_fmamk_f32 v9, v9, 0xbdd2d3e8, v245
	v_mul_f32_e32 v9, v9, v1
	v_exp_f32_e32 v0, v0
	v_exp_f32_e32 v8, v8
	v_exp_f32_e32 v9, v9
	v_add_f32_e32 v0, 1.0, v0
	v_rcp_f32_e32 v10, v0
	v_add_f32_e32 v0, 1.0, v8
	v_rcp_f32_e32 v8, v0
	v_add_f32_e32 v0, 1.0, v9
	v_lshlrev_b32_e32 v9, 16, v2
	v_mul_f32_e32 v11, v9, v9
	v_and_b32_e32 v2, 0xffff0000, v2
	v_fmamk_f32 v11, v11, 0xbdd2d3e8, v245
	v_mul_f32_e32 v12, v2, v2
	v_mul_f32_e32 v11, v11, v9
	v_fmamk_f32 v12, v12, 0xbdd2d3e8, v245
	v_mul_f32_e32 v12, v12, v2
	v_exp_f32_e32 v11, v11
	v_exp_f32_e32 v12, v12
	v_mul_f32_e32 v5, v4, v4
	v_fmamk_f32 v5, v5, 0xbdd2d3e8, v245
	v_rcp_f32_e32 v13, v0
	v_add_f32_e32 v0, 1.0, v11
	v_mul_f32_e32 v5, v5, v4
	v_rcp_f32_e32 v11, v0
	v_add_f32_e32 v0, 1.0, v12
	v_lshlrev_b32_e32 v12, 16, v3
	v_mul_f32_e32 v14, v12, v12
	v_and_b32_e32 v3, 0xffff0000, v3
	v_fmamk_f32 v14, v14, 0xbdd2d3e8, v245
	v_mul_f32_e32 v15, v3, v3
	v_exp_f32_e32 v5, v5
	v_mul_f32_e32 v14, v14, v12
	v_fmamk_f32 v15, v15, 0xbdd2d3e8, v245
	v_mul_f32_e32 v15, v15, v3
	v_exp_f32_e32 v14, v14
	v_add_f32_e32 v5, 1.0, v5
	v_exp_f32_e32 v15, v15
	v_rcp_f32_e32 v5, v5
	v_rcp_f32_e32 v16, v0
	v_add_f32_e32 v0, 1.0, v14
	v_rcp_f32_e32 v14, v0
	v_add_f32_e32 v0, 1.0, v15
	v_rcp_f32_e32 v15, v0
	v_fma_f32 v0, v5, v4, 0
	v_fmac_f32_e32 v0, v10, v6
	v_fmac_f32_e32 v0, v8, v7
	v_fmac_f32_e32 v0, v13, v1
	v_fmac_f32_e32 v0, v11, v9
	v_fmac_f32_e32 v0, v16, v2
	v_fmac_f32_e32 v0, v14, v12
	v_fmac_f32_e32 v0, v15, v3
	s_nop 1
	v_add_f32_dpp v0, v0, v0 quad_perm:[1,0,3,2] row_mask:0xf bank_mask:0xf bound_ctrl:1
	s_nop 1
	v_add_f32_dpp v0, v0, v0 quad_perm:[2,3,0,1] row_mask:0xf bank_mask:0xf bound_ctrl:1
	s_nop 1
	v_add_f32_dpp v0, v0, v0 row_half_mirror row_mask:0xf bank_mask:0xf bound_ctrl:1
	s_nop 1
	v_add_f32_dpp v0, v0, v0 row_mirror row_mask:0xf bank_mask:0xf bound_ctrl:1
	s_nop 0
	v_readlane_b32 s6, v0, 16
	v_readlane_b32 s5, v0, 0
	s_nop 0
	v_mov_b32_e32 v17, s6
	v_readlane_b32 s6, v0, 48
	v_add_f32_e32 v17, s5, v17
	v_readlane_b32 s5, v0, 32
	v_mov_b32_e32 v0, s6
	s_nop 0
	v_add_f32_e32 v0, s5, v0
	v_add_f32_e32 v0, v17, v0
	v_mul_f32_e32 v0, 0x3b000000, v0
	v_fma_f32 v4, v5, v4, -v0
	v_fma_f32 v5, v10, v6, -v0
	v_mul_f32_e32 v5, v5, v5
	v_fmac_f32_e32 v5, v4, v4
	v_fma_f32 v4, v8, v7, -v0
	v_fmac_f32_e32 v5, v4, v4
	v_fma_f32 v1, v13, v1, -v0
	v_fmac_f32_e32 v5, v1, v1
	v_fma_f32 v1, v11, v9, -v0
	v_fmac_f32_e32 v5, v1, v1
	v_fma_f32 v1, v16, v2, -v0
	v_fmac_f32_e32 v5, v1, v1
	v_fma_f32 v1, v14, v12, -v0
	v_fmac_f32_e32 v5, v1, v1
	v_fma_f32 v1, v15, v3, -v0
	v_fmac_f32_e32 v5, v1, v1
	s_nop 1
	v_add_f32_dpp v1, v5, v5 quad_perm:[1,0,3,2] row_mask:0xf bank_mask:0xf bound_ctrl:1
	s_nop 1
	v_add_f32_dpp v1, v1, v1 quad_perm:[2,3,0,1] row_mask:0xf bank_mask:0xf bound_ctrl:1
	s_nop 1
	v_add_f32_dpp v1, v1, v1 row_half_mirror row_mask:0xf bank_mask:0xf bound_ctrl:1
	s_nop 1
	v_add_f32_dpp v1, v1, v1 row_mirror row_mask:0xf bank_mask:0xf bound_ctrl:1
	s_nop 0
	v_readlane_b32 s82, v1, 0
	v_readlane_b32 s5, v1, 16
	v_readlane_b32 s83, v1, 32
	v_readlane_b32 s6, v1, 48
	s_and_saveexec_b64 s[44:45], s[42:43]
	s_cbranch_execz .LBB0_362
	v_mov_b32_e32 v2, s5
	v_mov_b32_e32 v3, s6
	v_pk_add_f32 v[2:3], s[82:83], v[2:3]
	s_nop 0
	v_add_f32_e32 v1, v2, v3
	v_fmamk_f32 v1, v1, 0x3b000000, v176
	v_mul_f32_e32 v2, 0x4f800000, v1
	v_cmp_gt_f32_e32 vcc, s79, v1
	s_nop 1
	v_cndmask_b32_e32 v1, v1, v2, vcc
	v_sqrt_f32_e32 v2, v1
	s_nop 0
	v_add_u32_e32 v3, -1, v2
	v_fma_f32 v4, -v3, v2, v1
	v_cmp_ge_f32_e64 s[42:43], 0, v4
	v_add_u32_e32 v4, 1, v2
	s_nop 0
	v_cndmask_b32_e64 v3, v2, v3, s[42:43]
	v_fma_f32 v2, -v4, v2, v1
	v_cmp_lt_f32_e64 s[42:43], 0, v2
	s_nop 1
	v_cndmask_b32_e64 v2, v3, v4, s[42:43]
	v_mul_f32_e32 v3, 0x37800000, v2
	v_cndmask_b32_e32 v2, v2, v3, vcc
	v_cmp_class_f32_e32 vcc, v1, v177
	s_nop 1
	v_cndmask_b32_e32 v1, v2, v1, vcc
	v_div_scale_f32 v2, s[6:7], v1, v1, 1.0
	v_rcp_f32_e32 v3, v2
	s_nop 0
	v_fma_f32 v4, -v2, v3, 1.0
	v_fmac_f32_e32 v3, v4, v3
	v_div_scale_f32 v4, vcc, 1.0, v1, 1.0
	v_mul_f32_e32 v5, v4, v3
	v_fma_f32 v6, -v2, v5, v4
	v_fmac_f32_e32 v5, v6, v3
	v_fma_f32 v2, -v2, v5, v4
	v_div_fmas_f32 v2, v2, v3, v5
	v_div_fixup_f32 v1, v2, v1, 1.0
	ds_write_b64 v30, v[0:1] offset:120
	s_branch .LBB0_362

.LBB0_579:
	s_andn2_b64 vcc, exec, s[0:1]
	s_cbranch_vccnz .LBB0_688
	s_and_b64 s[0:1], s[10:11], exec
	s_cselect_b32 s5, 0, 2
	v_readlane_b32 s0, v243, 57
	s_add_i32 s0, s5, s0
	s_cmpk_gt_i32 s0, 0x81
	v_mov_b32_e32 v0, v175
	s_mov_b64 s[58:59], s[68:69]
	v_readlane_b32 s1, v243, 58
	s_cbranch_scc1 .LBB0_621
	v_readlane_b32 s1, v243, 12
	s_lshl_b32 s1, s1, 1
	s_lshl_b32 s4, s96, 19
	s_or_b32 s1, s4, s1
	s_add_u32 s1, s58, s1
	s_addc_u32 s4, s59, 0
	s_add_u32 s6, s1, 0x15ee4c40
	s_addc_u32 s7, s4, 0
	v_ashrrev_i32_e32 v1, 31, v0
	v_lshl_add_u64 v[4:5], v[0:1], 4, s[6:7]
	s_barrier
	global_load_dwordx4 v[48:51], v[4:5], off
	v_add_u32_e32 v8, 0x200, v0
	v_lshl_add_u32 v2, v0, 4, 0
	v_ashrrev_i32_e32 v9, 31, v8
	v_lshl_add_u64 v[4:5], v[8:9], 4, s[6:7]
	global_load_dwordx4 v[52:55], v[4:5], off
	v_add_u32_e32 v8, 0x400, v0
	v_ashrrev_i32_e32 v9, 31, v8
	v_lshl_add_u64 v[4:5], v[8:9], 4, s[6:7]
	global_load_dwordx4 v[56:59], v[4:5], off
	v_add_u32_e32 v8, 0x600, v0
	v_ashrrev_i32_e32 v9, 31, v8
	v_lshl_add_u64 v[4:5], v[8:9], 4, s[6:7]
	global_load_dwordx4 v[60:63], v[4:5], off
	v_lshlrev_b32_e32 v29, 4, v0
	v_lshlrev_b32_e32 v31, 2, v0
	s_movk_i32 s1, 0x140
	v_and_b32_e32 v3, 63, v0
	v_cmp_gt_i32_e32 vcc, s1, v0
	s_and_saveexec_b64 s[40:41], vcc
	s_cbranch_execz .LBB0_587
	v_ashrrev_i32_e32 v6, 6, v0
	v_cmp_lt_i32_e32 vcc, 3, v6
	s_and_saveexec_b64 s[6:7], vcc
	s_xor_b64 s[42:43], exec, s[6:7]
	s_cbranch_execz .LBB0_584
	s_lshl_b32 s1, s96, 10
	v_readlane_b32 s4, v243, 13
	s_or_b32 s1, s1, s4
	s_mov_b64 s[6:7], s[10:11]
	v_readlane_b32 s8, v243, 14
	v_or_b32_e32 v144, s1, v3
	v_readlane_b32 s10, v243, 16
	v_readlane_b32 s11, v243, 17
	v_readlane_b32 s9, v243, 15
	s_movk_i32 s31, 0x4100
	v_lshl_add_u64 v[4:5], v[144:145], 2, s[10:11]
	s_mov_b64 s[10:11], s[6:7]

.LBB0_586:
	s_or_b64 exec, exec, s[42:43]
	global_load_dword v30, v[4:5], off

.LBB0_591:
	s_or_b64 exec, exec, s[46:47]
	s_movk_i32 s1, 0x90
	v_mul_lo_u32 v164, v2, s1
	v_lshlrev_b32_e32 v165, 5, v9
	v_add3_u32 v9, 0, v164, v165
	v_mul_lo_u32 v166, v6, s1
	s_waitcnt vmcnt(0)
	ds_write_b128 v29, v[48:51]
	ds_write_b128 v29, v[52:55] offset:8192
	ds_write_b128 v29, v[56:59] offset:16384
	ds_write_b128 v29, v[60:63] offset:24576
	v_cmp_gt_i32_e32 vcc, 0x140, v0
	s_and_saveexec_b64 s[42:43], vcc
	ds_write_b32 v31, v30 offset:32768
	s_or_b64 exec, exec, s[42:43]
	ds_write_b128 v9, v[36:39] offset:35104
	ds_write_b128 v9, v[32:35] offset:35120
	s_and_saveexec_b64 s[42:43], s[40:41]
	s_cbranch_execz .LBB0_593
	v_add3_u32 v9, 0, v166, v165
	ds_write_b128 v9, v[44:47] offset:34816
	ds_write_b128 v9, v[40:43] offset:34832

	.amdhsa_kernel _Z8mega_fwd4Args
		.amdhsa_group_segment_fixed_size 0
		.amdhsa_private_segment_fixed_size 0
		.amdhsa_kernarg_size 480
		.amdhsa_user_sgpr_count 2
		.amdhsa_user_sgpr_dispatch_ptr 0
		.amdhsa_user_sgpr_queue_ptr 0
		.amdhsa_user_sgpr_kernarg_segment_ptr 1
		.amdhsa_user_sgpr_dispatch_id 0
		.amdhsa_user_sgpr_kernarg_preload_length 0
		.amdhsa_user_sgpr_kernarg_preload_offset 0
		.amdhsa_user_sgpr_private_segment_size 0
		.amdhsa_uses_dynamic_stack 0
		.amdhsa_enable_private_segment 0
		.amdhsa_system_sgpr_workgroup_id_x 1
		.amdhsa_system_sgpr_workgroup_id_y 0
		.amdhsa_system_sgpr_workgroup_id_z 0
		.amdhsa_system_sgpr_workgroup_info 0
		.amdhsa_system_vgpr_workitem_id 2
		.amdhsa_next_free_vgpr 246
		.amdhsa_next_free_sgpr 98
		.amdhsa_accum_offset 248
		.amdhsa_reserve_vcc 1
		.amdhsa_float_round_mode_32 0
		.amdhsa_float_round_mode_16_64 0
		.amdhsa_float_denorm_mode_32 3
		.amdhsa_float_denorm_mode_16_64 3
		.amdhsa_dx10_clamp 1
		.amdhsa_ieee_mode 1
		.amdhsa_fp16_overflow 0
		.amdhsa_tg_split 0
		.amdhsa_exception_fp_ieee_invalid_op 0
		.amdhsa_exception_fp_denorm_src 0
		.amdhsa_exception_fp_ieee_div_zero 0
		.amdhsa_exception_fp_ieee_overflow 0
		.amdhsa_exception_fp_ieee_underflow 0
		.amdhsa_exception_fp_ieee_inexact 0
		.amdhsa_exception_int_div_zero 0
	.end_amdhsa_kernel

amdhsa.kernels:
  - .agpr_count:     0
    .args:
      - .offset:         0
        .size:           224
        .value_kind:     by_value
      - .offset:         224
        .size:           4
        .value_kind:     hidden_block_count_x
      - .offset:         228
        .size:           4
        .value_kind:     hidden_block_count_y
      - .offset:         232
        .size:           4
        .value_kind:     hidden_block_count_z
      - .offset:         236
        .size:           2
        .value_kind:     hidden_group_size_x
      - .offset:         238
        .size:           2
        .value_kind:     hidden_group_size_y
      - .offset:         240
        .size:           2
        .value_kind:     hidden_group_size_z
      - .offset:         242
        .size:           2
        .value_kind:     hidden_remainder_x
      - .offset:         244
        .size:           2
        .value_kind:     hidden_remainder_y
      - .offset:         246
        .size:           2
        .value_kind:     hidden_remainder_z
      - .offset:         264
        .size:           8
        .value_kind:     hidden_global_offset_x
      - .offset:         272
        .size:           8
        .value_kind:     hidden_global_offset_y
      - .offset:         280
        .size:           8
        .value_kind:     hidden_global_offset_z
      - .offset:         288
        .size:           2
        .value_kind:     hidden_grid_dims
      - .offset:         312
        .size:           8
        .value_kind:     hidden_multigrid_sync_arg
      - .offset:         344
        .size:           4
        .value_kind:     hidden_dynamic_lds_size
    .group_segment_fixed_size: 0
    .kernarg_segment_align: 8
    .kernarg_segment_size: 480
    .language:       OpenCL C
    .language_version:
      - 2
      - 0
    .max_flat_workgroup_size: 512
    .name:           _Z8mega_fwd4Args
    .private_segment_fixed_size: 0
    .sgpr_count:     104
    .sgpr_spill_count: 182
    .symbol:         _Z8mega_fwd4Args.kd
    .uniform_work_group_size: 1
    .uses_dynamic_stack: false
    .vgpr_count:     246
    .vgpr_spill_count: 0
    .wavefront_size: 64
